# fused rmsnorm epilogue without tile reload (packed tile kept in consumed accumulator registers) + dead zero-init movs removed from conv-gate epilogue
# speedup vs baseline: 1.0200x; 1.0105x over previous
;     __device__ __forceinline__ void operator()(const f32x4 (&acc)[2][2][4][2], const Unit& u, int wr, int wc, int fr_in, int fq_in) const {
;     ...
;         asm volatile("s_waitcnt vmcnt(0) lgkmcnt(0)" ::: "memory"); __builtin_amdgcn_s_barrier(); asm volatile("" ::: "memory");
;         const int j = u.flag;
;         bf16_t* obase = (bf16_t*)u.O + cl;
;         u32x2 ypk[2][4];
; #pragma unroll
;         for (int n = 0; n < 2; ++n) {
;             f32x4 wv[4][2];
; #pragma unroll
;             for (int k = 0; k < 4; ++k)
; #pragma unroll
;                 for (int bj = 0; bj < 2; ++bj) wv[k][bj] = *(const LAS f32x4*)(W + (k * 2 + bj) * 128 + cl + 4 * n);
; #pragma unroll
;             for (int ai = 0; ai < 2; ++ai) { const int Bk = 2 * ai + wr;
; #pragma unroll
;                 for (int m = 0; m < 4; ++m) {
;                     const int r = 128 * ai + 64 * wr + 16 * m + fr, tb = 254 * j + r - 1;
;                     f32x4 res[2];
; #pragma unroll
;                     for (int bj = 0; bj < 2; ++bj) {
;                         const f32x4 cur = acc[ai][bj][m][n];
;                         f32x4 pe, ne;
;                         if (m > 0) { const f32x4 q = acc[ai][bj][m > 0 ? m - 1 : 0][n]; pe = (f32x4){dpp_ror1(q[0]), dpp_ror1(q[1]), dpp_ror1(q[2]), dpp_ror1(q[3])}; }
;                         else pe = *(const LAS f32x4*)(X + (((Bk > 0 ? Bk - 1 : 0) * 2 + 1) * 2 + bj) * 128 + cl + 4 * n);
;                         if (m < 3) { const f32x4 q = acc[ai][bj][m < 3 ? m + 1 : 3][n]; ne = (f32x4){dpp_rol1(q[0]), dpp_rol1(q[1]), dpp_rol1(q[2]), dpp_rol1(q[3])}; }
;                         else ne = *(const LAS f32x4*)(X + (((Bk < 3 ? Bk + 1 : 3) * 2 + 0) * 2 + bj) * 128 + cl + 4 * n);
;                         f32x4 pvv, nvv;
; #pragma unroll
;                         for (int e = 0; e < 4; ++e) {
;                             float pv = __int_as_float(__builtin_amdgcn_update_dpp(__float_as_int(pe[e]), __float_as_int(cur[e]), 0x111, 0xf, 0xf, false));
;                             float nv = __int_as_float(__builtin_amdgcn_update_dpp(__float_as_int(ne[e]), __float_as_int(cur[e]), 0x101, 0xf, 0xf, false));
;                             if (ai == 0 && m == 0) pv = (tb == 0) ? 0.f : pv;
;                             if (ai == 0 && m == 2) nv = (tb == SEQ - 1) ? 0.f : nv;
;                             pvv[e] = pv; nvv[e] = nv; }
.LBB0_224:
	s_or_b64 exec, exec, s[8:9]
	v_lshl_add_u32 v128, v132, 2, 0
	v_readlane_b32 s0, v254, 59
	s_waitcnt vmcnt(0) lgkmcnt(0)
	s_barrier
	v_add_u32_e32 v154, 0x22000, v128
	v_add_u32_e32 v237, s0, v138
	v_add_u32_e32 v229, s81, v134
	ds_read_b128 v[164:167], v154
	s_waitcnt vmcnt(0)
	ds_read_b128 v[134:137], v154 offset:512
	ds_read_b128 v[168:171], v154 offset:1024
	ds_read_b128 v[142:145], v154 offset:1536
	ds_read_b128 v[172:175], v154 offset:2048
	ds_read_b128 v[146:149], v154 offset:2560
	ds_read_b128 v[176:179], v154 offset:3072
	ds_read_b128 v[150:153], v154 offset:3584
	ds_read_b128 v[128:131], v237
	v_ashrrev_i32_e32 v133, 31, v132
	v_lshl_add_u64 v[204:205], v[132:133], 1, s[14:15]
	s_nop 1
	v_mul_lo_u32 v230, v223, s67
	v_mov_b32_dpp v132, v120 row_ror:15 row_mask:0xf bank_mask:0xf
	v_mov_b32_dpp v133, v121 row_ror:15 row_mask:0xf bank_mask:0xf
	s_nop 1
	v_add_u32_e32 v182, v229, v230
	v_mov_b32_dpp v140, v122 row_ror:15 row_mask:0xf bank_mask:0xf
	v_mov_b32_dpp v141, v123 row_ror:15 row_mask:0xf bank_mask:0xf
	v_mov_b32_dpp v132, v124 row_shl:1 row_mask:0xf bank_mask:0xf
	v_mov_b32_dpp v133, v125 row_shl:1 row_mask:0xf bank_mask:0xf
	v_cmp_eq_u32_e32 vcc, 1, v182
	s_waitcnt lgkmcnt(0)
	v_mov_b32_dpp v128, v124 row_shr:1 row_mask:0xf bank_mask:0xf
	v_mov_b32_dpp v129, v125 row_shr:1 row_mask:0xf bank_mask:0xf
	v_mov_b32_dpp v140, v126 row_shl:1 row_mask:0xf bank_mask:0xf
	v_mov_b32_dpp v141, v127 row_shl:1 row_mask:0xf bank_mask:0xf
	v_pk_fma_f32 v[132:133], v[172:173], v[132:133], v[176:177]
	v_readlane_b32 s0, v254, 56
	v_cndmask_b32_e64 v128, v128, 0, vcc
	v_cndmask_b32_e64 v129, v129, 0, vcc
	v_mov_b32_dpp v130, v126 row_shr:1 row_mask:0xf bank_mask:0xf
	v_mov_b32_dpp v131, v127 row_shr:1 row_mask:0xf bank_mask:0xf
	v_pk_fma_f32 v[140:141], v[174:175], v[140:141], v[178:179]
	v_pk_fma_f32 v[132:133], v[124:125], v[168:169], v[132:133]
	v_add_u32_e32 v238, s0, v138
	v_cndmask_b32_e64 v130, v130, 0, vcc
	v_cndmask_b32_e64 v131, v131, 0, vcc
	v_pk_fma_f32 v[140:141], v[126:127], v[170:171], v[140:141]
	v_pk_fma_f32 v[132:133], v[164:165], v[128:129], v[132:133]
	v_add_u32_e32 v128, 0xfffffe00, v238
	v_pk_fma_f32 v[140:141], v[166:167], v[130:131], v[140:141]
	ds_read_b128 v[128:131], v128
	s_nop 1
	v_mov_b32_dpp v156, v92 row_ror:15 row_mask:0xf bank_mask:0xf
	v_mov_b32_dpp v157, v93 row_ror:15 row_mask:0xf bank_mask:0xf
	v_mov_b32_dpp v158, v94 row_ror:15 row_mask:0xf bank_mask:0xf
	v_mov_b32_dpp v159, v95 row_ror:15 row_mask:0xf bank_mask:0xf
	v_mov_b32_dpp v156, v100 row_shl:1 row_mask:0xf bank_mask:0xf
	v_mov_b32_dpp v157, v101 row_shl:1 row_mask:0xf bank_mask:0xf
	v_mov_b32_dpp v158, v102 row_shl:1 row_mask:0xf bank_mask:0xf
	v_mov_b32_dpp v159, v103 row_shl:1 row_mask:0xf bank_mask:0xf
	s_waitcnt lgkmcnt(0)
	v_mov_b32_dpp v128, v100 row_shr:1 row_mask:0xf bank_mask:0xf
	v_mov_b32_dpp v129, v101 row_shr:1 row_mask:0xf bank_mask:0xf
	v_mov_b32_dpp v130, v102 row_shr:1 row_mask:0xf bank_mask:0xf
	v_mov_b32_dpp v131, v103 row_shr:1 row_mask:0xf bank_mask:0xf
	v_pk_fma_f32 v[158:159], v[148:149], v[158:159], v[152:153]
	v_pk_fma_f32 v[156:157], v[146:147], v[156:157], v[150:151]
	v_cndmask_b32_e64 v128, v128, 0, vcc
	v_cndmask_b32_e64 v129, v129, 0, vcc
	v_cndmask_b32_e64 v130, v130, 0, vcc
	v_cndmask_b32_e64 v131, v131, 0, vcc
	v_pk_fma_f32 v[156:157], v[100:101], v[142:143], v[156:157]
	v_pk_fma_f32 v[158:159], v[102:103], v[144:145], v[158:159]
	s_mov_b32 s0, 0xbfb8aa3b
	v_pk_fma_f32 v[130:131], v[136:137], v[130:131], v[158:159]
	v_pk_fma_f32 v[128:129], v[134:135], v[128:129], v[156:157]
	v_pk_mul_f32 v[156:157], v[140:141], s[0:1] op_sel_hi:[1,0]
	v_pk_mul_f32 v[158:159], v[132:133], s[0:1] op_sel_hi:[1,0]
	v_exp_f32_e32 v156, v156
	v_exp_f32_e32 v158, v158
	v_exp_f32_e32 v159, v159
	v_exp_f32_e32 v157, v157
	v_pk_mul_f32 v[128:129], v[132:133], v[128:129]
	v_pk_mul_f32 v[130:131], v[140:141], v[130:131]
	v_pk_add_f32 v[158:159], v[158:159], 1.0 op_sel_hi:[1,0]
	v_pk_add_f32 v[156:157], v[156:157], 1.0 op_sel_hi:[1,0]
	v_rcp_f32_e32 v158, v158
	v_rcp_f32_e32 v159, v159
	v_rcp_f32_e32 v156, v156
	v_rcp_f32_e32 v157, v157
	s_nop 1
	v_pk_mul_f32 v[130:131], v[156:157], v[130:131]
	v_pk_mul_f32 v[128:129], v[158:159], v[128:129]
	v_mov_b32_dpp v132, v112 row_ror:15 row_mask:0xf bank_mask:0xf
	v_mov_b32_dpp v133, v113 row_ror:15 row_mask:0xf bank_mask:0xf
	v_mov_b32_dpp v140, v114 row_ror:15 row_mask:0xf bank_mask:0xf
	v_mov_b32_dpp v141, v115 row_ror:15 row_mask:0xf bank_mask:0xf
	v_cvt_pk_bf16_f32 v162, v128, v129
	v_cvt_pk_bf16_f32 v163, v130, v131
	s_nop 1
	v_mov_b32_dpp v132, v120 row_shl:1 row_mask:0xf bank_mask:0xf
	v_mov_b32_dpp v133, v121 row_shl:1 row_mask:0xf bank_mask:0xf
	v_mov_b32_dpp v140, v122 row_shl:1 row_mask:0xf bank_mask:0xf
	v_mov_b32_dpp v141, v123 row_shl:1 row_mask:0xf bank_mask:0xf
	v_mov_b32_dpp v128, v124 row_ror:1 row_mask:0xf bank_mask:0xf
	v_mov_b32_dpp v129, v125 row_ror:1 row_mask:0xf bank_mask:0xf
	v_mov_b32_dpp v130, v126 row_ror:1 row_mask:0xf bank_mask:0xf
	v_mov_b32_dpp v131, v127 row_ror:1 row_mask:0xf bank_mask:0xf
	v_pk_fma_f32 v[132:133], v[172:173], v[132:133], v[176:177]
	v_pk_fma_f32 v[140:141], v[174:175], v[140:141], v[178:179]
	s_nop 1
	v_mov_b32_dpp v128, v120 row_shr:1 row_mask:0xf bank_mask:0xf
	v_mov_b32_dpp v129, v121 row_shr:1 row_mask:0xf bank_mask:0xf
	v_mov_b32_dpp v130, v122 row_shr:1 row_mask:0xf bank_mask:0xf
	v_mov_b32_dpp v131, v123 row_shr:1 row_mask:0xf bank_mask:0xf
	v_pk_fma_f32 v[140:141], v[122:123], v[170:171], v[140:141]
	v_pk_fma_f32 v[132:133], v[120:121], v[168:169], v[132:133]
	v_mov_b32_dpp v156, v84 row_ror:15 row_mask:0xf bank_mask:0xf
; #define LAS __attribute__((address_space(3)))
;     __device__ __forceinline__ void operator()(const f32x4 (&acc)[2][2][4][2], const Unit& u, int wr, int wc, int fr_in, int fq_in) const {
;     ...
;             for (int ai = 0; ai < 2; ++ai) { const int Bk = 2 * ai + wr;
; #pragma unroll
;                 for (int m = 0; m < 4; ++m) {
;                     const int r = 128 * ai + 64 * wr + 16 * m + fr, tb = 254 * j + r - 1;
;                     f32x4 res[2];
; #pragma unroll
;                     for (int bj = 0; bj < 2; ++bj) {
;                         const f32x4 cur = acc[ai][bj][m][n];
;                         f32x4 pe, ne;
;                         if (m > 0) { const f32x4 q = acc[ai][bj][m > 0 ? m - 1 : 0][n]; pe = (f32x4){dpp_ror1(q[0]), dpp_ror1(q[1]), dpp_ror1(q[2]), dpp_ror1(q[3])}; }
;                         else pe = *(const LAS f32x4*)(X + (((Bk > 0 ? Bk - 1 : 0) * 2 + 1) * 2 + bj) * 128 + cl + 4 * n);
;                         if (m < 3) { const f32x4 q = acc[ai][bj][m < 3 ? m + 1 : 3][n]; ne = (f32x4){dpp_rol1(q[0]), dpp_rol1(q[1]), dpp_rol1(q[2]), dpp_rol1(q[3])}; }
;                         else ne = *(const LAS f32x4*)(X + (((Bk < 3 ? Bk + 1 : 3) * 2 + 0) * 2 + bj) * 128 + cl + 4 * n);
;                         f32x4 pvv, nvv;
; #pragma unroll
;                         for (int e = 0; e < 4; ++e) {
;                             float pv = __int_as_float(__builtin_amdgcn_update_dpp(__float_as_int(pe[e]), __float_as_int(cur[e]), 0x111, 0xf, 0xf, false));
;                             float nv = __int_as_float(__builtin_amdgcn_update_dpp(__float_as_int(ne[e]), __float_as_int(cur[e]), 0x101, 0xf, 0xf, false));
;                             if (ai == 0 && m == 0) pv = (tb == 0) ? 0.f : pv;
;                             if (ai == 0 && m == 2) nv = (tb == SEQ - 1) ? 0.f : nv;
;                             pvv[e] = pv; nvv[e] = nv; }
;                         res[bj] = pvv * wv[0][bj] + (cur * wv[1][bj] + (nvv * wv[2][bj] + wv[3][bj]));
;                     }
;                     f32x4 y;
;                     { const f32x4 G = res[0], t = G * -1.4426950408889634f;
;                       f32x4 den; den[0] = __builtin_amdgcn_exp2f(t[0]); den[1] = __builtin_amdgcn_exp2f(t[1]); den[2] = __builtin_amdgcn_exp2f(t[2]); den[3] = __builtin_amdgcn_exp2f(t[3]);
;                       den = den + 1.0f;
	v_mov_b32_dpp v157, v85 row_ror:15 row_mask:0xf bank_mask:0xf
	v_mov_b32_dpp v158, v86 row_ror:15 row_mask:0xf bank_mask:0xf
	v_mov_b32_dpp v159, v87 row_ror:15 row_mask:0xf bank_mask:0xf
	v_pk_fma_f32 v[128:129], v[164:165], v[128:129], v[132:133]
	v_pk_fma_f32 v[130:131], v[166:167], v[130:131], v[140:141]
	s_nop 1
	v_mov_b32_dpp v156, v92 row_shl:1 row_mask:0xf bank_mask:0xf
	v_mov_b32_dpp v157, v93 row_shl:1 row_mask:0xf bank_mask:0xf
	v_mov_b32_dpp v158, v94 row_shl:1 row_mask:0xf bank_mask:0xf
	v_mov_b32_dpp v159, v95 row_shl:1 row_mask:0xf bank_mask:0xf
	v_mov_b32_dpp v132, v100 row_ror:1 row_mask:0xf bank_mask:0xf
	v_mov_b32_dpp v133, v101 row_ror:1 row_mask:0xf bank_mask:0xf
	v_mov_b32_dpp v140, v102 row_ror:1 row_mask:0xf bank_mask:0xf
	v_mov_b32_dpp v141, v103 row_ror:1 row_mask:0xf bank_mask:0xf
	v_pk_fma_f32 v[158:159], v[148:149], v[158:159], v[152:153]
	v_pk_fma_f32 v[156:157], v[146:147], v[156:157], v[150:151]
	v_mov_b32_dpp v132, v92 row_shr:1 row_mask:0xf bank_mask:0xf
	v_mov_b32_dpp v133, v93 row_shr:1 row_mask:0xf bank_mask:0xf
	v_mov_b32_dpp v140, v94 row_shr:1 row_mask:0xf bank_mask:0xf
	v_mov_b32_dpp v141, v95 row_shr:1 row_mask:0xf bank_mask:0xf
	v_pk_fma_f32 v[156:157], v[92:93], v[142:143], v[156:157]
	v_pk_fma_f32 v[158:159], v[94:95], v[144:145], v[158:159]
	v_pk_fma_f32 v[132:133], v[134:135], v[132:133], v[156:157]
	v_pk_fma_f32 v[140:141], v[136:137], v[140:141], v[158:159]
	v_pk_mul_f32 v[156:157], v[130:131], s[0:1] op_sel_hi:[1,0]
	v_pk_mul_f32 v[158:159], v[128:129], s[0:1] op_sel_hi:[1,0]
	v_exp_f32_e32 v156, v156
	v_exp_f32_e32 v158, v158
	v_exp_f32_e32 v159, v159
	v_exp_f32_e32 v157, v157
	v_pk_mul_f32 v[128:129], v[128:129], v[132:133]
	v_pk_mul_f32 v[130:131], v[130:131], v[140:141]
	v_pk_add_f32 v[158:159], v[158:159], 1.0 op_sel_hi:[1,0]
	v_pk_add_f32 v[156:157], v[156:157], 1.0 op_sel_hi:[1,0]
	v_rcp_f32_e32 v158, v158
	v_rcp_f32_e32 v159, v159
	v_rcp_f32_e32 v156, v156
	v_rcp_f32_e32 v157, v157
	v_add_u32_e32 v232, 32, v229
	s_nop 1
	v_add_u32_e32 v233, v232, v230
	v_mov_b32_dpp v132, v104 row_ror:15 row_mask:0xf bank_mask:0xf
	v_mov_b32_dpp v133, v105 row_ror:15 row_mask:0xf bank_mask:0xf
	v_mov_b32_dpp v139, v106 row_ror:15 row_mask:0xf bank_mask:0xf
	v_mov_b32_dpp v141, v107 row_ror:15 row_mask:0xf bank_mask:0xf
	v_pk_mul_f32 v[130:131], v[156:157], v[130:131]
	v_pk_mul_f32 v[128:129], v[158:159], v[128:129]
	v_cmp_eq_u32_e64 s[38:39], s93, v233
	v_mov_b32_dpp v132, v112 row_shl:1 row_mask:0xf bank_mask:0xf
	v_mov_b32_dpp v133, v113 row_shl:1 row_mask:0xf bank_mask:0xf
	v_mov_b32_dpp v139, v114 row_shl:1 row_mask:0xf bank_mask:0xf
	v_mov_b32_dpp v141, v115 row_shl:1 row_mask:0xf bank_mask:0xf
	v_cvt_pk_bf16_f32 v160, v128, v129
	v_cvt_pk_bf16_f32 v161, v130, v131
	s_nop 1
	v_cndmask_b32_e64 v132, v132, 0, s[38:39]
	v_cndmask_b32_e64 v133, v133, 0, s[38:39]
	v_cndmask_b32_e64 v140, v139, 0, s[38:39]
	v_cndmask_b32_e64 v141, v141, 0, s[38:39]
	s_nop 1
	v_mov_b32_dpp v128, v120 row_ror:1 row_mask:0xf bank_mask:0xf
	v_mov_b32_dpp v129, v121 row_ror:1 row_mask:0xf bank_mask:0xf
	v_mov_b32_dpp v130, v122 row_ror:1 row_mask:0xf bank_mask:0xf
	v_mov_b32_dpp v131, v123 row_ror:1 row_mask:0xf bank_mask:0xf
	v_pk_fma_f32 v[140:141], v[174:175], v[140:141], v[178:179]
	v_pk_fma_f32 v[132:133], v[172:173], v[132:133], v[176:177]
	v_mov_b32_dpp v139, v76 row_ror:15 row_mask:0xf bank_mask:0xf
	v_mov_b32_dpp v155, v77 row_ror:15 row_mask:0xf bank_mask:0xf
	v_mov_b32_dpp v158, v78 row_ror:15 row_mask:0xf bank_mask:0xf
	v_mov_b32_dpp v159, v79 row_ror:15 row_mask:0xf bank_mask:0xf
	v_mov_b32_dpp v128, v112 row_shr:1 row_mask:0xf bank_mask:0xf
	v_mov_b32_dpp v129, v113 row_shr:1 row_mask:0xf bank_mask:0xf
	v_mov_b32_dpp v130, v114 row_shr:1 row_mask:0xf bank_mask:0xf
	v_mov_b32_dpp v131, v115 row_shr:1 row_mask:0xf bank_mask:0xf
	v_pk_fma_f32 v[140:141], v[114:115], v[170:171], v[140:141]
	v_pk_fma_f32 v[132:133], v[112:113], v[168:169], v[132:133]
	v_mov_b32_dpp v139, v84 row_shl:1 row_mask:0xf bank_mask:0xf
	v_mov_b32_dpp v155, v85 row_shl:1 row_mask:0xf bank_mask:0xf
	v_mov_b32_dpp v158, v86 row_shl:1 row_mask:0xf bank_mask:0xf
	v_mov_b32_dpp v159, v87 row_shl:1 row_mask:0xf bank_mask:0xf
	v_pk_fma_f32 v[130:131], v[166:167], v[130:131], v[140:141]
	v_pk_fma_f32 v[128:129], v[164:165], v[128:129], v[132:133]
	s_nop 1
	v_cndmask_b32_e64 v156, v139, 0, s[38:39]
	v_cndmask_b32_e64 v157, v155, 0, s[38:39]
	v_cndmask_b32_e64 v158, v158, 0, s[38:39]
	v_cndmask_b32_e64 v159, v159, 0, s[38:39]
	v_mov_b32_dpp v132, v92 row_ror:1 row_mask:0xf bank_mask:0xf
	v_mov_b32_dpp v133, v93 row_ror:1 row_mask:0xf bank_mask:0xf
	v_mov_b32_dpp v140, v94 row_ror:1 row_mask:0xf bank_mask:0xf
	v_mov_b32_dpp v141, v95 row_ror:1 row_mask:0xf bank_mask:0xf
	v_pk_fma_f32 v[158:159], v[148:149], v[158:159], v[152:153]
	v_pk_fma_f32 v[156:157], v[146:147], v[156:157], v[150:151]
	v_mov_b32_dpp v132, v84 row_shr:1 row_mask:0xf bank_mask:0xf
	v_mov_b32_dpp v133, v85 row_shr:1 row_mask:0xf bank_mask:0xf
	v_mov_b32_dpp v140, v86 row_shr:1 row_mask:0xf bank_mask:0xf
	v_mov_b32_dpp v141, v87 row_shr:1 row_mask:0xf bank_mask:0xf
	v_pk_fma_f32 v[158:159], v[86:87], v[144:145], v[158:159]
	v_pk_fma_f32 v[156:157], v[84:85], v[142:143], v[156:157]
	v_pk_fma_f32 v[140:141], v[136:137], v[140:141], v[158:159]
	v_pk_fma_f32 v[132:133], v[134:135], v[132:133], v[156:157]
	v_pk_mul_f32 v[156:157], v[130:131], s[0:1] op_sel_hi:[1,0]
	v_pk_mul_f32 v[158:159], v[128:129], s[0:1] op_sel_hi:[1,0]
	v_exp_f32_e32 v156, v156
	v_exp_f32_e32 v158, v158
	v_exp_f32_e32 v159, v159
	v_exp_f32_e32 v157, v157
	v_pk_mul_f32 v[130:131], v[130:131], v[140:141]
	v_pk_mul_f32 v[128:129], v[128:129], v[132:133]
	v_pk_add_f32 v[158:159], v[158:159], 1.0 op_sel_hi:[1,0]
	v_pk_add_f32 v[156:157], v[156:157], 1.0 op_sel_hi:[1,0]
	v_rcp_f32_e32 v158, v158
	v_rcp_f32_e32 v159, v159
	v_rcp_f32_e32 v156, v156
	v_rcp_f32_e32 v157, v157
	v_readlane_b32 s1, v254, 57
	v_pk_mul_f32 v[128:129], v[158:159], v[128:129]
	s_nop 1
	v_pk_mul_f32 v[130:131], v[156:157], v[130:131]
	v_add_u32_e32 v234, s1, v138
	v_cvt_pk_bf16_f32 v158, v128, v129
	v_cvt_pk_bf16_f32 v159, v130, v131
	ds_read_b128 v[128:131], v234 offset:2048
	s_nop 1
	v_mov_b32_dpp v132, v112 row_ror:1 row_mask:0xf bank_mask:0xf
	s_waitcnt lgkmcnt(0)
; #define LAS __attribute__((address_space(3)))
;     __device__ __forceinline__ void operator()(const f32x4 (&acc)[2][2][4][2], const Unit& u, int wr, int wc, int fr_in, int fq_in) const {
;     ...
;             for (int ai = 0; ai < 2; ++ai) { const int Bk = 2 * ai + wr;
; #pragma unroll
;                 for (int m = 0; m < 4; ++m) {
;                     const int r = 128 * ai + 64 * wr + 16 * m + fr, tb = 254 * j + r - 1;
;                     f32x4 res[2];
; #pragma unroll
;                     for (int bj = 0; bj < 2; ++bj) {
;                         const f32x4 cur = acc[ai][bj][m][n];
;                         f32x4 pe, ne;
;                         if (m > 0) { const f32x4 q = acc[ai][bj][m > 0 ? m - 1 : 0][n]; pe = (f32x4){dpp_ror1(q[0]), dpp_ror1(q[1]), dpp_ror1(q[2]), dpp_ror1(q[3])}; }
;                         else pe = *(const LAS f32x4*)(X + (((Bk > 0 ? Bk - 1 : 0) * 2 + 1) * 2 + bj) * 128 + cl + 4 * n);
;                         if (m < 3) { const f32x4 q = acc[ai][bj][m < 3 ? m + 1 : 3][n]; ne = (f32x4){dpp_rol1(q[0]), dpp_rol1(q[1]), dpp_rol1(q[2]), dpp_rol1(q[3])}; }
;                         else ne = *(const LAS f32x4*)(X + (((Bk < 3 ? Bk + 1 : 3) * 2 + 0) * 2 + bj) * 128 + cl + 4 * n);
;                         f32x4 pvv, nvv;
; #pragma unroll
;                         for (int e = 0; e < 4; ++e) {
;                             float pv = __int_as_float(__builtin_amdgcn_update_dpp(__float_as_int(pe[e]), __float_as_int(cur[e]), 0x111, 0xf, 0xf, false));
;                             float nv = __int_as_float(__builtin_amdgcn_update_dpp(__float_as_int(ne[e]), __float_as_int(cur[e]), 0x101, 0xf, 0xf, false));
;                             if (ai == 0 && m == 0) pv = (tb == 0) ? 0.f : pv;
;                             if (ai == 0 && m == 2) nv = (tb == SEQ - 1) ? 0.f : nv;
;                             pvv[e] = pv; nvv[e] = nv; }
;                         res[bj] = pvv * wv[0][bj] + (cur * wv[1][bj] + (nvv * wv[2][bj] + wv[3][bj]));
;                     }
;                     f32x4 y;
;                     { const f32x4 G = res[0], t = G * -1.4426950408889634f;
;                       f32x4 den; den[0] = __builtin_amdgcn_exp2f(t[0]); den[1] = __builtin_amdgcn_exp2f(t[1]); den[2] = __builtin_amdgcn_exp2f(t[2]); den[3] = __builtin_amdgcn_exp2f(t[3]);
;                       den = den + 1.0f;
	v_mov_b32_dpp v128, v104 row_shl:1 row_mask:0xf bank_mask:0xf
	v_mov_b32_dpp v129, v105 row_shl:1 row_mask:0xf bank_mask:0xf
	v_mov_b32_dpp v130, v106 row_shl:1 row_mask:0xf bank_mask:0xf
	v_mov_b32_dpp v131, v107 row_shl:1 row_mask:0xf bank_mask:0xf
	v_mov_b32_dpp v133, v113 row_ror:1 row_mask:0xf bank_mask:0xf
	v_mov_b32_dpp v140, v114 row_ror:1 row_mask:0xf bank_mask:0xf
	v_mov_b32_dpp v141, v115 row_ror:1 row_mask:0xf bank_mask:0xf
	v_pk_fma_f32 v[128:129], v[172:173], v[128:129], v[176:177]
	v_pk_fma_f32 v[130:131], v[174:175], v[130:131], v[178:179]
	v_mov_b32_dpp v132, v104 row_shr:1 row_mask:0xf bank_mask:0xf
	v_mov_b32_dpp v133, v105 row_shr:1 row_mask:0xf bank_mask:0xf
	v_mov_b32_dpp v140, v106 row_shr:1 row_mask:0xf bank_mask:0xf
	v_mov_b32_dpp v141, v107 row_shr:1 row_mask:0xf bank_mask:0xf
	v_pk_fma_f32 v[130:131], v[106:107], v[170:171], v[130:131]
	v_pk_fma_f32 v[128:129], v[104:105], v[168:169], v[128:129]
	v_pk_fma_f32 v[140:141], v[166:167], v[140:141], v[130:131]
	v_pk_fma_f32 v[132:133], v[164:165], v[132:133], v[128:129]
	ds_read_b128 v[128:131], v234 offset:2560
	s_nop 1
	s_waitcnt lgkmcnt(0)
	v_mov_b32_dpp v128, v76 row_shl:1 row_mask:0xf bank_mask:0xf
	v_mov_b32_dpp v129, v77 row_shl:1 row_mask:0xf bank_mask:0xf
	v_mov_b32_dpp v130, v78 row_shl:1 row_mask:0xf bank_mask:0xf
	v_mov_b32_dpp v131, v79 row_shl:1 row_mask:0xf bank_mask:0xf
	v_mov_b32_dpp v156, v84 row_ror:1 row_mask:0xf bank_mask:0xf
	v_mov_b32_dpp v157, v85 row_ror:1 row_mask:0xf bank_mask:0xf
	v_mov_b32_dpp v180, v86 row_ror:1 row_mask:0xf bank_mask:0xf
	v_mov_b32_dpp v181, v87 row_ror:1 row_mask:0xf bank_mask:0xf
	v_pk_fma_f32 v[130:131], v[148:149], v[130:131], v[152:153]
	v_pk_fma_f32 v[128:129], v[146:147], v[128:129], v[150:151]
	v_mov_b32_dpp v156, v76 row_shr:1 row_mask:0xf bank_mask:0xf
	v_mov_b32_dpp v157, v77 row_shr:1 row_mask:0xf bank_mask:0xf
	v_mov_b32_dpp v180, v78 row_shr:1 row_mask:0xf bank_mask:0xf
	v_mov_b32_dpp v181, v79 row_shr:1 row_mask:0xf bank_mask:0xf
	v_pk_fma_f32 v[128:129], v[76:77], v[142:143], v[128:129]
	v_pk_fma_f32 v[130:131], v[78:79], v[144:145], v[130:131]
	v_pk_fma_f32 v[128:129], v[134:135], v[156:157], v[128:129]
	v_pk_fma_f32 v[130:131], v[136:137], v[180:181], v[130:131]
	v_pk_mul_f32 v[156:157], v[140:141], s[0:1] op_sel_hi:[1,0]
	v_pk_mul_f32 v[180:181], v[132:133], s[0:1] op_sel_hi:[1,0]
	v_exp_f32_e32 v156, v156
	v_exp_f32_e32 v180, v180
	v_exp_f32_e32 v181, v181
	v_exp_f32_e32 v157, v157
	v_pk_mul_f32 v[128:129], v[132:133], v[128:129]
	v_pk_mul_f32 v[130:131], v[140:141], v[130:131]
	v_pk_add_f32 v[180:181], v[180:181], 1.0 op_sel_hi:[1,0]
	v_pk_add_f32 v[156:157], v[156:157], 1.0 op_sel_hi:[1,0]
	v_rcp_f32_e32 v180, v180
	v_rcp_f32_e32 v181, v181
	v_rcp_f32_e32 v156, v156
	v_rcp_f32_e32 v157, v157
	v_readlane_b32 s1, v255, 2
	v_pk_mul_f32 v[128:129], v[180:181], v[128:129]
	s_nop 1
	v_pk_mul_f32 v[130:131], v[156:157], v[130:131]
	v_add_u32_e32 v236, s1, v138
	v_cvt_pk_bf16_f32 v156, v128, v129
	v_cvt_pk_bf16_f32 v157, v130, v131
	ds_read_b128 v[128:131], v236
	s_nop 1
	v_mov_b32_dpp v132, v64 row_ror:15 row_mask:0xf bank_mask:0xf
	s_nop 1
	v_mov_b32_dpp v133, v65 row_ror:15 row_mask:0xf bank_mask:0xf
	s_nop 1
	v_mov_b32_dpp v140, v66 row_ror:15 row_mask:0xf bank_mask:0xf
	v_mov_b32_dpp v132, v68 row_shl:1 row_mask:0xf bank_mask:0xf
	v_mov_b32_dpp v141, v67 row_ror:15 row_mask:0xf bank_mask:0xf
	v_mov_b32_dpp v133, v69 row_shl:1 row_mask:0xf bank_mask:0xf
	v_mov_b32_dpp v140, v70 row_shl:1 row_mask:0xf bank_mask:0xf
	v_mov_b32_dpp v141, v71 row_shl:1 row_mask:0xf bank_mask:0xf
	v_pk_fma_f32 v[132:133], v[172:173], v[132:133], v[176:177]
	v_readlane_b32 s1, v254, 58
	s_waitcnt lgkmcnt(0)
	v_mov_b32_dpp v128, v68 row_shr:1 row_mask:0xf bank_mask:0xf
	v_mov_b32_dpp v129, v69 row_shr:1 row_mask:0xf bank_mask:0xf
	v_pk_fma_f32 v[140:141], v[174:175], v[140:141], v[178:179]
	v_pk_fma_f32 v[132:133], v[68:69], v[168:169], v[132:133]
	v_add_u32_e32 v235, s1, v138
	v_mov_b32_dpp v130, v70 row_shr:1 row_mask:0xf bank_mask:0xf
	v_mov_b32_dpp v131, v71 row_shr:1 row_mask:0xf bank_mask:0xf
	v_pk_fma_f32 v[140:141], v[70:71], v[170:171], v[140:141]
	v_pk_fma_f32 v[132:133], v[164:165], v[128:129], v[132:133]
	v_add_u32_e32 v128, 0xfffffe00, v235
	v_pk_fma_f32 v[140:141], v[166:167], v[130:131], v[140:141]
	ds_read_b128 v[128:131], v128
	s_nop 1
	v_mov_b32_dpp v180, v36 row_ror:15 row_mask:0xf bank_mask:0xf
	v_mov_b32_dpp v181, v37 row_ror:15 row_mask:0xf bank_mask:0xf
	v_mov_b32_dpp v212, v38 row_ror:15 row_mask:0xf bank_mask:0xf
	v_mov_b32_dpp v213, v39 row_ror:15 row_mask:0xf bank_mask:0xf
	v_mov_b32_dpp v180, v44 row_shl:1 row_mask:0xf bank_mask:0xf
	v_mov_b32_dpp v181, v45 row_shl:1 row_mask:0xf bank_mask:0xf
	v_mov_b32_dpp v212, v46 row_shl:1 row_mask:0xf bank_mask:0xf
	v_mov_b32_dpp v213, v47 row_shl:1 row_mask:0xf bank_mask:0xf
	v_pk_fma_f32 v[212:213], v[148:149], v[212:213], v[152:153]
	v_pk_fma_f32 v[180:181], v[146:147], v[180:181], v[150:151]
	s_waitcnt lgkmcnt(0)
; #define LAS __attribute__((address_space(3)))
;     __device__ __forceinline__ void operator()(const f32x4 (&acc)[2][2][4][2], const Unit& u, int wr, int wc, int fr_in, int fq_in) const {
;     ...
;             for (int ai = 0; ai < 2; ++ai) { const int Bk = 2 * ai + wr;
; #pragma unroll
;                 for (int m = 0; m < 4; ++m) {
;                     const int r = 128 * ai + 64 * wr + 16 * m + fr, tb = 254 * j + r - 1;
;                     f32x4 res[2];
; #pragma unroll
;                     for (int bj = 0; bj < 2; ++bj) {
;                         const f32x4 cur = acc[ai][bj][m][n];
;                         f32x4 pe, ne;
;                         if (m > 0) { const f32x4 q = acc[ai][bj][m > 0 ? m - 1 : 0][n]; pe = (f32x4){dpp_ror1(q[0]), dpp_ror1(q[1]), dpp_ror1(q[2]), dpp_ror1(q[3])}; }
;                         else pe = *(const LAS f32x4*)(X + (((Bk > 0 ? Bk - 1 : 0) * 2 + 1) * 2 + bj) * 128 + cl + 4 * n);
;                         if (m < 3) { const f32x4 q = acc[ai][bj][m < 3 ? m + 1 : 3][n]; ne = (f32x4){dpp_rol1(q[0]), dpp_rol1(q[1]), dpp_rol1(q[2]), dpp_rol1(q[3])}; }
;                         else ne = *(const LAS f32x4*)(X + (((Bk < 3 ? Bk + 1 : 3) * 2 + 0) * 2 + bj) * 128 + cl + 4 * n);
;                         f32x4 pvv, nvv;
; #pragma unroll
;                         for (int e = 0; e < 4; ++e) {
;                             float pv = __int_as_float(__builtin_amdgcn_update_dpp(__float_as_int(pe[e]), __float_as_int(cur[e]), 0x111, 0xf, 0xf, false));
;                             float nv = __int_as_float(__builtin_amdgcn_update_dpp(__float_as_int(ne[e]), __float_as_int(cur[e]), 0x101, 0xf, 0xf, false));
;                             if (ai == 0 && m == 0) pv = (tb == 0) ? 0.f : pv;
;                             if (ai == 0 && m == 2) nv = (tb == SEQ - 1) ? 0.f : nv;
;                             pvv[e] = pv; nvv[e] = nv; }
;                         res[bj] = pvv * wv[0][bj] + (cur * wv[1][bj] + (nvv * wv[2][bj] + wv[3][bj]));
;                     }
;                     f32x4 y;
;                     { const f32x4 G = res[0], t = G * -1.4426950408889634f;
;                       f32x4 den; den[0] = __builtin_amdgcn_exp2f(t[0]); den[1] = __builtin_amdgcn_exp2f(t[1]); den[2] = __builtin_amdgcn_exp2f(t[2]); den[3] = __builtin_amdgcn_exp2f(t[3]);
;                       den = den + 1.0f;
	v_mov_b32_dpp v128, v44 row_shr:1 row_mask:0xf bank_mask:0xf
	v_mov_b32_dpp v129, v45 row_shr:1 row_mask:0xf bank_mask:0xf
	v_mov_b32_dpp v130, v46 row_shr:1 row_mask:0xf bank_mask:0xf
	v_mov_b32_dpp v131, v47 row_shr:1 row_mask:0xf bank_mask:0xf
	v_pk_fma_f32 v[180:181], v[44:45], v[142:143], v[180:181]
	v_pk_fma_f32 v[212:213], v[46:47], v[144:145], v[212:213]
	v_pk_fma_f32 v[128:129], v[134:135], v[128:129], v[180:181]
	v_pk_fma_f32 v[130:131], v[136:137], v[130:131], v[212:213]
	v_pk_mul_f32 v[180:181], v[140:141], s[0:1] op_sel_hi:[1,0]
	v_pk_mul_f32 v[212:213], v[132:133], s[0:1] op_sel_hi:[1,0]
	v_exp_f32_e32 v180, v180
	v_exp_f32_e32 v212, v212
	v_exp_f32_e32 v213, v213
	v_exp_f32_e32 v181, v181
	v_pk_mul_f32 v[128:129], v[132:133], v[128:129]
	v_pk_mul_f32 v[130:131], v[140:141], v[130:131]
	v_pk_add_f32 v[212:213], v[212:213], 1.0 op_sel_hi:[1,0]
	v_pk_add_f32 v[180:181], v[180:181], 1.0 op_sel_hi:[1,0]
	v_rcp_f32_e32 v212, v212
	v_rcp_f32_e32 v213, v213
	v_rcp_f32_e32 v180, v180
	v_rcp_f32_e32 v181, v181
	s_nop 1
	v_pk_mul_f32 v[128:129], v[212:213], v[128:129]
	v_pk_mul_f32 v[130:131], v[180:181], v[130:131]
	v_mov_b32_dpp v132, v56 row_ror:15 row_mask:0xf bank_mask:0xf
	v_mov_b32_dpp v133, v57 row_ror:15 row_mask:0xf bank_mask:0xf
	s_nop 1
	v_cvt_pk_bf16_f32 v140, v128, v129
	s_nop 1
	v_mov_b32_dpp v180, v58 row_ror:15 row_mask:0xf bank_mask:0xf
	v_mov_b32_dpp v181, v59 row_ror:15 row_mask:0xf bank_mask:0xf
	v_mov_b32_dpp v132, v64 row_shl:1 row_mask:0xf bank_mask:0xf
	v_mov_b32_dpp v133, v65 row_shl:1 row_mask:0xf bank_mask:0xf
	v_cvt_pk_bf16_f32 v141, v130, v131
	v_mov_b32_dpp v128, v68 row_ror:1 row_mask:0xf bank_mask:0xf
	v_mov_b32_dpp v129, v69 row_ror:1 row_mask:0xf bank_mask:0xf
	s_nop 1
	v_mov_b32_dpp v180, v66 row_shl:1 row_mask:0xf bank_mask:0xf
	v_mov_b32_dpp v181, v67 row_shl:1 row_mask:0xf bank_mask:0xf
	v_pk_fma_f32 v[132:133], v[172:173], v[132:133], v[176:177]
	s_nop 1
	v_mov_b32_dpp v130, v70 row_ror:1 row_mask:0xf bank_mask:0xf
	v_mov_b32_dpp v131, v71 row_ror:1 row_mask:0xf bank_mask:0xf
	v_mov_b32_dpp v128, v64 row_shr:1 row_mask:0xf bank_mask:0xf
	v_mov_b32_dpp v129, v65 row_shr:1 row_mask:0xf bank_mask:0xf
	v_pk_fma_f32 v[180:181], v[174:175], v[180:181], v[178:179]
	v_pk_fma_f32 v[132:133], v[64:65], v[168:169], v[132:133]
	v_mov_b32_dpp v212, v28 row_ror:15 row_mask:0xf bank_mask:0xf
	v_mov_b32_dpp v213, v29 row_ror:15 row_mask:0xf bank_mask:0xf
	s_nop 1
	v_mov_b32_dpp v130, v66 row_shr:1 row_mask:0xf bank_mask:0xf
	v_mov_b32_dpp v131, v67 row_shr:1 row_mask:0xf bank_mask:0xf
	v_pk_fma_f32 v[180:181], v[66:67], v[170:171], v[180:181]
	v_pk_fma_f32 v[128:129], v[164:165], v[128:129], v[132:133]
	s_nop 1
	v_mov_b32_dpp v214, v30 row_ror:15 row_mask:0xf bank_mask:0xf
	v_mov_b32_dpp v215, v31 row_ror:15 row_mask:0xf bank_mask:0xf
	v_mov_b32_dpp v212, v36 row_shl:1 row_mask:0xf bank_mask:0xf
	v_mov_b32_dpp v213, v37 row_shl:1 row_mask:0xf bank_mask:0xf
	v_pk_fma_f32 v[130:131], v[166:167], v[130:131], v[180:181]
	v_mov_b32_dpp v132, v44 row_ror:1 row_mask:0xf bank_mask:0xf
	v_mov_b32_dpp v133, v45 row_ror:1 row_mask:0xf bank_mask:0xf
	s_nop 1
	v_mov_b32_dpp v214, v38 row_shl:1 row_mask:0xf bank_mask:0xf
	v_mov_b32_dpp v215, v39 row_shl:1 row_mask:0xf bank_mask:0xf
	v_pk_fma_f32 v[212:213], v[146:147], v[212:213], v[150:151]
	v_mov_b32_dpp v180, v46 row_ror:1 row_mask:0xf bank_mask:0xf
	v_mov_b32_dpp v181, v47 row_ror:1 row_mask:0xf bank_mask:0xf
	v_mov_b32_dpp v132, v36 row_shr:1 row_mask:0xf bank_mask:0xf
	v_mov_b32_dpp v133, v37 row_shr:1 row_mask:0xf bank_mask:0xf
	v_pk_fma_f32 v[214:215], v[148:149], v[214:215], v[152:153]
	v_pk_fma_f32 v[212:213], v[36:37], v[142:143], v[212:213]
	v_mov_b32_dpp v180, v38 row_shr:1 row_mask:0xf bank_mask:0xf
	v_mov_b32_dpp v181, v39 row_shr:1 row_mask:0xf bank_mask:0xf
	v_pk_fma_f32 v[214:215], v[38:39], v[144:145], v[214:215]
	v_pk_fma_f32 v[132:133], v[134:135], v[132:133], v[212:213]
	v_pk_mul_f32 v[212:213], v[130:131], s[0:1] op_sel_hi:[1,0]
	v_pk_fma_f32 v[180:181], v[136:137], v[180:181], v[214:215]
	v_pk_mul_f32 v[214:215], v[128:129], s[0:1] op_sel_hi:[1,0]
	v_exp_f32_e32 v212, v212
	v_exp_f32_e32 v213, v213
	v_exp_f32_e32 v214, v214
	v_exp_f32_e32 v215, v215
	v_pk_mul_f32 v[130:131], v[130:131], v[180:181]
	v_pk_add_f32 v[212:213], v[212:213], 1.0 op_sel_hi:[1,0]
	v_pk_mul_f32 v[128:129], v[128:129], v[132:133]
	v_pk_add_f32 v[214:215], v[214:215], 1.0 op_sel_hi:[1,0]
	v_rcp_f32_e32 v212, v212
	v_rcp_f32_e32 v213, v213
	v_rcp_f32_e32 v214, v214
	v_rcp_f32_e32 v215, v215
	s_nop 1
	v_pk_mul_f32 v[130:131], v[212:213], v[130:131]
	s_nop 1
	v_pk_mul_f32 v[128:129], v[214:215], v[128:129]
	v_mov_b32_dpp v180, v48 row_ror:15 row_mask:0xf bank_mask:0xf
	v_mov_b32_dpp v181, v49 row_ror:15 row_mask:0xf bank_mask:0xf
	v_mov_b32_dpp v212, v50 row_ror:15 row_mask:0xf bank_mask:0xf
	v_mov_b32_dpp v213, v51 row_ror:15 row_mask:0xf bank_mask:0xf
	v_cvt_pk_bf16_f32 v132, v128, v129
	v_cvt_pk_bf16_f32 v133, v130, v131
	s_nop 1
	v_mov_b32_dpp v180, v56 row_shl:1 row_mask:0xf bank_mask:0xf
	v_mov_b32_dpp v181, v57 row_shl:1 row_mask:0xf bank_mask:0xf
	v_mov_b32_dpp v212, v58 row_shl:1 row_mask:0xf bank_mask:0xf
	v_mov_b32_dpp v213, v59 row_shl:1 row_mask:0xf bank_mask:0xf
	v_mov_b32_dpp v128, v64 row_ror:1 row_mask:0xf bank_mask:0xf
	v_mov_b32_dpp v129, v65 row_ror:1 row_mask:0xf bank_mask:0xf
	v_mov_b32_dpp v130, v66 row_ror:1 row_mask:0xf bank_mask:0xf
	v_mov_b32_dpp v131, v67 row_ror:1 row_mask:0xf bank_mask:0xf
	v_pk_fma_f32 v[180:181], v[172:173], v[180:181], v[176:177]
	v_pk_fma_f32 v[212:213], v[174:175], v[212:213], v[178:179]
	s_nop 1
; #define LAS __attribute__((address_space(3)))
;     __device__ __forceinline__ void operator()(const f32x4 (&acc)[2][2][4][2], const Unit& u, int wr, int wc, int fr_in, int fq_in) const {
;     ...
;         for (int n = 0; n < 2; ++n) {
;             f32x4 wv[4][2];
; #pragma unroll
;             for (int k = 0; k < 4; ++k)
; #pragma unroll
;                 for (int bj = 0; bj < 2; ++bj) wv[k][bj] = *(const LAS f32x4*)(W + (k * 2 + bj) * 128 + cl + 4 * n);
; #pragma unroll
;             for (int ai = 0; ai < 2; ++ai) { const int Bk = 2 * ai + wr;
; #pragma unroll
;                 for (int m = 0; m < 4; ++m) {
;                     const int r = 128 * ai + 64 * wr + 16 * m + fr, tb = 254 * j + r - 1;
;                     f32x4 res[2];
; #pragma unroll
;                     for (int bj = 0; bj < 2; ++bj) {
;                         const f32x4 cur = acc[ai][bj][m][n];
;                         f32x4 pe, ne;
;                         if (m > 0) { const f32x4 q = acc[ai][bj][m > 0 ? m - 1 : 0][n]; pe = (f32x4){dpp_ror1(q[0]), dpp_ror1(q[1]), dpp_ror1(q[2]), dpp_ror1(q[3])}; }
;                         else pe = *(const LAS f32x4*)(X + (((Bk > 0 ? Bk - 1 : 0) * 2 + 1) * 2 + bj) * 128 + cl + 4 * n);
;                         if (m < 3) { const f32x4 q = acc[ai][bj][m < 3 ? m + 1 : 3][n]; ne = (f32x4){dpp_rol1(q[0]), dpp_rol1(q[1]), dpp_rol1(q[2]), dpp_rol1(q[3])}; }
;                         else ne = *(const LAS f32x4*)(X + (((Bk < 3 ? Bk + 1 : 3) * 2 + 0) * 2 + bj) * 128 + cl + 4 * n);
;                         f32x4 pvv, nvv;
; #pragma unroll
;                         for (int e = 0; e < 4; ++e) {
;                             float pv = __int_as_float(__builtin_amdgcn_update_dpp(__float_as_int(pe[e]), __float_as_int(cur[e]), 0x111, 0xf, 0xf, false));
;                             float nv = __int_as_float(__builtin_amdgcn_update_dpp(__float_as_int(ne[e]), __float_as_int(cur[e]), 0x101, 0xf, 0xf, false));
;                             if (ai == 0 && m == 0) pv = (tb == 0) ? 0.f : pv;
;                             if (ai == 0 && m == 2) nv = (tb == SEQ - 1) ? 0.f : nv;
;                             pvv[e] = pv; nvv[e] = nv; }
;                         res[bj] = pvv * wv[0][bj] + (cur * wv[1][bj] + (nvv * wv[2][bj] + wv[3][bj]));
;                     }
;                     f32x4 y;
;                     { const f32x4 G = res[0], t = G * -1.4426950408889634f;
	v_mov_b32_dpp v128, v56 row_shr:1 row_mask:0xf bank_mask:0xf
	v_mov_b32_dpp v129, v57 row_shr:1 row_mask:0xf bank_mask:0xf
	v_mov_b32_dpp v130, v58 row_shr:1 row_mask:0xf bank_mask:0xf
	v_mov_b32_dpp v131, v59 row_shr:1 row_mask:0xf bank_mask:0xf
	v_pk_fma_f32 v[212:213], v[58:59], v[170:171], v[212:213]
	v_pk_fma_f32 v[180:181], v[56:57], v[168:169], v[180:181]
	v_mov_b32_dpp v214, v20 row_ror:15 row_mask:0xf bank_mask:0xf
	v_mov_b32_dpp v215, v21 row_ror:15 row_mask:0xf bank_mask:0xf
	v_mov_b32_dpp v218, v22 row_ror:15 row_mask:0xf bank_mask:0xf
	v_mov_b32_dpp v219, v23 row_ror:15 row_mask:0xf bank_mask:0xf
	v_pk_fma_f32 v[128:129], v[164:165], v[128:129], v[180:181]
	v_pk_fma_f32 v[130:131], v[166:167], v[130:131], v[212:213]
	s_nop 1
	v_mov_b32_dpp v214, v28 row_shl:1 row_mask:0xf bank_mask:0xf
	v_mov_b32_dpp v215, v29 row_shl:1 row_mask:0xf bank_mask:0xf
	v_mov_b32_dpp v218, v30 row_shl:1 row_mask:0xf bank_mask:0xf
	v_mov_b32_dpp v219, v31 row_shl:1 row_mask:0xf bank_mask:0xf
	v_mov_b32_dpp v180, v36 row_ror:1 row_mask:0xf bank_mask:0xf
	v_mov_b32_dpp v181, v37 row_ror:1 row_mask:0xf bank_mask:0xf
	v_mov_b32_dpp v212, v38 row_ror:1 row_mask:0xf bank_mask:0xf
	v_mov_b32_dpp v213, v39 row_ror:1 row_mask:0xf bank_mask:0xf
	v_pk_fma_f32 v[218:219], v[148:149], v[218:219], v[152:153]
	v_pk_fma_f32 v[214:215], v[146:147], v[214:215], v[150:151]
	v_mov_b32_dpp v180, v28 row_shr:1 row_mask:0xf bank_mask:0xf
	v_mov_b32_dpp v181, v29 row_shr:1 row_mask:0xf bank_mask:0xf
	v_mov_b32_dpp v212, v30 row_shr:1 row_mask:0xf bank_mask:0xf
	v_mov_b32_dpp v213, v31 row_shr:1 row_mask:0xf bank_mask:0xf
	v_pk_fma_f32 v[214:215], v[28:29], v[142:143], v[214:215]
	v_pk_fma_f32 v[218:219], v[30:31], v[144:145], v[218:219]
	v_pk_fma_f32 v[180:181], v[134:135], v[180:181], v[214:215]
	v_pk_fma_f32 v[212:213], v[136:137], v[212:213], v[218:219]
	v_pk_mul_f32 v[214:215], v[130:131], s[0:1] op_sel_hi:[1,0]
	v_pk_mul_f32 v[218:219], v[128:129], s[0:1] op_sel_hi:[1,0]
	v_exp_f32_e32 v214, v214
	v_exp_f32_e32 v218, v218
	v_exp_f32_e32 v219, v219
	v_exp_f32_e32 v215, v215
	v_readlane_b32 s1, v255, 1
	v_pk_mul_f32 v[128:129], v[128:129], v[180:181]
	v_pk_add_f32 v[218:219], v[218:219], 1.0 op_sel_hi:[1,0]
	v_pk_add_f32 v[214:215], v[214:215], 1.0 op_sel_hi:[1,0]
	v_rcp_f32_e32 v218, v218
	v_rcp_f32_e32 v219, v219
	v_rcp_f32_e32 v214, v214
	v_rcp_f32_e32 v215, v215
	v_pk_mul_f32 v[130:131], v[130:131], v[212:213]
	v_add_u32_e32 v231, s1, v138
	v_pk_mul_f32 v[128:129], v[218:219], v[128:129]
	v_pk_mul_f32 v[180:181], v[214:215], v[130:131]
	v_cvt_pk_bf16_f32 v130, v128, v129
	s_nop 1
	v_cvt_pk_bf16_f32 v131, v180, v181
	ds_read_b128 v[240:243], v231 offset:2048
	s_nop 1
	v_mov_b32_dpp v128, v56 row_ror:1 row_mask:0xf bank_mask:0xf
	s_waitcnt lgkmcnt(0)
	v_mov_b32_dpp v240, v48 row_shl:1 row_mask:0xf bank_mask:0xf
	v_mov_b32_dpp v241, v49 row_shl:1 row_mask:0xf bank_mask:0xf
	v_mov_b32_dpp v242, v50 row_shl:1 row_mask:0xf bank_mask:0xf
	v_mov_b32_dpp v243, v51 row_shl:1 row_mask:0xf bank_mask:0xf
	v_mov_b32_dpp v129, v57 row_ror:1 row_mask:0xf bank_mask:0xf
	v_mov_b32_dpp v180, v58 row_ror:1 row_mask:0xf bank_mask:0xf
	v_mov_b32_dpp v181, v59 row_ror:1 row_mask:0xf bank_mask:0xf
	v_pk_fma_f32 v[138:139], v[172:173], v[240:241], v[176:177]
	v_pk_fma_f32 v[172:173], v[174:175], v[242:243], v[178:179]
	v_mov_b32_dpp v128, v48 row_shr:1 row_mask:0xf bank_mask:0xf
	v_mov_b32_dpp v129, v49 row_shr:1 row_mask:0xf bank_mask:0xf
	v_mov_b32_dpp v180, v50 row_shr:1 row_mask:0xf bank_mask:0xf
	v_mov_b32_dpp v181, v51 row_shr:1 row_mask:0xf bank_mask:0xf
	v_pk_fma_f32 v[170:171], v[50:51], v[170:171], v[172:173]
	v_pk_fma_f32 v[138:139], v[48:49], v[168:169], v[138:139]
	s_nop 1
	v_pk_fma_f32 v[128:129], v[164:165], v[128:129], v[138:139]
	v_pk_fma_f32 v[138:139], v[166:167], v[180:181], v[170:171]
	ds_read_b128 v[164:167], v231 offset:2560
	s_nop 1
	v_mov_b32_dpp v170, v30 row_ror:1 row_mask:0xf bank_mask:0xf
	s_waitcnt lgkmcnt(0)
	v_mov_b32_dpp v166, v22 row_shl:1 row_mask:0xf bank_mask:0xf
	v_mov_b32_dpp v167, v23 row_shl:1 row_mask:0xf bank_mask:0xf
	v_mov_b32_dpp v171, v31 row_ror:1 row_mask:0xf bank_mask:0xf
	v_mov_b32_dpp v164, v20 row_shl:1 row_mask:0xf bank_mask:0xf
	v_mov_b32_dpp v165, v21 row_shl:1 row_mask:0xf bank_mask:0xf
	v_pk_fma_f32 v[148:149], v[148:149], v[166:167], v[152:153]
	v_mov_b32_dpp v168, v28 row_ror:1 row_mask:0xf bank_mask:0xf
	v_mov_b32_dpp v169, v29 row_ror:1 row_mask:0xf bank_mask:0xf
	v_mov_b32_dpp v170, v22 row_shr:1 row_mask:0xf bank_mask:0xf
	v_mov_b32_dpp v171, v23 row_shr:1 row_mask:0xf bank_mask:0xf
	v_pk_fma_f32 v[146:147], v[146:147], v[164:165], v[150:151]
	v_pk_fma_f32 v[144:145], v[22:23], v[144:145], v[148:149]
	v_mov_b32_dpp v168, v20 row_shr:1 row_mask:0xf bank_mask:0xf
	v_mov_b32_dpp v169, v21 row_shr:1 row_mask:0xf bank_mask:0xf
	v_pk_fma_f32 v[142:143], v[20:21], v[142:143], v[146:147]
	v_pk_fma_f32 v[136:137], v[136:137], v[170:171], v[144:145]
	v_pk_mul_f32 v[144:145], v[128:129], s[0:1] op_sel_hi:[1,0]
	v_pk_fma_f32 v[134:135], v[134:135], v[168:169], v[142:143]
	v_pk_mul_f32 v[142:143], v[138:139], s[0:1] op_sel_hi:[1,0]
	v_exp_f32_e32 v144, v144
	v_exp_f32_e32 v145, v145
	v_exp_f32_e32 v142, v142
	v_exp_f32_e32 v143, v143
	v_pk_mul_f32 v[128:129], v[128:129], v[134:135]
	v_pk_add_f32 v[144:145], v[144:145], 1.0 op_sel_hi:[1,0]
	v_pk_mul_f32 v[134:135], v[138:139], v[136:137]
	v_pk_add_f32 v[142:143], v[142:143], 1.0 op_sel_hi:[1,0]
	v_rcp_f32_e32 v144, v144
	v_rcp_f32_e32 v145, v145
	v_rcp_f32_e32 v142, v142
	v_rcp_f32_e32 v143, v143
	v_pk_mul_f32 v[128:129], v[144:145], v[128:129]
	s_nop 0
	v_cvt_pk_bf16_f32 v128, v128, v129
	v_pk_mul_f32 v[134:135], v[142:143], v[134:135]
	s_nop 1
	v_cvt_pk_bf16_f32 v129, v134, v135
	ds_read_b128 v[166:169], v154 offset:16
	ds_read_b128 v[136:139], v154 offset:528
	ds_read_b128 v[170:173], v154 offset:1040
	ds_read_b128 v[144:147], v154 offset:1552
	ds_read_b128 v[174:177], v154 offset:2064
	ds_read_b128 v[148:151], v154 offset:2576
	ds_read_b128 v[178:181], v154 offset:3088
	ds_read_b128 v[152:155], v154 offset:3600
	ds_read_b128 v[240:243], v237 offset:16
	s_nop 1
	v_mov_b32_dpp v134, v116 row_ror:15 row_mask:0xf bank_mask:0xf
	v_mov_b32_dpp v135, v117 row_ror:15 row_mask:0xf bank_mask:0xf
	s_waitcnt lgkmcnt(0)
; #define LAS __attribute__((address_space(3)))
;     __device__ __forceinline__ void operator()(const f32x4 (&acc)[2][2][4][2], const Unit& u, int wr, int wc, int fr_in, int fq_in) const {
;     ...
;             for (int ai = 0; ai < 2; ++ai) { const int Bk = 2 * ai + wr;
; #pragma unroll
;                 for (int m = 0; m < 4; ++m) {
;                     const int r = 128 * ai + 64 * wr + 16 * m + fr, tb = 254 * j + r - 1;
;                     f32x4 res[2];
; #pragma unroll
;                     for (int bj = 0; bj < 2; ++bj) {
;                         const f32x4 cur = acc[ai][bj][m][n];
;                         f32x4 pe, ne;
;                         if (m > 0) { const f32x4 q = acc[ai][bj][m > 0 ? m - 1 : 0][n]; pe = (f32x4){dpp_ror1(q[0]), dpp_ror1(q[1]), dpp_ror1(q[2]), dpp_ror1(q[3])}; }
;                         else pe = *(const LAS f32x4*)(X + (((Bk > 0 ? Bk - 1 : 0) * 2 + 1) * 2 + bj) * 128 + cl + 4 * n);
;                         if (m < 3) { const f32x4 q = acc[ai][bj][m < 3 ? m + 1 : 3][n]; ne = (f32x4){dpp_rol1(q[0]), dpp_rol1(q[1]), dpp_rol1(q[2]), dpp_rol1(q[3])}; }
;                         else ne = *(const LAS f32x4*)(X + (((Bk < 3 ? Bk + 1 : 3) * 2 + 0) * 2 + bj) * 128 + cl + 4 * n);
;                         f32x4 pvv, nvv;
; #pragma unroll
;                         for (int e = 0; e < 4; ++e) {
;                             float pv = __int_as_float(__builtin_amdgcn_update_dpp(__float_as_int(pe[e]), __float_as_int(cur[e]), 0x111, 0xf, 0xf, false));
;                             float nv = __int_as_float(__builtin_amdgcn_update_dpp(__float_as_int(ne[e]), __float_as_int(cur[e]), 0x101, 0xf, 0xf, false));
;                             if (ai == 0 && m == 0) pv = (tb == 0) ? 0.f : pv;
;                             if (ai == 0 && m == 2) nv = (tb == SEQ - 1) ? 0.f : nv;
;                             pvv[e] = pv; nvv[e] = nv; }
;                         res[bj] = pvv * wv[0][bj] + (cur * wv[1][bj] + (nvv * wv[2][bj] + wv[3][bj]));
;                     }
;                     f32x4 y;
;                     { const f32x4 G = res[0], t = G * -1.4426950408889634f;
;                       f32x4 den; den[0] = __builtin_amdgcn_exp2f(t[0]); den[1] = __builtin_amdgcn_exp2f(t[1]); den[2] = __builtin_amdgcn_exp2f(t[2]); den[3] = __builtin_amdgcn_exp2f(t[3]);
;                       den = den + 1.0f;
	v_mov_b32_dpp v240, v0 row_shr:1 row_mask:0xf bank_mask:0xf
	v_mov_b32_dpp v134, v0 row_shl:1 row_mask:0xf bank_mask:0xf
	v_mov_b32_dpp v135, v1 row_shl:1 row_mask:0xf bank_mask:0xf
	v_mov_b32_dpp v241, v1 row_shr:1 row_mask:0xf bank_mask:0xf
	v_pk_fma_f32 v[134:135], v[174:175], v[134:135], v[178:179]
	v_mov_b32_dpp v142, v118 row_ror:15 row_mask:0xf bank_mask:0xf
	v_mov_b32_dpp v143, v119 row_ror:15 row_mask:0xf bank_mask:0xf
	v_cndmask_b32_e64 v164, v240, 0, vcc
	v_cndmask_b32_e64 v165, v241, 0, vcc
	v_pk_fma_f32 v[134:135], v[0:1], v[170:171], v[134:135]
	v_mov_b32_dpp v142, v2 row_shl:1 row_mask:0xf bank_mask:0xf
	v_mov_b32_dpp v143, v3 row_shl:1 row_mask:0xf bank_mask:0xf
	v_pk_fma_f32 v[134:135], v[166:167], v[164:165], v[134:135]
	v_add_u32_e32 v164, 0xfffffe10, v238
	v_mov_b32_dpp v242, v2 row_shr:1 row_mask:0xf bank_mask:0xf
	v_mov_b32_dpp v243, v3 row_shr:1 row_mask:0xf bank_mask:0xf
	v_pk_fma_f32 v[142:143], v[176:177], v[142:143], v[180:181]
	ds_read_b128 v[238:241], v164
	v_cndmask_b32_e64 v212, v242, 0, vcc
	v_cndmask_b32_e64 v213, v243, 0, vcc
	v_pk_fma_f32 v[142:143], v[2:3], v[172:173], v[142:143]
	s_nop 1
	v_pk_fma_f32 v[142:143], v[168:169], v[212:213], v[142:143]
	s_nop 1
	s_waitcnt lgkmcnt(0)
	v_mov_b32_dpp v240, v98 row_shr:1 row_mask:0xf bank_mask:0xf
	v_mov_b32_dpp v212, v90 row_ror:15 row_mask:0xf bank_mask:0xf
	v_mov_b32_dpp v213, v91 row_ror:15 row_mask:0xf bank_mask:0xf
	v_mov_b32_dpp v241, v99 row_shr:1 row_mask:0xf bank_mask:0xf
	v_mov_b32_dpp v212, v98 row_shl:1 row_mask:0xf bank_mask:0xf
	v_mov_b32_dpp v213, v99 row_shl:1 row_mask:0xf bank_mask:0xf
	v_pk_fma_f32 v[212:213], v[150:151], v[212:213], v[154:155]
	s_nop 1
	v_cndmask_b32_e64 v218, v240, 0, vcc
	v_cndmask_b32_e64 v219, v241, 0, vcc
	v_pk_fma_f32 v[212:213], v[98:99], v[146:147], v[212:213]
	v_mov_b32_dpp v164, v88 row_ror:15 row_mask:0xf bank_mask:0xf
	v_mov_b32_dpp v165, v89 row_ror:15 row_mask:0xf bank_mask:0xf
	v_pk_fma_f32 v[212:213], v[138:139], v[218:219], v[212:213]
	v_pk_mul_f32 v[218:219], v[134:135], s[0:1] op_sel_hi:[1,0]
	v_mov_b32_dpp v164, v96 row_shl:1 row_mask:0xf bank_mask:0xf
	v_mov_b32_dpp v165, v97 row_shl:1 row_mask:0xf bank_mask:0xf
	v_exp_f32_e32 v218, v218
	v_exp_f32_e32 v219, v219
	v_mov_b32_dpp v238, v96 row_shr:1 row_mask:0xf bank_mask:0xf
	v_mov_b32_dpp v239, v97 row_shr:1 row_mask:0xf bank_mask:0xf
	v_pk_fma_f32 v[164:165], v[148:149], v[164:165], v[152:153]
	v_cndmask_b32_e64 v214, v238, 0, vcc
	v_cndmask_b32_e64 v215, v239, 0, vcc
	v_pk_fma_f32 v[164:165], v[96:97], v[144:145], v[164:165]
	v_pk_add_f32 v[218:219], v[218:219], 1.0 op_sel_hi:[1,0]
	v_pk_fma_f32 v[164:165], v[136:137], v[214:215], v[164:165]
	v_pk_mul_f32 v[214:215], v[142:143], s[0:1] op_sel_hi:[1,0]
	v_rcp_f32_e32 v218, v218
	v_exp_f32_e32 v214, v214
	v_exp_f32_e32 v215, v215
	v_rcp_f32_e32 v219, v219
	v_pk_mul_f32 v[134:135], v[134:135], v[164:165]
	s_movk_i32 s0, 0x1001
	v_pk_add_f32 v[214:215], v[214:215], 1.0 op_sel_hi:[1,0]
	v_pk_mul_f32 v[134:135], v[218:219], v[134:135]
	v_rcp_f32_e32 v214, v214
	v_rcp_f32_e32 v215, v215
	v_cvt_pk_bf16_f32 v164, v134, v135
	v_add_u32_e32 v134, -1, v229
	v_cmp_gt_u32_e32 vcc, s67, v134
	v_cmp_gt_i32_e64 s[0:1], s0, v182
	v_pk_mul_f32 v[142:143], v[142:143], v[212:213]
	s_and_b64 s[8:9], vcc, s[0:1]
	v_pk_mul_f32 v[142:143], v[214:215], v[142:143]
	s_nop 0
	v_cvt_pk_bf16_f32 v165, v142, v143
	s_and_saveexec_b64 s[0:1], s[8:9]
	s_cbranch_execz .LBB0_226
	s_movk_i32 s8, 0x1600
	v_mul_lo_u32 v182, v229, s8
	v_lshl_add_u64 v[134:135], v[182:183], 1, v[204:205]
	global_store_dwordx4 v[134:135], v[162:165], off
.LBB0_226:
	s_or_b64 exec, exec, s[0:1]
	s_nop 1
	v_mov_b32_dpp v212, v110 row_ror:15 row_mask:0xf bank_mask:0xf
	v_mov_b32_dpp v213, v111 row_ror:15 row_mask:0xf bank_mask:0xf
	s_nop 1
	v_mov_b32_dpp v164, v108 row_ror:15 row_mask:0xf bank_mask:0xf
	v_mov_b32_dpp v165, v109 row_ror:15 row_mask:0xf bank_mask:0xf
	v_mov_b32_dpp v212, v118 row_shl:1 row_mask:0xf bank_mask:0xf
	v_mov_b32_dpp v213, v119 row_shl:1 row_mask:0xf bank_mask:0xf
	s_nop 1
	v_mov_b32_dpp v162, v2 row_ror:1 row_mask:0xf bank_mask:0xf
	v_mov_b32_dpp v163, v3 row_ror:1 row_mask:0xf bank_mask:0xf
	v_mov_b32_dpp v164, v116 row_shl:1 row_mask:0xf bank_mask:0xf
	v_mov_b32_dpp v165, v117 row_shl:1 row_mask:0xf bank_mask:0xf
	v_pk_fma_f32 v[212:213], v[176:177], v[212:213], v[180:181]
	s_nop 1
	v_mov_b32_dpp v142, v0 row_ror:1 row_mask:0xf bank_mask:0xf
	v_mov_b32_dpp v143, v1 row_ror:1 row_mask:0xf bank_mask:0xf
	v_mov_b32_dpp v162, v118 row_shr:1 row_mask:0xf bank_mask:0xf
	v_mov_b32_dpp v163, v119 row_shr:1 row_mask:0xf bank_mask:0xf
	v_pk_fma_f32 v[164:165], v[174:175], v[164:165], v[178:179]
	v_pk_fma_f32 v[212:213], v[118:119], v[172:173], v[212:213]
	s_nop 1
	v_mov_b32_dpp v218, v82 row_ror:15 row_mask:0xf bank_mask:0xf
	v_mov_b32_dpp v219, v83 row_ror:15 row_mask:0xf bank_mask:0xf
	v_mov_b32_dpp v142, v116 row_shr:1 row_mask:0xf bank_mask:0xf
	v_mov_b32_dpp v143, v117 row_shr:1 row_mask:0xf bank_mask:0xf
	v_pk_fma_f32 v[164:165], v[116:117], v[170:171], v[164:165]
	v_pk_fma_f32 v[162:163], v[168:169], v[162:163], v[212:213]
	s_nop 1
	v_mov_b32_dpp v214, v80 row_ror:15 row_mask:0xf bank_mask:0xf
	v_mov_b32_dpp v215, v81 row_ror:15 row_mask:0xf bank_mask:0xf
	v_mov_b32_dpp v218, v90 row_shl:1 row_mask:0xf bank_mask:0xf
	v_mov_b32_dpp v219, v91 row_shl:1 row_mask:0xf bank_mask:0xf
	v_pk_fma_f32 v[142:143], v[166:167], v[142:143], v[164:165]
	s_nop 1
	v_mov_b32_dpp v212, v98 row_ror:1 row_mask:0xf bank_mask:0xf
	v_mov_b32_dpp v213, v99 row_ror:1 row_mask:0xf bank_mask:0xf
	v_mov_b32_dpp v214, v88 row_shl:1 row_mask:0xf bank_mask:0xf
; #define LAS __attribute__((address_space(3)))
;     __device__ __forceinline__ void operator()(const f32x4 (&acc)[2][2][4][2], const Unit& u, int wr, int wc, int fr_in, int fq_in) const {
;     ...
;             for (int ai = 0; ai < 2; ++ai) { const int Bk = 2 * ai + wr;
; #pragma unroll
;                 for (int m = 0; m < 4; ++m) {
;                     const int r = 128 * ai + 64 * wr + 16 * m + fr, tb = 254 * j + r - 1;
;                     f32x4 res[2];
; #pragma unroll
;                     for (int bj = 0; bj < 2; ++bj) {
;                         const f32x4 cur = acc[ai][bj][m][n];
;                         f32x4 pe, ne;
;                         if (m > 0) { const f32x4 q = acc[ai][bj][m > 0 ? m - 1 : 0][n]; pe = (f32x4){dpp_ror1(q[0]), dpp_ror1(q[1]), dpp_ror1(q[2]), dpp_ror1(q[3])}; }
;                         else pe = *(const LAS f32x4*)(X + (((Bk > 0 ? Bk - 1 : 0) * 2 + 1) * 2 + bj) * 128 + cl + 4 * n);
;                         if (m < 3) { const f32x4 q = acc[ai][bj][m < 3 ? m + 1 : 3][n]; ne = (f32x4){dpp_rol1(q[0]), dpp_rol1(q[1]), dpp_rol1(q[2]), dpp_rol1(q[3])}; }
;                         else ne = *(const LAS f32x4*)(X + (((Bk < 3 ? Bk + 1 : 3) * 2 + 0) * 2 + bj) * 128 + cl + 4 * n);
;                         f32x4 pvv, nvv;
; #pragma unroll
;                         for (int e = 0; e < 4; ++e) {
;                             float pv = __int_as_float(__builtin_amdgcn_update_dpp(__float_as_int(pe[e]), __float_as_int(cur[e]), 0x111, 0xf, 0xf, false));
;                             float nv = __int_as_float(__builtin_amdgcn_update_dpp(__float_as_int(ne[e]), __float_as_int(cur[e]), 0x101, 0xf, 0xf, false));
;                             if (ai == 0 && m == 0) pv = (tb == 0) ? 0.f : pv;
;                             if (ai == 0 && m == 2) nv = (tb == SEQ - 1) ? 0.f : nv;
;                             pvv[e] = pv; nvv[e] = nv; }
;                         res[bj] = pvv * wv[0][bj] + (cur * wv[1][bj] + (nvv * wv[2][bj] + wv[3][bj]));
;                     }
;                     f32x4 y;
;                     { const f32x4 G = res[0], t = G * -1.4426950408889634f;
;                       f32x4 den; den[0] = __builtin_amdgcn_exp2f(t[0]); den[1] = __builtin_amdgcn_exp2f(t[1]); den[2] = __builtin_amdgcn_exp2f(t[2]); den[3] = __builtin_amdgcn_exp2f(t[3]);
;                       den = den + 1.0f;
	v_mov_b32_dpp v215, v89 row_shl:1 row_mask:0xf bank_mask:0xf
	v_pk_fma_f32 v[218:219], v[150:151], v[218:219], v[154:155]
	v_mov_b32_dpp v164, v96 row_ror:1 row_mask:0xf bank_mask:0xf
	v_mov_b32_dpp v165, v97 row_ror:1 row_mask:0xf bank_mask:0xf
	v_mov_b32_dpp v212, v90 row_shr:1 row_mask:0xf bank_mask:0xf
	v_mov_b32_dpp v213, v91 row_shr:1 row_mask:0xf bank_mask:0xf
	v_pk_fma_f32 v[214:215], v[148:149], v[214:215], v[152:153]
	v_pk_fma_f32 v[218:219], v[90:91], v[146:147], v[218:219]
	s_mov_b32 s0, 0xbfb8aa3b
	v_mov_b32_dpp v164, v88 row_shr:1 row_mask:0xf bank_mask:0xf
	v_mov_b32_dpp v165, v89 row_shr:1 row_mask:0xf bank_mask:0xf
	v_pk_fma_f32 v[214:215], v[88:89], v[144:145], v[214:215]
	v_pk_fma_f32 v[212:213], v[138:139], v[212:213], v[218:219]
	v_pk_mul_f32 v[218:219], v[142:143], s[0:1] op_sel_hi:[1,0]
	v_pk_fma_f32 v[164:165], v[136:137], v[164:165], v[214:215]
	v_pk_mul_f32 v[214:215], v[162:163], s[0:1] op_sel_hi:[1,0]
	v_exp_f32_e32 v218, v218
	v_exp_f32_e32 v219, v219
	v_exp_f32_e32 v214, v214
	v_exp_f32_e32 v215, v215
	v_pk_mul_f32 v[142:143], v[142:143], v[164:165]
	v_pk_add_f32 v[218:219], v[218:219], 1.0 op_sel_hi:[1,0]
	v_add_u32_e32 v134, 16, v229
	v_pk_add_f32 v[214:215], v[214:215], 1.0 op_sel_hi:[1,0]
	v_rcp_f32_e32 v218, v218
	v_rcp_f32_e32 v219, v219
	v_rcp_f32_e32 v214, v214
	v_rcp_f32_e32 v215, v215
	v_pk_mul_f32 v[162:163], v[162:163], v[212:213]
	v_pk_mul_f32 v[142:143], v[218:219], v[142:143]
	v_add_u32_e32 v135, v134, v230
	v_pk_mul_f32 v[164:165], v[214:215], v[162:163]
	v_cvt_pk_bf16_f32 v162, v142, v143
	v_add_u32_e32 v142, 15, v229
	s_movk_i32 s0, 0x1001
	v_cmp_gt_u32_e32 vcc, s67, v142
	v_cmp_gt_i32_e64 s[0:1], s0, v135
	s_and_b64 s[8:9], vcc, s[0:1]
	v_cvt_pk_bf16_f32 v163, v164, v165
	s_and_saveexec_b64 s[0:1], s[8:9]
	s_cbranch_execz .LBB0_228
	s_movk_i32 s8, 0x1600
	v_mul_lo_u32 v182, v134, s8
	v_lshl_add_u64 v[134:135], v[182:183], 1, v[204:205]
	global_store_dwordx4 v[134:135], v[160:163], off
.LBB0_228:
	s_or_b64 exec, exec, s[0:1]
	s_nop 0
	s_nop 1
	v_mov_b32_dpp v162, v6 row_ror:15 row_mask:0xf bank_mask:0xf
	v_mov_b32_dpp v163, v7 row_ror:15 row_mask:0xf bank_mask:0xf
	s_nop 1
	v_mov_b32_dpp v162, v110 row_shl:1 row_mask:0xf bank_mask:0xf
	v_mov_b32_dpp v163, v111 row_shl:1 row_mask:0xf bank_mask:0xf
	s_nop 1
	v_mov_b32_dpp v160, v4 row_ror:15 row_mask:0xf bank_mask:0xf
	v_mov_b32_dpp v161, v5 row_ror:15 row_mask:0xf bank_mask:0xf
	v_cndmask_b32_e64 v162, v162, 0, s[38:39]
	v_cndmask_b32_e64 v163, v163, 0, s[38:39]
	s_nop 1
	v_mov_b32_dpp v142, v118 row_ror:1 row_mask:0xf bank_mask:0xf
	v_mov_b32_dpp v143, v119 row_ror:1 row_mask:0xf bank_mask:0xf
	v_mov_b32_dpp v160, v108 row_shl:1 row_mask:0xf bank_mask:0xf
	v_mov_b32_dpp v161, v109 row_shl:1 row_mask:0xf bank_mask:0xf
	v_pk_fma_f32 v[162:163], v[176:177], v[162:163], v[180:181]
	v_mov_b32_dpp v182, v74 row_ror:15 row_mask:0xf bank_mask:0xf
	v_mov_b32_dpp v213, v75 row_ror:15 row_mask:0xf bank_mask:0xf
	s_nop 1
	v_cndmask_b32_e64 v160, v160, 0, s[38:39]
	v_cndmask_b32_e64 v161, v161, 0, s[38:39]
	v_mov_b32_dpp v142, v110 row_shr:1 row_mask:0xf bank_mask:0xf
	v_mov_b32_dpp v143, v111 row_shr:1 row_mask:0xf bank_mask:0xf
	v_pk_fma_f32 v[162:163], v[110:111], v[172:173], v[162:163]
	v_mov_b32_dpp v182, v82 row_shl:1 row_mask:0xf bank_mask:0xf
	v_mov_b32_dpp v213, v83 row_shl:1 row_mask:0xf bank_mask:0xf
	v_mov_b32_dpp v134, v116 row_ror:1 row_mask:0xf bank_mask:0xf
	v_mov_b32_dpp v135, v117 row_ror:1 row_mask:0xf bank_mask:0xf
	v_pk_fma_f32 v[160:161], v[174:175], v[160:161], v[178:179]
	v_pk_fma_f32 v[142:143], v[168:169], v[142:143], v[162:163]
	s_nop 1
	v_cndmask_b32_e64 v212, v182, 0, s[38:39]
	v_cndmask_b32_e64 v213, v213, 0, s[38:39]
	v_mov_b32_dpp v134, v108 row_shr:1 row_mask:0xf bank_mask:0xf
	v_mov_b32_dpp v135, v109 row_shr:1 row_mask:0xf bank_mask:0xf
	v_pk_fma_f32 v[160:161], v[108:109], v[170:171], v[160:161]
	v_mov_b32_dpp v162, v90 row_ror:1 row_mask:0xf bank_mask:0xf
	v_mov_b32_dpp v163, v91 row_ror:1 row_mask:0xf bank_mask:0xf
	s_nop 1
	v_pk_fma_f32 v[212:213], v[150:151], v[212:213], v[154:155]
	v_pk_fma_f32 v[134:135], v[166:167], v[134:135], v[160:161]
	v_mov_b32_dpp v164, v72 row_ror:15 row_mask:0xf bank_mask:0xf
	v_mov_b32_dpp v165, v73 row_ror:15 row_mask:0xf bank_mask:0xf
	v_mov_b32_dpp v162, v82 row_shr:1 row_mask:0xf bank_mask:0xf
	v_mov_b32_dpp v163, v83 row_shr:1 row_mask:0xf bank_mask:0xf
	v_pk_fma_f32 v[212:213], v[82:83], v[146:147], v[212:213]
	s_mov_b32 s0, 0xbfb8aa3b
	v_mov_b32_dpp v164, v80 row_shl:1 row_mask:0xf bank_mask:0xf
	v_mov_b32_dpp v165, v81 row_shl:1 row_mask:0xf bank_mask:0xf
	v_pk_fma_f32 v[162:163], v[138:139], v[162:163], v[212:213]
	v_pk_mul_f32 v[212:213], v[134:135], s[0:1] op_sel_hi:[1,0]
	s_nop 1
	v_cndmask_b32_e64 v164, v164, 0, s[38:39]
	v_cndmask_b32_e64 v165, v165, 0, s[38:39]
	v_exp_f32_e32 v212, v212
	v_exp_f32_e32 v213, v213
	v_mov_b32_dpp v160, v88 row_ror:1 row_mask:0xf bank_mask:0xf
	v_mov_b32_dpp v161, v89 row_ror:1 row_mask:0xf bank_mask:0xf
	v_pk_fma_f32 v[164:165], v[148:149], v[164:165], v[152:153]
	v_mov_b32_dpp v160, v80 row_shr:1 row_mask:0xf bank_mask:0xf
	v_mov_b32_dpp v161, v81 row_shr:1 row_mask:0xf bank_mask:0xf
	v_pk_fma_f32 v[164:165], v[80:81], v[144:145], v[164:165]
	v_pk_add_f32 v[212:213], v[212:213], 1.0 op_sel_hi:[1,0]
	v_pk_fma_f32 v[160:161], v[136:137], v[160:161], v[164:165]
	v_pk_mul_f32 v[164:165], v[142:143], s[0:1] op_sel_hi:[1,0]
	v_rcp_f32_e32 v212, v212
	v_exp_f32_e32 v164, v164
	v_exp_f32_e32 v165, v165
	v_rcp_f32_e32 v213, v213
	v_pk_mul_f32 v[134:135], v[134:135], v[160:161]
	s_movk_i32 s0, 0x1001
	v_pk_add_f32 v[164:165], v[164:165], 1.0 op_sel_hi:[1,0]
	v_pk_mul_f32 v[134:135], v[212:213], v[134:135]
	v_rcp_f32_e32 v164, v164
	v_rcp_f32_e32 v165, v165
	v_cvt_pk_bf16_f32 v160, v134, v135
	v_add_u32_e32 v134, 31, v229
	v_cmp_gt_u32_e32 vcc, s67, v134
	v_cmp_gt_i32_e64 s[0:1], s0, v233
	v_pk_mul_f32 v[142:143], v[142:143], v[162:163]
	s_and_b64 s[8:9], vcc, s[0:1]
	v_pk_mul_f32 v[142:143], v[164:165], v[142:143]
	s_nop 0
	v_cvt_pk_bf16_f32 v161, v142, v143
	s_and_saveexec_b64 s[0:1], s[8:9]
	s_cbranch_execz .LBB0_230
	s_movk_i32 s8, 0x1600
	v_mul_lo_u32 v182, v232, s8
	v_lshl_add_u64 v[134:135], v[182:183], 1, v[204:205]
	global_store_dwordx4 v[134:135], v[158:161], off
; #define LAS __attribute__((address_space(3)))
;     __device__ __forceinline__ void operator()(const f32x4 (&acc)[2][2][4][2], const Unit& u, int wr, int wc, int fr_in, int fq_in) const {
;     ...
;             for (int ai = 0; ai < 2; ++ai) { const int Bk = 2 * ai + wr;
; #pragma unroll
;                 for (int m = 0; m < 4; ++m) {
;                     const int r = 128 * ai + 64 * wr + 16 * m + fr, tb = 254 * j + r - 1;
;                     f32x4 res[2];
; #pragma unroll
;                     for (int bj = 0; bj < 2; ++bj) {
;                         const f32x4 cur = acc[ai][bj][m][n];
;                         f32x4 pe, ne;
;                         if (m > 0) { const f32x4 q = acc[ai][bj][m > 0 ? m - 1 : 0][n]; pe = (f32x4){dpp_ror1(q[0]), dpp_ror1(q[1]), dpp_ror1(q[2]), dpp_ror1(q[3])}; }
;                         else pe = *(const LAS f32x4*)(X + (((Bk > 0 ? Bk - 1 : 0) * 2 + 1) * 2 + bj) * 128 + cl + 4 * n);
;                         if (m < 3) { const f32x4 q = acc[ai][bj][m < 3 ? m + 1 : 3][n]; ne = (f32x4){dpp_rol1(q[0]), dpp_rol1(q[1]), dpp_rol1(q[2]), dpp_rol1(q[3])}; }
;                         else ne = *(const LAS f32x4*)(X + (((Bk < 3 ? Bk + 1 : 3) * 2 + 0) * 2 + bj) * 128 + cl + 4 * n);
;                         f32x4 pvv, nvv;
; #pragma unroll
;                         for (int e = 0; e < 4; ++e) {
;                             float pv = __int_as_float(__builtin_amdgcn_update_dpp(__float_as_int(pe[e]), __float_as_int(cur[e]), 0x111, 0xf, 0xf, false));
;                             float nv = __int_as_float(__builtin_amdgcn_update_dpp(__float_as_int(ne[e]), __float_as_int(cur[e]), 0x101, 0xf, 0xf, false));
;                             if (ai == 0 && m == 0) pv = (tb == 0) ? 0.f : pv;
;                             if (ai == 0 && m == 2) nv = (tb == SEQ - 1) ? 0.f : nv;
;                             pvv[e] = pv; nvv[e] = nv; }
;                         res[bj] = pvv * wv[0][bj] + (cur * wv[1][bj] + (nvv * wv[2][bj] + wv[3][bj]));
;                     }
;                     f32x4 y;
;                     { const f32x4 G = res[0], t = G * -1.4426950408889634f;
;                       f32x4 den; den[0] = __builtin_amdgcn_exp2f(t[0]); den[1] = __builtin_amdgcn_exp2f(t[1]); den[2] = __builtin_amdgcn_exp2f(t[2]); den[3] = __builtin_amdgcn_exp2f(t[3]);
;                       den = den + 1.0f;
.LBB0_230:
	s_or_b64 exec, exec, s[0:1]
	ds_read_b128 v[158:161], v234 offset:2064
	s_nop 1
	s_waitcnt lgkmcnt(0)
	v_mov_b32_dpp v158, v4 row_shl:1 row_mask:0xf bank_mask:0xf
	v_mov_b32_dpp v159, v5 row_shl:1 row_mask:0xf bank_mask:0xf
	v_mov_b32_dpp v160, v6 row_shl:1 row_mask:0xf bank_mask:0xf
	v_mov_b32_dpp v161, v7 row_shl:1 row_mask:0xf bank_mask:0xf
	v_mov_b32_dpp v142, v108 row_ror:1 row_mask:0xf bank_mask:0xf
	v_mov_b32_dpp v143, v109 row_ror:1 row_mask:0xf bank_mask:0xf
	v_mov_b32_dpp v162, v110 row_ror:1 row_mask:0xf bank_mask:0xf
	v_mov_b32_dpp v163, v111 row_ror:1 row_mask:0xf bank_mask:0xf
	v_pk_fma_f32 v[158:159], v[174:175], v[158:159], v[178:179]
	v_pk_fma_f32 v[160:161], v[176:177], v[160:161], v[180:181]
	v_mov_b32_dpp v142, v4 row_shr:1 row_mask:0xf bank_mask:0xf
	v_mov_b32_dpp v143, v5 row_shr:1 row_mask:0xf bank_mask:0xf
	v_mov_b32_dpp v162, v6 row_shr:1 row_mask:0xf bank_mask:0xf
	v_mov_b32_dpp v163, v7 row_shr:1 row_mask:0xf bank_mask:0xf
	v_pk_fma_f32 v[160:161], v[6:7], v[172:173], v[160:161]
	v_pk_fma_f32 v[158:159], v[4:5], v[170:171], v[158:159]
	v_pk_fma_f32 v[162:163], v[168:169], v[162:163], v[160:161]
	v_pk_fma_f32 v[142:143], v[166:167], v[142:143], v[158:159]
	ds_read_b128 v[158:161], v234 offset:2576
	s_nop 1
	s_waitcnt lgkmcnt(0)
	v_mov_b32_dpp v160, v74 row_shl:1 row_mask:0xf bank_mask:0xf
	v_mov_b32_dpp v161, v75 row_shl:1 row_mask:0xf bank_mask:0xf
	v_mov_b32_dpp v212, v82 row_ror:1 row_mask:0xf bank_mask:0xf
	v_mov_b32_dpp v213, v83 row_ror:1 row_mask:0xf bank_mask:0xf
	v_mov_b32_dpp v158, v72 row_shl:1 row_mask:0xf bank_mask:0xf
	v_mov_b32_dpp v159, v73 row_shl:1 row_mask:0xf bank_mask:0xf
	v_pk_fma_f32 v[160:161], v[150:151], v[160:161], v[154:155]
	v_mov_b32_dpp v164, v80 row_ror:1 row_mask:0xf bank_mask:0xf
	v_mov_b32_dpp v165, v81 row_ror:1 row_mask:0xf bank_mask:0xf
	v_mov_b32_dpp v212, v74 row_shr:1 row_mask:0xf bank_mask:0xf
	v_mov_b32_dpp v213, v75 row_shr:1 row_mask:0xf bank_mask:0xf
	v_pk_fma_f32 v[158:159], v[148:149], v[158:159], v[152:153]
	v_pk_fma_f32 v[160:161], v[74:75], v[146:147], v[160:161]
	s_mov_b32 s0, 0xbfb8aa3b
	v_mov_b32_dpp v164, v72 row_shr:1 row_mask:0xf bank_mask:0xf
	v_mov_b32_dpp v165, v73 row_shr:1 row_mask:0xf bank_mask:0xf
	v_pk_fma_f32 v[158:159], v[72:73], v[144:145], v[158:159]
	v_pk_fma_f32 v[160:161], v[138:139], v[212:213], v[160:161]
	v_pk_mul_f32 v[212:213], v[142:143], s[0:1] op_sel_hi:[1,0]
	v_pk_fma_f32 v[158:159], v[136:137], v[164:165], v[158:159]
	v_pk_mul_f32 v[164:165], v[162:163], s[0:1] op_sel_hi:[1,0]
	v_exp_f32_e32 v212, v212
	v_exp_f32_e32 v213, v213
	v_exp_f32_e32 v164, v164
	v_exp_f32_e32 v165, v165
	v_pk_mul_f32 v[142:143], v[142:143], v[158:159]
	v_pk_add_f32 v[212:213], v[212:213], 1.0 op_sel_hi:[1,0]
	v_add_u32_e32 v134, 48, v229
	v_pk_add_f32 v[164:165], v[164:165], 1.0 op_sel_hi:[1,0]
	v_rcp_f32_e32 v212, v212
	v_rcp_f32_e32 v213, v213
	v_rcp_f32_e32 v164, v164
	v_rcp_f32_e32 v165, v165
	v_pk_mul_f32 v[158:159], v[162:163], v[160:161]
	v_pk_mul_f32 v[142:143], v[212:213], v[142:143]
	v_add_u32_e32 v135, v134, v230
	v_pk_mul_f32 v[160:161], v[164:165], v[158:159]
	v_cvt_pk_bf16_f32 v158, v142, v143
	v_add_u32_e32 v142, 47, v229
	s_movk_i32 s0, 0x1001
	v_cmp_gt_u32_e32 vcc, s67, v142
	v_cmp_gt_i32_e64 s[0:1], s0, v135
	s_and_b64 s[8:9], vcc, s[0:1]
	v_cvt_pk_bf16_f32 v159, v160, v161
	s_and_saveexec_b64 s[0:1], s[8:9]
	s_cbranch_execz .LBB0_232
	s_movk_i32 s8, 0x1600
	v_mul_lo_u32 v182, v134, s8
	v_lshl_add_u64 v[134:135], v[182:183], 1, v[204:205]
	global_store_dwordx4 v[134:135], v[156:159], off
.LBB0_232:
	s_or_b64 exec, exec, s[0:1]
	ds_read_b128 v[156:159], v236 offset:16
	s_nop 1
	v_mov_b32_dpp v142, v60 row_ror:15 row_mask:0xf bank_mask:0xf
	v_mov_b32_dpp v143, v61 row_ror:15 row_mask:0xf bank_mask:0xf
	s_nop 1
	v_mov_b32_dpp v160, v62 row_ror:15 row_mask:0xf bank_mask:0xf
	v_mov_b32_dpp v142, v8 row_shl:1 row_mask:0xf bank_mask:0xf
	v_mov_b32_dpp v161, v63 row_ror:15 row_mask:0xf bank_mask:0xf
	v_mov_b32_dpp v143, v9 row_shl:1 row_mask:0xf bank_mask:0xf
	v_mov_b32_dpp v160, v10 row_shl:1 row_mask:0xf bank_mask:0xf
	v_mov_b32_dpp v161, v11 row_shl:1 row_mask:0xf bank_mask:0xf
	v_pk_fma_f32 v[142:143], v[174:175], v[142:143], v[178:179]
	s_waitcnt lgkmcnt(0)
	v_mov_b32_dpp v156, v8 row_shr:1 row_mask:0xf bank_mask:0xf
	v_mov_b32_dpp v157, v9 row_shr:1 row_mask:0xf bank_mask:0xf
	v_pk_fma_f32 v[160:161], v[176:177], v[160:161], v[180:181]
	v_pk_fma_f32 v[142:143], v[8:9], v[170:171], v[142:143]
	v_mov_b32_dpp v158, v10 row_shr:1 row_mask:0xf bank_mask:0xf
	v_mov_b32_dpp v159, v11 row_shr:1 row_mask:0xf bank_mask:0xf
	v_pk_fma_f32 v[160:161], v[10:11], v[172:173], v[160:161]
	v_pk_fma_f32 v[142:143], v[166:167], v[156:157], v[142:143]
	v_add_u32_e32 v156, 0xfffffe10, v235
	v_pk_fma_f32 v[160:161], v[168:169], v[158:159], v[160:161]
	ds_read_b128 v[156:159], v156
	s_nop 1
	v_mov_b32_dpp v162, v32 row_ror:15 row_mask:0xf bank_mask:0xf
	v_mov_b32_dpp v163, v33 row_ror:15 row_mask:0xf bank_mask:0xf
	v_mov_b32_dpp v164, v34 row_ror:15 row_mask:0xf bank_mask:0xf
	v_mov_b32_dpp v165, v35 row_ror:15 row_mask:0xf bank_mask:0xf
	v_mov_b32_dpp v162, v40 row_shl:1 row_mask:0xf bank_mask:0xf
	v_mov_b32_dpp v163, v41 row_shl:1 row_mask:0xf bank_mask:0xf
	v_mov_b32_dpp v164, v42 row_shl:1 row_mask:0xf bank_mask:0xf
	v_mov_b32_dpp v165, v43 row_shl:1 row_mask:0xf bank_mask:0xf
	v_pk_fma_f32 v[164:165], v[150:151], v[164:165], v[154:155]
	v_pk_fma_f32 v[162:163], v[148:149], v[162:163], v[152:153]
	s_waitcnt lgkmcnt(0)
	v_mov_b32_dpp v156, v40 row_shr:1 row_mask:0xf bank_mask:0xf
	v_mov_b32_dpp v157, v41 row_shr:1 row_mask:0xf bank_mask:0xf
	v_mov_b32_dpp v158, v42 row_shr:1 row_mask:0xf bank_mask:0xf
	v_mov_b32_dpp v159, v43 row_shr:1 row_mask:0xf bank_mask:0xf
	v_pk_fma_f32 v[162:163], v[40:41], v[144:145], v[162:163]
	v_pk_fma_f32 v[164:165], v[42:43], v[146:147], v[164:165]
	s_mov_b32 s0, 0xbfb8aa3b
	v_pk_fma_f32 v[158:159], v[138:139], v[158:159], v[164:165]
	v_pk_fma_f32 v[156:157], v[136:137], v[156:157], v[162:163]
	v_pk_mul_f32 v[162:163], v[160:161], s[0:1] op_sel_hi:[1,0]
	v_pk_mul_f32 v[164:165], v[142:143], s[0:1] op_sel_hi:[1,0]
	v_exp_f32_e32 v162, v162
	v_exp_f32_e32 v164, v164
	v_exp_f32_e32 v165, v165
	v_exp_f32_e32 v163, v163
	v_pk_mul_f32 v[142:143], v[142:143], v[156:157]
	v_pk_mul_f32 v[156:157], v[160:161], v[158:159]
	v_pk_add_f32 v[164:165], v[164:165], 1.0 op_sel_hi:[1,0]
	v_pk_add_f32 v[162:163], v[162:163], 1.0 op_sel_hi:[1,0]
	v_rcp_f32_e32 v164, v164
	v_rcp_f32_e32 v165, v165
	v_rcp_f32_e32 v162, v162
	v_rcp_f32_e32 v163, v163
	v_add_u32_e32 v134, 0x80, v229
	v_pk_mul_f32 v[142:143], v[164:165], v[142:143]
	v_add_u32_e32 v135, v134, v230
	v_pk_mul_f32 v[156:157], v[162:163], v[156:157]
	v_cvt_pk_bf16_f32 v142, v142, v143
	s_movk_i32 s0, 0x1001
	v_cvt_pk_bf16_f32 v143, v156, v157
	v_add_u32_e32 v156, 0x7f, v229
	v_cmp_gt_u32_e32 vcc, s67, v156
	v_cmp_gt_i32_e64 s[0:1], s0, v135
	s_and_b64 s[8:9], vcc, s[0:1]
	s_and_saveexec_b64 s[0:1], s[8:9]
	s_cbranch_execz .LBB0_234
; #define LAS __attribute__((address_space(3)))
;     __device__ __forceinline__ void operator()(const f32x4 (&acc)[2][2][4][2], const Unit& u, int wr, int wc, int fr_in, int fq_in) const {
;     ...
;             for (int ai = 0; ai < 2; ++ai) { const int Bk = 2 * ai + wr;
; #pragma unroll
;                 for (int m = 0; m < 4; ++m) {
;                     const int r = 128 * ai + 64 * wr + 16 * m + fr, tb = 254 * j + r - 1;
;                     f32x4 res[2];
; #pragma unroll
;                     for (int bj = 0; bj < 2; ++bj) {
;                         const f32x4 cur = acc[ai][bj][m][n];
;                         f32x4 pe, ne;
;                         if (m > 0) { const f32x4 q = acc[ai][bj][m > 0 ? m - 1 : 0][n]; pe = (f32x4){dpp_ror1(q[0]), dpp_ror1(q[1]), dpp_ror1(q[2]), dpp_ror1(q[3])}; }
;                         else pe = *(const LAS f32x4*)(X + (((Bk > 0 ? Bk - 1 : 0) * 2 + 1) * 2 + bj) * 128 + cl + 4 * n);
;                         if (m < 3) { const f32x4 q = acc[ai][bj][m < 3 ? m + 1 : 3][n]; ne = (f32x4){dpp_rol1(q[0]), dpp_rol1(q[1]), dpp_rol1(q[2]), dpp_rol1(q[3])}; }
;                         else ne = *(const LAS f32x4*)(X + (((Bk < 3 ? Bk + 1 : 3) * 2 + 0) * 2 + bj) * 128 + cl + 4 * n);
;                         f32x4 pvv, nvv;
; #pragma unroll
;                         for (int e = 0; e < 4; ++e) {
;                             float pv = __int_as_float(__builtin_amdgcn_update_dpp(__float_as_int(pe[e]), __float_as_int(cur[e]), 0x111, 0xf, 0xf, false));
;                             float nv = __int_as_float(__builtin_amdgcn_update_dpp(__float_as_int(ne[e]), __float_as_int(cur[e]), 0x101, 0xf, 0xf, false));
;                             if (ai == 0 && m == 0) pv = (tb == 0) ? 0.f : pv;
;                             if (ai == 0 && m == 2) nv = (tb == SEQ - 1) ? 0.f : nv;
;                             pvv[e] = pv; nvv[e] = nv; }
;                         res[bj] = pvv * wv[0][bj] + (cur * wv[1][bj] + (nvv * wv[2][bj] + wv[3][bj]));
;                     }
;                     f32x4 y;
;                     { const f32x4 G = res[0], t = G * -1.4426950408889634f;
;                       f32x4 den; den[0] = __builtin_amdgcn_exp2f(t[0]); den[1] = __builtin_amdgcn_exp2f(t[1]); den[2] = __builtin_amdgcn_exp2f(t[2]); den[3] = __builtin_amdgcn_exp2f(t[3]);
;                       den = den + 1.0f;
	s_movk_i32 s8, 0x1600
	v_mul_lo_u32 v182, v134, s8
	v_lshl_add_u64 v[134:135], v[182:183], 1, v[204:205]
	global_store_dwordx4 v[134:135], v[140:143], off
.LBB0_234:
	s_or_b64 exec, exec, s[0:1]
	s_nop 1
	v_mov_b32_dpp v156, v52 row_ror:15 row_mask:0xf bank_mask:0xf
	v_mov_b32_dpp v157, v53 row_ror:15 row_mask:0xf bank_mask:0xf
	v_mov_b32_dpp v158, v54 row_ror:15 row_mask:0xf bank_mask:0xf
	v_mov_b32_dpp v159, v55 row_ror:15 row_mask:0xf bank_mask:0xf
	s_nop 1
	v_mov_b32_dpp v156, v60 row_shl:1 row_mask:0xf bank_mask:0xf
	v_mov_b32_dpp v157, v61 row_shl:1 row_mask:0xf bank_mask:0xf
	v_mov_b32_dpp v158, v62 row_shl:1 row_mask:0xf bank_mask:0xf
	v_mov_b32_dpp v159, v63 row_shl:1 row_mask:0xf bank_mask:0xf
	v_mov_b32_dpp v134, v8 row_ror:1 row_mask:0xf bank_mask:0xf
	v_mov_b32_dpp v135, v9 row_ror:1 row_mask:0xf bank_mask:0xf
	v_mov_b32_dpp v142, v10 row_ror:1 row_mask:0xf bank_mask:0xf
	v_mov_b32_dpp v143, v11 row_ror:1 row_mask:0xf bank_mask:0xf
	v_pk_fma_f32 v[156:157], v[174:175], v[156:157], v[178:179]
	v_pk_fma_f32 v[158:159], v[176:177], v[158:159], v[180:181]
	s_nop 1
	v_mov_b32_dpp v134, v60 row_shr:1 row_mask:0xf bank_mask:0xf
	v_mov_b32_dpp v135, v61 row_shr:1 row_mask:0xf bank_mask:0xf
	v_mov_b32_dpp v142, v62 row_shr:1 row_mask:0xf bank_mask:0xf
	v_mov_b32_dpp v143, v63 row_shr:1 row_mask:0xf bank_mask:0xf
	v_pk_fma_f32 v[158:159], v[62:63], v[172:173], v[158:159]
	v_pk_fma_f32 v[156:157], v[60:61], v[170:171], v[156:157]
	v_mov_b32_dpp v160, v24 row_ror:15 row_mask:0xf bank_mask:0xf
	v_mov_b32_dpp v161, v25 row_ror:15 row_mask:0xf bank_mask:0xf
	v_mov_b32_dpp v162, v26 row_ror:15 row_mask:0xf bank_mask:0xf
	v_mov_b32_dpp v163, v27 row_ror:15 row_mask:0xf bank_mask:0xf
	v_pk_fma_f32 v[134:135], v[166:167], v[134:135], v[156:157]
	v_pk_fma_f32 v[142:143], v[168:169], v[142:143], v[158:159]
	s_nop 1
	v_mov_b32_dpp v160, v32 row_shl:1 row_mask:0xf bank_mask:0xf
	v_mov_b32_dpp v161, v33 row_shl:1 row_mask:0xf bank_mask:0xf
	v_mov_b32_dpp v162, v34 row_shl:1 row_mask:0xf bank_mask:0xf
	v_mov_b32_dpp v163, v35 row_shl:1 row_mask:0xf bank_mask:0xf
	v_mov_b32_dpp v156, v40 row_ror:1 row_mask:0xf bank_mask:0xf
	v_mov_b32_dpp v157, v41 row_ror:1 row_mask:0xf bank_mask:0xf
	v_mov_b32_dpp v158, v42 row_ror:1 row_mask:0xf bank_mask:0xf
	v_mov_b32_dpp v159, v43 row_ror:1 row_mask:0xf bank_mask:0xf
	v_pk_fma_f32 v[162:163], v[150:151], v[162:163], v[154:155]
	v_pk_fma_f32 v[160:161], v[148:149], v[160:161], v[152:153]
	v_mov_b32_dpp v156, v32 row_shr:1 row_mask:0xf bank_mask:0xf
	v_mov_b32_dpp v157, v33 row_shr:1 row_mask:0xf bank_mask:0xf
	v_mov_b32_dpp v158, v34 row_shr:1 row_mask:0xf bank_mask:0xf
	v_mov_b32_dpp v159, v35 row_shr:1 row_mask:0xf bank_mask:0xf
	v_pk_fma_f32 v[160:161], v[32:33], v[144:145], v[160:161]
	v_pk_fma_f32 v[162:163], v[34:35], v[146:147], v[162:163]
	s_mov_b32 s0, 0xbfb8aa3b
	v_pk_fma_f32 v[158:159], v[138:139], v[158:159], v[162:163]
	v_pk_fma_f32 v[156:157], v[136:137], v[156:157], v[160:161]
	v_pk_mul_f32 v[160:161], v[142:143], s[0:1] op_sel_hi:[1,0]
	v_pk_mul_f32 v[162:163], v[134:135], s[0:1] op_sel_hi:[1,0]
	v_exp_f32_e32 v160, v160
	v_exp_f32_e32 v162, v162
	v_exp_f32_e32 v163, v163
	v_exp_f32_e32 v161, v161
	v_pk_mul_f32 v[134:135], v[134:135], v[156:157]
	v_pk_mul_f32 v[142:143], v[142:143], v[158:159]
	v_pk_add_f32 v[162:163], v[162:163], 1.0 op_sel_hi:[1,0]
	v_pk_add_f32 v[160:161], v[160:161], 1.0 op_sel_hi:[1,0]
	v_rcp_f32_e32 v162, v162
	v_rcp_f32_e32 v163, v163
	v_rcp_f32_e32 v160, v160
	v_rcp_f32_e32 v161, v161
	v_add_u32_e32 v140, 0x90, v229
	v_pk_mul_f32 v[134:135], v[162:163], v[134:135]
	v_add_u32_e32 v141, v140, v230
	v_pk_mul_f32 v[142:143], v[160:161], v[142:143]
	v_cvt_pk_bf16_f32 v134, v134, v135
	s_movk_i32 s0, 0x1001
	v_cvt_pk_bf16_f32 v135, v142, v143
	v_add_u32_e32 v142, 0x8f, v229
	v_cmp_gt_u32_e32 vcc, s67, v142
	v_cmp_gt_i32_e64 s[0:1], s0, v141
	s_and_b64 s[8:9], vcc, s[0:1]
	s_and_saveexec_b64 s[0:1], s[8:9]
	s_cbranch_execz .LBB0_236
	s_movk_i32 s8, 0x1600
	v_mul_lo_u32 v182, v140, s8
	v_lshl_add_u64 v[140:141], v[182:183], 1, v[204:205]
	global_store_dwordx4 v[140:141], v[132:135], off
.LBB0_236:
	s_or_b64 exec, exec, s[0:1]
	s_nop 1
	v_mov_b32_dpp v142, v12 row_ror:15 row_mask:0xf bank_mask:0xf
	v_mov_b32_dpp v143, v13 row_ror:15 row_mask:0xf bank_mask:0xf
	v_mov_b32_dpp v156, v14 row_ror:15 row_mask:0xf bank_mask:0xf
	v_mov_b32_dpp v157, v15 row_ror:15 row_mask:0xf bank_mask:0xf
	s_nop 1
	v_mov_b32_dpp v142, v52 row_shl:1 row_mask:0xf bank_mask:0xf
	v_mov_b32_dpp v143, v53 row_shl:1 row_mask:0xf bank_mask:0xf
	v_mov_b32_dpp v156, v54 row_shl:1 row_mask:0xf bank_mask:0xf
	v_mov_b32_dpp v157, v55 row_shl:1 row_mask:0xf bank_mask:0xf
	v_mov_b32_dpp v132, v60 row_ror:1 row_mask:0xf bank_mask:0xf
	v_mov_b32_dpp v133, v61 row_ror:1 row_mask:0xf bank_mask:0xf
	v_mov_b32_dpp v140, v62 row_ror:1 row_mask:0xf bank_mask:0xf
	v_mov_b32_dpp v141, v63 row_ror:1 row_mask:0xf bank_mask:0xf
	v_pk_fma_f32 v[142:143], v[174:175], v[142:143], v[178:179]
	v_pk_fma_f32 v[156:157], v[176:177], v[156:157], v[180:181]
	s_nop 1
	v_mov_b32_dpp v132, v52 row_shr:1 row_mask:0xf bank_mask:0xf
	v_mov_b32_dpp v133, v53 row_shr:1 row_mask:0xf bank_mask:0xf
	v_mov_b32_dpp v140, v54 row_shr:1 row_mask:0xf bank_mask:0xf
	v_mov_b32_dpp v141, v55 row_shr:1 row_mask:0xf bank_mask:0xf
	v_pk_fma_f32 v[156:157], v[54:55], v[172:173], v[156:157]
	v_pk_fma_f32 v[142:143], v[52:53], v[170:171], v[142:143]
	v_mov_b32_dpp v158, v16 row_ror:15 row_mask:0xf bank_mask:0xf
	v_mov_b32_dpp v159, v17 row_ror:15 row_mask:0xf bank_mask:0xf
	v_mov_b32_dpp v160, v18 row_ror:15 row_mask:0xf bank_mask:0xf
; #define LAS __attribute__((address_space(3)))
;     __device__ __forceinline__ void operator()(const f32x4 (&acc)[2][2][4][2], const Unit& u, int wr, int wc, int fr_in, int fq_in) const {
;     ...
;             for (int ai = 0; ai < 2; ++ai) { const int Bk = 2 * ai + wr;
; #pragma unroll
;                 for (int m = 0; m < 4; ++m) {
;                     const int r = 128 * ai + 64 * wr + 16 * m + fr, tb = 254 * j + r - 1;
;                     f32x4 res[2];
; #pragma unroll
;                     for (int bj = 0; bj < 2; ++bj) {
;                         const f32x4 cur = acc[ai][bj][m][n];
;                         f32x4 pe, ne;
;                         if (m > 0) { const f32x4 q = acc[ai][bj][m > 0 ? m - 1 : 0][n]; pe = (f32x4){dpp_ror1(q[0]), dpp_ror1(q[1]), dpp_ror1(q[2]), dpp_ror1(q[3])}; }
;                         else pe = *(const LAS f32x4*)(X + (((Bk > 0 ? Bk - 1 : 0) * 2 + 1) * 2 + bj) * 128 + cl + 4 * n);
;                         if (m < 3) { const f32x4 q = acc[ai][bj][m < 3 ? m + 1 : 3][n]; ne = (f32x4){dpp_rol1(q[0]), dpp_rol1(q[1]), dpp_rol1(q[2]), dpp_rol1(q[3])}; }
;                         else ne = *(const LAS f32x4*)(X + (((Bk < 3 ? Bk + 1 : 3) * 2 + 0) * 2 + bj) * 128 + cl + 4 * n);
;                         f32x4 pvv, nvv;
; #pragma unroll
;                         for (int e = 0; e < 4; ++e) {
;                             float pv = __int_as_float(__builtin_amdgcn_update_dpp(__float_as_int(pe[e]), __float_as_int(cur[e]), 0x111, 0xf, 0xf, false));
;                             float nv = __int_as_float(__builtin_amdgcn_update_dpp(__float_as_int(ne[e]), __float_as_int(cur[e]), 0x101, 0xf, 0xf, false));
;                             if (ai == 0 && m == 0) pv = (tb == 0) ? 0.f : pv;
;                             if (ai == 0 && m == 2) nv = (tb == SEQ - 1) ? 0.f : nv;
;                             pvv[e] = pv; nvv[e] = nv; }
;                         res[bj] = pvv * wv[0][bj] + (cur * wv[1][bj] + (nvv * wv[2][bj] + wv[3][bj]));
;                     }
;                     f32x4 y;
;                     { const f32x4 G = res[0], t = G * -1.4426950408889634f;
;                       f32x4 den; den[0] = __builtin_amdgcn_exp2f(t[0]); den[1] = __builtin_amdgcn_exp2f(t[1]); den[2] = __builtin_amdgcn_exp2f(t[2]); den[3] = __builtin_amdgcn_exp2f(t[3]);
;                       den = den + 1.0f;
	v_mov_b32_dpp v161, v19 row_ror:15 row_mask:0xf bank_mask:0xf
	v_pk_fma_f32 v[132:133], v[166:167], v[132:133], v[142:143]
	v_pk_fma_f32 v[140:141], v[168:169], v[140:141], v[156:157]
	s_nop 1
	v_mov_b32_dpp v158, v24 row_shl:1 row_mask:0xf bank_mask:0xf
	v_mov_b32_dpp v159, v25 row_shl:1 row_mask:0xf bank_mask:0xf
	v_mov_b32_dpp v160, v26 row_shl:1 row_mask:0xf bank_mask:0xf
	v_mov_b32_dpp v161, v27 row_shl:1 row_mask:0xf bank_mask:0xf
	v_mov_b32_dpp v142, v32 row_ror:1 row_mask:0xf bank_mask:0xf
	v_mov_b32_dpp v143, v33 row_ror:1 row_mask:0xf bank_mask:0xf
	v_mov_b32_dpp v156, v34 row_ror:1 row_mask:0xf bank_mask:0xf
	v_mov_b32_dpp v157, v35 row_ror:1 row_mask:0xf bank_mask:0xf
	v_pk_fma_f32 v[160:161], v[150:151], v[160:161], v[154:155]
	v_pk_fma_f32 v[158:159], v[148:149], v[158:159], v[152:153]
	v_mov_b32_dpp v142, v24 row_shr:1 row_mask:0xf bank_mask:0xf
	v_mov_b32_dpp v143, v25 row_shr:1 row_mask:0xf bank_mask:0xf
	v_mov_b32_dpp v156, v26 row_shr:1 row_mask:0xf bank_mask:0xf
	v_mov_b32_dpp v157, v27 row_shr:1 row_mask:0xf bank_mask:0xf
	v_pk_fma_f32 v[158:159], v[24:25], v[144:145], v[158:159]
	v_pk_fma_f32 v[160:161], v[26:27], v[146:147], v[160:161]
	s_mov_b32 s0, 0xbfb8aa3b
	v_pk_fma_f32 v[156:157], v[138:139], v[156:157], v[160:161]
	v_pk_fma_f32 v[142:143], v[136:137], v[142:143], v[158:159]
	v_pk_mul_f32 v[158:159], v[140:141], s[0:1] op_sel_hi:[1,0]
	v_pk_mul_f32 v[160:161], v[132:133], s[0:1] op_sel_hi:[1,0]
	v_exp_f32_e32 v158, v158
	v_exp_f32_e32 v160, v160
	v_exp_f32_e32 v161, v161
	v_exp_f32_e32 v159, v159
	v_pk_mul_f32 v[132:133], v[132:133], v[142:143]
	v_pk_mul_f32 v[140:141], v[140:141], v[156:157]
	v_pk_add_f32 v[160:161], v[160:161], 1.0 op_sel_hi:[1,0]
	v_pk_add_f32 v[158:159], v[158:159], 1.0 op_sel_hi:[1,0]
	v_rcp_f32_e32 v160, v160
	v_rcp_f32_e32 v161, v161
	v_rcp_f32_e32 v158, v158
	v_rcp_f32_e32 v159, v159
	v_add_u32_e32 v134, 0xa0, v229
	v_pk_mul_f32 v[132:133], v[160:161], v[132:133]
	v_add_u32_e32 v135, v134, v230
	v_pk_mul_f32 v[140:141], v[158:159], v[140:141]
	v_cvt_pk_bf16_f32 v132, v132, v133
	s_movk_i32 s0, 0x1001
	v_cvt_pk_bf16_f32 v133, v140, v141
	v_add_u32_e32 v140, 0x9f, v229
	v_cmp_gt_u32_e32 vcc, s67, v140
	v_cmp_gt_i32_e64 s[0:1], s0, v135
	s_and_b64 s[8:9], vcc, s[0:1]
	s_and_saveexec_b64 s[0:1], s[8:9]
	s_cbranch_execz .LBB0_238
	s_movk_i32 s8, 0x1600
	v_mul_lo_u32 v182, v134, s8
	v_lshl_add_u64 v[134:135], v[182:183], 1, v[204:205]
	global_store_dwordx4 v[134:135], v[130:133], off
.LBB0_238:
	s_or_b64 exec, exec, s[0:1]
	ds_read_b128 v[140:143], v231 offset:2064
	s_nop 1
	s_waitcnt lgkmcnt(0)
	v_mov_b32_dpp v140, v12 row_shl:1 row_mask:0xf bank_mask:0xf
	v_mov_b32_dpp v141, v13 row_shl:1 row_mask:0xf bank_mask:0xf
	v_mov_b32_dpp v142, v14 row_shl:1 row_mask:0xf bank_mask:0xf
	v_mov_b32_dpp v143, v15 row_shl:1 row_mask:0xf bank_mask:0xf
	v_mov_b32_dpp v130, v52 row_ror:1 row_mask:0xf bank_mask:0xf
	v_mov_b32_dpp v131, v53 row_ror:1 row_mask:0xf bank_mask:0xf
	v_mov_b32_dpp v134, v54 row_ror:1 row_mask:0xf bank_mask:0xf
	v_mov_b32_dpp v135, v55 row_ror:1 row_mask:0xf bank_mask:0xf
	v_pk_fma_f32 v[140:141], v[174:175], v[140:141], v[178:179]
	v_pk_fma_f32 v[142:143], v[176:177], v[142:143], v[180:181]
	v_mov_b32_dpp v130, v12 row_shr:1 row_mask:0xf bank_mask:0xf
	v_mov_b32_dpp v131, v13 row_shr:1 row_mask:0xf bank_mask:0xf
	v_mov_b32_dpp v134, v14 row_shr:1 row_mask:0xf bank_mask:0xf
	v_mov_b32_dpp v135, v15 row_shr:1 row_mask:0xf bank_mask:0xf
	v_pk_fma_f32 v[142:143], v[14:15], v[172:173], v[142:143]
	v_pk_fma_f32 v[140:141], v[12:13], v[170:171], v[140:141]
	v_pk_fma_f32 v[134:135], v[168:169], v[134:135], v[142:143]
	v_pk_fma_f32 v[130:131], v[166:167], v[130:131], v[140:141]
	ds_read_b128 v[140:143], v231 offset:2576
	s_nop 1
	s_waitcnt lgkmcnt(0)
	v_mov_b32_dpp v140, v16 row_shl:1 row_mask:0xf bank_mask:0xf
	v_mov_b32_dpp v141, v17 row_shl:1 row_mask:0xf bank_mask:0xf
	v_mov_b32_dpp v142, v18 row_shl:1 row_mask:0xf bank_mask:0xf
	v_mov_b32_dpp v143, v19 row_shl:1 row_mask:0xf bank_mask:0xf
	v_mov_b32_dpp v156, v24 row_ror:1 row_mask:0xf bank_mask:0xf
	v_mov_b32_dpp v157, v25 row_ror:1 row_mask:0xf bank_mask:0xf
	v_mov_b32_dpp v158, v26 row_ror:1 row_mask:0xf bank_mask:0xf
	v_mov_b32_dpp v159, v27 row_ror:1 row_mask:0xf bank_mask:0xf
	v_pk_fma_f32 v[142:143], v[150:151], v[142:143], v[154:155]
	v_pk_fma_f32 v[140:141], v[148:149], v[140:141], v[152:153]
	v_mov_b32_dpp v156, v16 row_shr:1 row_mask:0xf bank_mask:0xf
	v_mov_b32_dpp v157, v17 row_shr:1 row_mask:0xf bank_mask:0xf
	v_mov_b32_dpp v158, v18 row_shr:1 row_mask:0xf bank_mask:0xf
	v_mov_b32_dpp v159, v19 row_shr:1 row_mask:0xf bank_mask:0xf
	v_pk_fma_f32 v[140:141], v[16:17], v[144:145], v[140:141]
	v_pk_fma_f32 v[142:143], v[18:19], v[146:147], v[142:143]
	s_mov_b32 s0, 0xbfb8aa3b
	v_pk_fma_f32 v[138:139], v[138:139], v[158:159], v[142:143]
	v_pk_fma_f32 v[136:137], v[136:137], v[156:157], v[140:141]
	v_pk_mul_f32 v[140:141], v[134:135], s[0:1] op_sel_hi:[1,0]
	v_pk_mul_f32 v[142:143], v[130:131], s[0:1] op_sel_hi:[1,0]
	v_exp_f32_e32 v140, v140
	v_exp_f32_e32 v142, v142
	v_exp_f32_e32 v143, v143
	v_exp_f32_e32 v141, v141
	v_pk_mul_f32 v[130:131], v[130:131], v[136:137]
	v_pk_mul_f32 v[134:135], v[134:135], v[138:139]
	v_pk_add_f32 v[142:143], v[142:143], 1.0 op_sel_hi:[1,0]
	v_pk_add_f32 v[140:141], v[140:141], 1.0 op_sel_hi:[1,0]
	v_rcp_f32_e32 v142, v142
	v_rcp_f32_e32 v143, v143
	v_rcp_f32_e32 v140, v140
	v_rcp_f32_e32 v141, v141
	v_add_u32_e32 v132, 0xb0, v229
	v_pk_mul_f32 v[130:131], v[142:143], v[130:131]
	v_add_u32_e32 v133, v132, v230
	v_pk_mul_f32 v[134:135], v[140:141], v[134:135]
	v_cvt_pk_bf16_f32 v130, v130, v131
	s_movk_i32 s0, 0x1001
	v_cvt_pk_bf16_f32 v131, v134, v135
	v_add_u32_e32 v134, 0xaf, v229
	v_cmp_gt_u32_e32 vcc, s67, v134
	v_cmp_gt_i32_e64 s[0:1], s0, v133
	s_and_b64 s[8:9], vcc, s[0:1]
	s_and_saveexec_b64 s[0:1], s[8:9]
	s_cbranch_execz .LBB0_240
	s_movk_i32 s8, 0x1600
	v_mul_lo_u32 v182, v132, s8
	v_lshl_add_u64 v[132:133], v[182:183], 1, v[204:205]
	global_store_dwordx4 v[132:133], v[128:131], off
	s_or_b64 exec, exec, s[0:1]
	s_andn2_b64 vcc, exec, s[36:37]
	s_cbranch_vccnz .LBB0_122
	s_branch .LBB0_241

; __device__ __forceinline__ float bflo(unsigned w) { return __uint_as_float(w << 16); }
; __device__ __forceinline__ float bfhi(unsigned w) { return __uint_as_float(w & 0xffff0000u); }
; __device__ __forceinline__ unsigned cvt_pk_bf16(float lo, float hi) { unsigned r; asm volatile("v_cvt_pk_bf16_f32 %0, %1, %2" : "=v"(r) : "v"(lo), "v"(hi)); return r; }
;     __device__ __forceinline__ void operator()(const f32x4 (&acc)[2][2][4][2], const Unit& u, int wr, int wc, int fr_in, int fq_in) const {
;     ...
;                     u32x4 rb[2][2];
; #pragma unroll
;                     for (int m2 = 0; m2 < 2; ++m2)
; #pragma unroll
;                         for (int bj = 0; bj < 2; ++bj) rb[m2][bj] = *(const u32x4*)(R16 + off0 + (size_t)(ai * HALF + (2 * mh + m2) * 16) * u.ldc + bj * HALF);
; #pragma unroll
;                     for (int m2 = 0; m2 < 2; ++m2)
; #pragma unroll
;                         for (int bj = 0; bj < 2; ++bj) { const u32x4 t = rb[m2][bj]; rv[m2][bj][0] = (f32x4){bflo(t.x), bfhi(t.x), bflo(t.y), bfhi(t.y)}; rv[m2][bj][1] = (f32x4){bflo(t.z), bfhi(t.z), bflo(t.w), bfhi(t.w)}; }
;                 }
;                 asm volatile("" ::: "memory");
; #pragma unroll
;                 for (int m2 = 0; m2 < 2; ++m2) { const int m = 2 * mh + m2; const size_t off = off0 + (size_t)(ai * HALF + m * 16) * u.ldc;
; #pragma unroll
;                     for (int bj = 0; bj < 2; ++bj) { const f32x4 v0 = acc[ai][bj][m][0] + rv[m2][bj][0], v1 = acc[ai][bj][m][1] + rv[m2][bj][1];
;                         u32x4 w; w.x = cvt_pk_bf16(v0[0], v0[1]); w.y = cvt_pk_bf16(v0[2], v0[3]); w.z = cvt_pk_bf16(v1[0], v1[1]); w.w = cvt_pk_bf16(v1[2], v1[3]);
;                         *(u32x4*)(O + off + bj * HALF) = w; } }
.LBB0_325:
	s_waitcnt vmcnt(0)
	v_pk_add_f32 v[130:131], v[126:127], v[130:131]
	v_pk_add_f32 v[128:129], v[124:125], v[128:129]
	v_lshl_add_u64 v[174:175], v[174:175], 1, s[8:9]
	v_pk_add_f32 v[146:147], v[122:123], v[146:147]
	v_pk_add_f32 v[144:145], v[120:121], v[144:145]
	v_cvt_pk_bf16_f32 v124, v128, v129
	v_cvt_pk_bf16_f32 v125, v130, v131
	s_mov_b64 s[58:59], -1
	v_cvt_pk_bf16_f32 v126, v144, v145
	v_cvt_pk_bf16_f32 v127, v146, v147
	global_store_dwordx4 v[174:175], v[124:127], off
	s_andn2_b64 vcc, exec, s[0:1]
	s_nop 0
	v_pk_add_f32 v[130:131], v[94:95], v[134:135]
	v_pk_add_f32 v[128:129], v[92:93], v[132:133]
	v_pk_add_f32 v[132:133], v[90:91], v[150:151]
	v_pk_add_f32 v[134:135], v[88:89], v[148:149]
	v_cvt_pk_bf16_f32 v92, v128, v129
	v_cvt_pk_bf16_f32 v93, v130, v131
	s_nop 0
	v_cvt_pk_bf16_f32 v94, v134, v135
	v_cvt_pk_bf16_f32 v95, v132, v133
	global_store_dwordx4 v[174:175], v[92:95], off offset:256
	v_lshl_add_u64 v[132:133], v[174:175], 0, s[38:39]
	v_pk_add_f32 v[134:135], v[114:115], v[154:155]
	v_pk_add_f32 v[130:131], v[118:119], v[138:139]
	v_pk_add_f32 v[128:129], v[116:117], v[136:137]
	v_pk_add_f32 v[136:137], v[112:113], v[152:153]
	v_cvt_pk_bf16_f32 v116, v128, v129
	v_cvt_pk_bf16_f32 v117, v130, v131
	s_nop 0
	v_cvt_pk_bf16_f32 v118, v136, v137
	v_cvt_pk_bf16_f32 v119, v134, v135
	global_store_dwordx4 v[132:133], v[116:119], off
	v_pk_add_f32 v[134:135], v[82:83], v[158:159]
	v_pk_add_f32 v[136:137], v[80:81], v[156:157]
	v_pk_add_f32 v[130:131], v[86:87], v[142:143]
	v_pk_add_f32 v[128:129], v[84:85], v[140:141]
	s_nop 0
	v_cvt_pk_bf16_f32 v84, v128, v129
	v_cvt_pk_bf16_f32 v85, v130, v131
	v_cvt_pk_bf16_f32 v86, v136, v137
	v_cvt_pk_bf16_f32 v87, v134, v135
	global_store_dwordx4 v[132:133], v[84:87], off offset:256
	s_nop 1
	v_cndmask_b32_e64 v128, 0, 1, s[0:1]
	v_cmp_ne_u32_e64 s[38:39], 1, v128
	s_mul_hi_i32 s1, s12, 0x60
	s_mul_i32 s0, s12, 0x60
	s_cbranch_vccnz .LBB0_327
	s_lshl_b64 s[56:57], s[12:13], 7
	v_lshl_add_u64 v[136:137], v[178:179], 0, s[56:57]
	s_lshl_b64 s[56:57], s[12:13], 6
	v_lshl_add_u64 v[144:145], v[136:137], 0, s[56:57]
	global_load_dwordx4 v[140:143], v[136:137], off offset:16
	global_load_dwordx4 v[128:131], v[136:137], off
	global_load_dwordx4 v[148:151], v[136:137], off offset:528
	global_load_dwordx4 v[132:135], v[136:137], off offset:512
	global_load_dwordx4 v[152:155], v[144:145], off offset:16
	s_nop 0
	global_load_dwordx4 v[136:139], v[144:145], off
	global_load_dwordx4 v[156:159], v[144:145], off offset:528
	s_nop 0
	global_load_dwordx4 v[144:147], v[144:145], off offset:512
	s_mov_b64 s[58:59], 0

; __device__ __forceinline__ float bflo(unsigned w) { return __uint_as_float(w << 16); }
; __device__ __forceinline__ float bfhi(unsigned w) { return __uint_as_float(w & 0xffff0000u); }
; __device__ __forceinline__ unsigned cvt_pk_bf16(float lo, float hi) { unsigned r; asm volatile("v_cvt_pk_bf16_f32 %0, %1, %2" : "=v"(r) : "v"(lo), "v"(hi)); return r; }
;     __device__ __forceinline__ void operator()(const f32x4 (&acc)[2][2][4][2], const Unit& u, int wr, int wc, int fr_in, int fq_in) const {
;     ...
;                     u32x4 rb[2][2];
; #pragma unroll
;                     for (int m2 = 0; m2 < 2; ++m2)
; #pragma unroll
;                         for (int bj = 0; bj < 2; ++bj) rb[m2][bj] = *(const u32x4*)(R16 + off0 + (size_t)(ai * HALF + (2 * mh + m2) * 16) * u.ldc + bj * HALF);
; #pragma unroll
;                     for (int m2 = 0; m2 < 2; ++m2)
; #pragma unroll
;                         for (int bj = 0; bj < 2; ++bj) { const u32x4 t = rb[m2][bj]; rv[m2][bj][0] = (f32x4){bflo(t.x), bfhi(t.x), bflo(t.y), bfhi(t.y)}; rv[m2][bj][1] = (f32x4){bflo(t.z), bfhi(t.z), bflo(t.w), bfhi(t.w)}; }
;                 }
;                 asm volatile("" ::: "memory");
; #pragma unroll
;                 for (int m2 = 0; m2 < 2; ++m2) { const int m = 2 * mh + m2; const size_t off = off0 + (size_t)(ai * HALF + m * 16) * u.ldc;
; #pragma unroll
;                     for (int bj = 0; bj < 2; ++bj) { const f32x4 v0 = acc[ai][bj][m][0] + rv[m2][bj][0], v1 = acc[ai][bj][m][1] + rv[m2][bj][1];
;                         u32x4 w; w.x = cvt_pk_bf16(v0[0], v0[1]); w.y = cvt_pk_bf16(v0[2], v0[3]); w.z = cvt_pk_bf16(v1[0], v1[1]); w.w = cvt_pk_bf16(v1[2], v1[3]);
;                         *(u32x4*)(O + off + bj * HALF) = w; } }
.LBB0_329:
	s_waitcnt vmcnt(6)
	v_pk_add_f32 v[130:131], v[110:111], v[130:131]
	v_pk_add_f32 v[128:129], v[108:109], v[128:129]
	v_lshl_add_u64 v[190:191], v[174:175], 0, s[56:57]
	v_pk_add_f32 v[142:143], v[106:107], v[142:143]
	v_pk_add_f32 v[140:141], v[104:105], v[140:141]
	v_cvt_pk_bf16_f32 v108, v128, v129
	v_cvt_pk_bf16_f32 v109, v130, v131
	s_mov_b64 s[58:59], -1
	v_cvt_pk_bf16_f32 v110, v140, v141
	v_cvt_pk_bf16_f32 v111, v142, v143
	global_store_dwordx4 v[190:191], v[108:111], off
	s_and_b64 vcc, exec, s[38:39]
	s_waitcnt vmcnt(5)
	v_pk_add_f32 v[130:131], v[78:79], v[134:135]
	v_pk_add_f32 v[128:129], v[76:77], v[132:133]
	v_pk_add_f32 v[132:133], v[74:75], v[150:151]
	v_pk_add_f32 v[134:135], v[72:73], v[148:149]
	v_cvt_pk_bf16_f32 v76, v128, v129
	v_cvt_pk_bf16_f32 v77, v130, v131
	s_nop 0
	v_cvt_pk_bf16_f32 v78, v134, v135
	v_cvt_pk_bf16_f32 v79, v132, v133
	global_store_dwordx4 v[190:191], v[76:79], off offset:256
	v_lshl_add_u64 v[132:133], v[174:175], 0, s[0:1]
	s_waitcnt vmcnt(5)
	v_pk_add_f32 v[134:135], v[98:99], v[154:155]
	s_waitcnt vmcnt(4)
	v_pk_add_f32 v[130:131], v[102:103], v[138:139]
	v_pk_add_f32 v[128:129], v[100:101], v[136:137]
	v_pk_add_f32 v[136:137], v[96:97], v[152:153]
	v_cvt_pk_bf16_f32 v100, v128, v129
	v_cvt_pk_bf16_f32 v101, v130, v131
	s_mul_hi_i32 s1, s12, 0x120
	v_cvt_pk_bf16_f32 v102, v136, v137
	v_cvt_pk_bf16_f32 v103, v134, v135
	global_store_dwordx4 v[132:133], v[100:103], off
	s_waitcnt vmcnt(4)
	v_pk_add_f32 v[134:135], v[66:67], v[158:159]
	v_pk_add_f32 v[136:137], v[64:65], v[156:157]
	s_waitcnt vmcnt(3)
	v_pk_add_f32 v[130:131], v[70:71], v[146:147]
	v_pk_add_f32 v[128:129], v[68:69], v[144:145]
	s_mul_i32 s0, s12, 0x120
	v_cvt_pk_bf16_f32 v68, v128, v129
	v_cvt_pk_bf16_f32 v69, v130, v131
	v_cvt_pk_bf16_f32 v70, v136, v137
	v_cvt_pk_bf16_f32 v71, v134, v135
	global_store_dwordx4 v[132:133], v[68:71], off offset:256
	s_cbranch_vccnz .LBB0_331
	s_lshl_b64 s[56:57], s[12:13], 9
	v_lshl_add_u64 v[136:137], v[178:179], 0, s[56:57]
	s_lshl_b64 s[56:57], s[12:13], 6
	v_lshl_add_u64 v[144:145], v[136:137], 0, s[56:57]
	global_load_dwordx4 v[140:143], v[136:137], off offset:16
	global_load_dwordx4 v[128:131], v[136:137], off
	global_load_dwordx4 v[148:151], v[136:137], off offset:528
	global_load_dwordx4 v[132:135], v[136:137], off offset:512
	global_load_dwordx4 v[152:155], v[144:145], off offset:16
	s_nop 0
	global_load_dwordx4 v[136:139], v[144:145], off
	global_load_dwordx4 v[156:159], v[144:145], off offset:528
	s_nop 0
	global_load_dwordx4 v[144:147], v[144:145], off offset:512
	s_lshl_b64 s[56:57], s[12:13], 8
	s_mov_b64 s[58:59], 0

; __device__ __forceinline__ float bflo(unsigned w) { return __uint_as_float(w << 16); }
; __device__ __forceinline__ float bfhi(unsigned w) { return __uint_as_float(w & 0xffff0000u); }
; __device__ __forceinline__ unsigned cvt_pk_bf16(float lo, float hi) { unsigned r; asm volatile("v_cvt_pk_bf16_f32 %0, %1, %2" : "=v"(r) : "v"(lo), "v"(hi)); return r; }
;     __device__ __forceinline__ void operator()(const f32x4 (&acc)[2][2][4][2], const Unit& u, int wr, int wc, int fr_in, int fq_in) const {
;     ...
;                     u32x4 rb[2][2];
; #pragma unroll
;                     for (int m2 = 0; m2 < 2; ++m2)
; #pragma unroll
;                         for (int bj = 0; bj < 2; ++bj) rb[m2][bj] = *(const u32x4*)(R16 + off0 + (size_t)(ai * HALF + (2 * mh + m2) * 16) * u.ldc + bj * HALF);
; #pragma unroll
;                     for (int m2 = 0; m2 < 2; ++m2)
; #pragma unroll
;                         for (int bj = 0; bj < 2; ++bj) { const u32x4 t = rb[m2][bj]; rv[m2][bj][0] = (f32x4){bflo(t.x), bfhi(t.x), bflo(t.y), bfhi(t.y)}; rv[m2][bj][1] = (f32x4){bflo(t.z), bfhi(t.z), bflo(t.w), bfhi(t.w)}; }
;                 }
;                 asm volatile("" ::: "memory");
; #pragma unroll
;                 for (int m2 = 0; m2 < 2; ++m2) { const int m = 2 * mh + m2; const size_t off = off0 + (size_t)(ai * HALF + m * 16) * u.ldc;
; #pragma unroll
;                     for (int bj = 0; bj < 2; ++bj) { const f32x4 v0 = acc[ai][bj][m][0] + rv[m2][bj][0], v1 = acc[ai][bj][m][1] + rv[m2][bj][1];
;                         u32x4 w; w.x = cvt_pk_bf16(v0[0], v0[1]); w.y = cvt_pk_bf16(v0[2], v0[3]); w.z = cvt_pk_bf16(v1[0], v1[1]); w.w = cvt_pk_bf16(v1[2], v1[3]);
;                         *(u32x4*)(O + off + bj * HALF) = w; } }
.LBB0_333:
	s_waitcnt vmcnt(6)
	v_pk_add_f32 v[130:131], v[62:63], v[130:131]
	v_pk_add_f32 v[128:129], v[60:61], v[128:129]
	v_lshl_add_u64 v[190:191], v[174:175], 0, s[56:57]
	v_pk_add_f32 v[142:143], v[58:59], v[142:143]
	v_pk_add_f32 v[140:141], v[56:57], v[140:141]
	v_cvt_pk_bf16_f32 v60, v128, v129
	v_cvt_pk_bf16_f32 v61, v130, v131
	s_mov_b64 s[56:57], -1
	v_cvt_pk_bf16_f32 v62, v140, v141
	v_cvt_pk_bf16_f32 v63, v142, v143
	global_store_dwordx4 v[190:191], v[60:63], off
	s_and_b64 vcc, exec, s[38:39]
	s_mul_hi_i32 s39, s12, 0x140
	s_waitcnt vmcnt(5)
	v_pk_add_f32 v[130:131], v[30:31], v[134:135]
	v_pk_add_f32 v[128:129], v[28:29], v[132:133]
	v_pk_add_f32 v[132:133], v[26:27], v[150:151]
	v_pk_add_f32 v[134:135], v[24:25], v[148:149]
	v_cvt_pk_bf16_f32 v28, v128, v129
	v_cvt_pk_bf16_f32 v29, v130, v131
	s_mul_i32 s38, s12, 0x140
	v_cvt_pk_bf16_f32 v30, v134, v135
	v_cvt_pk_bf16_f32 v31, v132, v133
	global_store_dwordx4 v[190:191], v[28:31], off offset:256
	v_lshl_add_u64 v[132:133], v[174:175], 0, s[0:1]
	s_waitcnt vmcnt(5)
	v_pk_add_f32 v[134:135], v[50:51], v[154:155]
	s_waitcnt vmcnt(4)
	v_pk_add_f32 v[130:131], v[54:55], v[138:139]
	v_pk_add_f32 v[128:129], v[52:53], v[136:137]
	v_pk_add_f32 v[136:137], v[48:49], v[152:153]
	v_cvt_pk_bf16_f32 v52, v128, v129
	v_cvt_pk_bf16_f32 v53, v130, v131
	s_mul_hi_i32 s1, s12, 0x160
	v_cvt_pk_bf16_f32 v54, v136, v137
	v_cvt_pk_bf16_f32 v55, v134, v135
	global_store_dwordx4 v[132:133], v[52:55], off
	s_waitcnt vmcnt(4)
	v_pk_add_f32 v[134:135], v[18:19], v[158:159]
	v_pk_add_f32 v[136:137], v[16:17], v[156:157]
	s_waitcnt vmcnt(3)
	v_pk_add_f32 v[130:131], v[22:23], v[146:147]
	v_pk_add_f32 v[128:129], v[20:21], v[144:145]
	s_mul_i32 s0, s12, 0x160
	v_cvt_pk_bf16_f32 v20, v128, v129
	v_cvt_pk_bf16_f32 v21, v130, v131
	v_cvt_pk_bf16_f32 v22, v136, v137
	v_cvt_pk_bf16_f32 v23, v134, v135
	global_store_dwordx4 v[132:133], v[20:23], off offset:256
	s_cbranch_vccnz .LBB0_335
	s_nop 0
	v_mov_b32_e32 v128, 0x280
	v_mad_i64_i32 v[136:137], s[56:57], s12, v128, v[178:179]
	s_lshl_b64 s[56:57], s[12:13], 6
	s_nop 0
	v_lshl_add_u64 v[144:145], v[136:137], 0, s[56:57]
	global_load_dwordx4 v[140:143], v[136:137], off offset:16
	global_load_dwordx4 v[128:131], v[136:137], off
	global_load_dwordx4 v[148:151], v[136:137], off offset:528
	global_load_dwordx4 v[132:135], v[136:137], off offset:512
	global_load_dwordx4 v[152:155], v[144:145], off offset:16
	s_nop 0
	global_load_dwordx4 v[136:139], v[144:145], off
	global_load_dwordx4 v[156:159], v[144:145], off offset:528
	s_nop 0
	global_load_dwordx4 v[144:147], v[144:145], off offset:512
	s_mov_b64 s[56:57], 0

; __device__ __forceinline__ float bflo(unsigned w) { return __uint_as_float(w << 16); }
; __device__ __forceinline__ float bfhi(unsigned w) { return __uint_as_float(w & 0xffff0000u); }
; __device__ __forceinline__ unsigned cvt_pk_bf16(float lo, float hi) { unsigned r; asm volatile("v_cvt_pk_bf16_f32 %0, %1, %2" : "=v"(r) : "v"(lo), "v"(hi)); return r; }
;     __device__ __forceinline__ void operator()(const f32x4 (&acc)[2][2][4][2], const Unit& u, int wr, int wc, int fr_in, int fq_in) const {
;     ...
;                     u32x4 rb[2][2];
; #pragma unroll
;                     for (int m2 = 0; m2 < 2; ++m2)
; #pragma unroll
;                         for (int bj = 0; bj < 2; ++bj) rb[m2][bj] = *(const u32x4*)(R16 + off0 + (size_t)(ai * HALF + (2 * mh + m2) * 16) * u.ldc + bj * HALF);
; #pragma unroll
;                     for (int m2 = 0; m2 < 2; ++m2)
; #pragma unroll
;                         for (int bj = 0; bj < 2; ++bj) { const u32x4 t = rb[m2][bj]; rv[m2][bj][0] = (f32x4){bflo(t.x), bfhi(t.x), bflo(t.y), bfhi(t.y)}; rv[m2][bj][1] = (f32x4){bflo(t.z), bfhi(t.z), bflo(t.w), bfhi(t.w)}; }
;                 }
;                 asm volatile("" ::: "memory");
; #pragma unroll
;                 for (int m2 = 0; m2 < 2; ++m2) { const int m = 2 * mh + m2; const size_t off = off0 + (size_t)(ai * HALF + m * 16) * u.ldc;
; #pragma unroll
;                     for (int bj = 0; bj < 2; ++bj) { const f32x4 v0 = acc[ai][bj][m][0] + rv[m2][bj][0], v1 = acc[ai][bj][m][1] + rv[m2][bj][1];
;                         u32x4 w; w.x = cvt_pk_bf16(v0[0], v0[1]); w.y = cvt_pk_bf16(v0[2], v0[3]); w.z = cvt_pk_bf16(v1[0], v1[1]); w.w = cvt_pk_bf16(v1[2], v1[3]);
;                         *(u32x4*)(O + off + bj * HALF) = w; } }
.LBB0_337:
	s_waitcnt vmcnt(6)
	v_pk_add_f32 v[130:131], v[46:47], v[130:131]
	v_pk_add_f32 v[128:129], v[44:45], v[128:129]
	v_lshl_add_u64 v[176:177], v[174:175], 0, s[38:39]
	v_pk_add_f32 v[142:143], v[42:43], v[142:143]
	v_pk_add_f32 v[140:141], v[40:41], v[140:141]
	v_cvt_pk_bf16_f32 v44, v128, v129
	v_cvt_pk_bf16_f32 v45, v130, v131
	s_andn2_b64 vcc, exec, s[64:65]
	v_cvt_pk_bf16_f32 v46, v140, v141
	v_cvt_pk_bf16_f32 v47, v142, v143
	global_store_dwordx4 v[176:177], v[44:47], off
	s_movk_i32 s56, 0x1f8
	s_movk_i32 s57, 0x1fff
	s_waitcnt vmcnt(5)
	v_pk_add_f32 v[130:131], v[14:15], v[134:135]
	v_pk_add_f32 v[128:129], v[12:13], v[132:133]
	v_pk_add_f32 v[132:133], v[10:11], v[150:151]
	v_pk_add_f32 v[134:135], v[8:9], v[148:149]
	v_cvt_pk_bf16_f32 v12, v128, v129
	v_cvt_pk_bf16_f32 v13, v130, v131
	s_mov_b32 s64, 0xb0000
	v_cvt_pk_bf16_f32 v14, v134, v135
	v_cvt_pk_bf16_f32 v15, v132, v133
	global_store_dwordx4 v[176:177], v[12:15], off offset:256
	v_lshl_add_u64 v[132:133], v[174:175], 0, s[0:1]
	s_waitcnt vmcnt(5)
	v_pk_add_f32 v[134:135], v[34:35], v[154:155]
	s_waitcnt vmcnt(4)
	v_pk_add_f32 v[130:131], v[38:39], v[138:139]
	v_pk_add_f32 v[128:129], v[36:37], v[136:137]
	v_pk_add_f32 v[136:137], v[32:33], v[152:153]
	v_cvt_pk_bf16_f32 v36, v128, v129
	v_cvt_pk_bf16_f32 v37, v130, v131
	s_mov_b32 s65, 0xdc000
	v_cvt_pk_bf16_f32 v38, v136, v137
	v_cvt_pk_bf16_f32 v39, v134, v135
	global_store_dwordx4 v[132:133], v[36:39], off
	s_waitcnt vmcnt(4)
	v_pk_add_f32 v[134:135], v[2:3], v[158:159]
	v_pk_add_f32 v[136:137], v[0:1], v[156:157]
	s_waitcnt vmcnt(3)
	v_pk_add_f32 v[130:131], v[6:7], v[146:147]
	v_pk_add_f32 v[128:129], v[4:5], v[144:145]
	s_nop 0
	v_cvt_pk_bf16_f32 v4, v128, v129
	v_cvt_pk_bf16_f32 v5, v130, v131
	v_cvt_pk_bf16_f32 v6, v136, v137
	v_cvt_pk_bf16_f32 v7, v134, v135
	global_store_dwordx4 v[132:133], v[4:7], off offset:256
	s_branch .Lln_begin

; __device__ __forceinline__ float bflo(unsigned w) { return __uint_as_float(w << 16); }
; __device__ __forceinline__ float bfhi(unsigned w) { return __uint_as_float(w & 0xffff0000u); }
; template <bool OUT_F32, bool IN_BF16>
; __device__ __forceinline__ void phase_rmsnorm(const void* Xv, const float* gain, void* out) {
;     ...
;     f32x4 g[4][2];
; #pragma unroll
;     for (int j = 0; j < 4; ++j) { g[j][0] = *(const f32x4*)(gain + 8 * lane + 512 * j); g[j][1] = *(const f32x4*)(gain + 8 * lane + 512 * j + 4); }
;     constexpr int RPT = 4;
;     for (int m0 = gw; m0 < NTOK; m0 += RPT * NGW) {
;         f32x4 v[RPT][4][2]; u32x4 t[RPT][4];
; #pragma unroll
;         for (int r = 0; r < RPT; ++r) { const int mr = m0 + r * NGW, mc = mr < NTOK ? mr : m0;
; #pragma unroll
;             for (int j = 0; j < 4; ++j) { if (IN_BF16) t[r][j] = *(const u32x4*)(Xb + (size_t)mc * DM + 8 * lane + 512 * j);
;                 else { v[r][j][0] = *(const f32x4*)(X + (size_t)mc * DM + 8 * lane + 512 * j); v[r][j][1] = *(const f32x4*)(X + (size_t)mc * DM + 8 * lane + 512 * j + 4); } } }
;         float rs[RPT];
; #pragma unroll
;         for (int r = 0; r < RPT; ++r) { float sq = 0.f;
; #pragma unroll
;             for (int j = 0; j < 4; ++j) { if (IN_BF16) { const u32x4 q = t[r][j]; v[r][j][0] = (f32x4){bflo(q.x), bfhi(q.x), bflo(q.y), bfhi(q.y)}; v[r][j][1] = (f32x4){bflo(q.z), bfhi(q.z), bflo(q.w), bfhi(q.w)}; }
; #pragma unroll
;                 for (int h = 0; h < 2; ++h) { const f32x4 a = v[r][j][h]; sq += (a.x * a.x + a.y * a.y) + (a.z * a.z + a.w * a.w); } }
;             rs[r] = 1.0f / sqrtf(wave_sum(sq) * (1.0f / DM) + EPS); }
.Lln_go:
	v_readlane_b32 s38, v252, 2
	v_readlane_b32 s39, v252, 3
	s_nop 0
	s_sub_u32 s38, s38, 0x90
	s_subb_u32 s39, s39, 0
	s_load_dwordx4 s[56:59], s[38:39], 0x38
	s_waitcnt lgkmcnt(0)
	s_cmp_eq_u32 s0, 1
	s_cselect_b32 s56, s58, s56
	s_cselect_b32 s57, s59, s57
	s_add_u32 s56, s56, s13
	s_addc_u32 s57, s57, 0
	v_readfirstlane_b32 s58, v174
	v_readfirstlane_b32 s59, v175
	s_add_u32 s64, s88, 0x1b900000
	s_addc_u32 s65, s89, 0
	s_sub_u32 s58, s58, s64
	s_subb_u32 s59, s59, s65
	s_lshr_b32 s13, s58, 20
	s_bfe_u32 s0, s58, 0x30009
	s_lshl_b32 s58, s1, 18
	s_lshl_b32 s59, s13, 13
	s_add_i32 s58, s58, s59
	s_add_u32 s38, s88, 0x30280000
	s_addc_u32 s39, s89, 0
	s_add_u32 s38, s38, s58
	s_addc_u32 s39, s39, 0
	s_lshl_b32 s1, s1, 5
	s_add_i32 s1, s1, s13
	s_lshl_b32 s1, s1, 6
	s_add_u32 s58, s88, 0x40a84000
	s_addc_u32 s59, s89, 0
	s_add_u32 s58, s58, s1
	s_addc_u32 s59, s59, 0
	s_lshl_b32 s1, s0, 10
	s_add_u32 s56, s56, s1
	s_addc_u32 s57, s57, 0
	v_lshrrev_b32_e32 v40, 6, v185
	v_and_b32_e32 v41, 3, v40
	v_lshrrev_b32_e32 v40, 2, v40
	v_bfe_u32 v42, v185, 4, 2
	v_and_b32_e32 v43, 15, v185
	v_lshlrev_b32_e32 v24, 2, v41
	v_lshlrev_b32_e32 v41, 7, v41
	v_lshl_add_u32 v41, v42, 5, v41
	v_lshlrev_b32_e32 v40, 6, v40
	v_add_u32_e32 v40, v40, v43
	v_lshl_add_u32 v35, v40, 4, v24
	v_add_u32_e32 v35, 0x20000, v35
	v_lshlrev_b32_e32 v42, 4, v185
	v_add_u32_e32 v42, 0x20000, v42
	v_and_b32_e32 v3, 63, v185
	v_xor_b32_e32 v2, 16, v3
	v_lshlrev_b32_e32 v2, 2, v2
	v_xor_b32_e32 v3, 32, v3
	v_lshlrev_b32_e32 v3, 2, v3
	v_lshlrev_b32_e32 v43, 5, v185
	s_lshl_b32 s1, s0, 2
	v_add_u32_e32 v32, s1, v43
	v_mov_b32_e32 v33, 1
	global_load_dwordx4 v[88:91], v41, s[56:57]
	global_load_dwordx4 v[80:83], v41, s[56:57] offset:16
	global_load_dwordx4 v[72:75], v41, s[56:57] offset:512
	global_load_dwordx4 v[64:67], v41, s[56:57] offset:528
	v_mov_b32_e32 v104, 0
	v_mov_b32_e32 v105, 0
	v_mov_b32_e32 v106, 0
	v_mov_b32_e32 v107, 0
	v_mov_b32_e32 v96, 0
	v_mov_b32_e32 v97, 0
	v_mov_b32_e32 v98, 0
	v_mov_b32_e32 v99, 0
	v_lshlrev_b32_e32 v120, 16, v124
	v_and_b32_e32 v121, 0xffff0000, v124
	v_lshlrev_b32_e32 v122, 16, v125
	v_and_b32_e32 v123, 0xffff0000, v125
	v_lshlrev_b32_e32 v112, 16, v126
	v_and_b32_e32 v113, 0xffff0000, v126
	v_lshlrev_b32_e32 v114, 16, v127
	v_and_b32_e32 v115, 0xffff0000, v127
	v_fmac_f32_e32 v104, v120, v120
	v_fmac_f32_e32 v104, v121, v121
	v_fmac_f32_e32 v104, v122, v122
	v_fmac_f32_e32 v104, v123, v123
	v_fmac_f32_e32 v104, v112, v112
	v_fmac_f32_e32 v104, v113, v113
	v_fmac_f32_e32 v104, v114, v114
	v_fmac_f32_e32 v104, v115, v115
	v_lshlrev_b32_e32 v120, 16, v92
	v_and_b32_e32 v121, 0xffff0000, v92
	v_lshlrev_b32_e32 v122, 16, v93
	v_and_b32_e32 v123, 0xffff0000, v93
	v_lshlrev_b32_e32 v112, 16, v94
	v_and_b32_e32 v113, 0xffff0000, v94
	v_lshlrev_b32_e32 v114, 16, v95
	v_and_b32_e32 v115, 0xffff0000, v95
	v_fmac_f32_e32 v104, v120, v120
	v_fmac_f32_e32 v104, v121, v121
	v_fmac_f32_e32 v104, v122, v122
	v_fmac_f32_e32 v104, v123, v123
	v_fmac_f32_e32 v104, v112, v112
	v_fmac_f32_e32 v104, v113, v113
	v_fmac_f32_e32 v104, v114, v114
	v_fmac_f32_e32 v104, v115, v115
	v_lshlrev_b32_e32 v120, 16, v116
	v_and_b32_e32 v121, 0xffff0000, v116
	v_lshlrev_b32_e32 v122, 16, v117
	v_and_b32_e32 v123, 0xffff0000, v117
	v_lshlrev_b32_e32 v112, 16, v118
	v_and_b32_e32 v113, 0xffff0000, v118
	v_lshlrev_b32_e32 v114, 16, v119
	v_and_b32_e32 v115, 0xffff0000, v119
	v_fmac_f32_e32 v105, v120, v120
	v_fmac_f32_e32 v105, v121, v121
	v_fmac_f32_e32 v105, v122, v122
	v_fmac_f32_e32 v105, v123, v123
	v_fmac_f32_e32 v105, v112, v112
	v_fmac_f32_e32 v105, v113, v113
	v_fmac_f32_e32 v105, v114, v114
	v_fmac_f32_e32 v105, v115, v115
	v_lshlrev_b32_e32 v120, 16, v84
	v_and_b32_e32 v121, 0xffff0000, v84
	v_lshlrev_b32_e32 v122, 16, v85
	v_and_b32_e32 v123, 0xffff0000, v85
	v_lshlrev_b32_e32 v112, 16, v86
	v_and_b32_e32 v113, 0xffff0000, v86
	v_lshlrev_b32_e32 v114, 16, v87
	v_and_b32_e32 v115, 0xffff0000, v87
	v_fmac_f32_e32 v105, v120, v120
	v_fmac_f32_e32 v105, v121, v121
	v_fmac_f32_e32 v105, v122, v122
	v_fmac_f32_e32 v105, v123, v123
	v_fmac_f32_e32 v105, v112, v112
	v_fmac_f32_e32 v105, v113, v113
	v_fmac_f32_e32 v105, v114, v114
	v_fmac_f32_e32 v105, v115, v115
	v_lshlrev_b32_e32 v120, 16, v108
	v_and_b32_e32 v121, 0xffff0000, v108
	v_lshlrev_b32_e32 v122, 16, v109
	v_and_b32_e32 v123, 0xffff0000, v109
	v_lshlrev_b32_e32 v112, 16, v110
	v_and_b32_e32 v113, 0xffff0000, v110
	v_lshlrev_b32_e32 v114, 16, v111
	v_and_b32_e32 v115, 0xffff0000, v111
	v_fmac_f32_e32 v106, v120, v120
	v_fmac_f32_e32 v106, v121, v121
	v_fmac_f32_e32 v106, v122, v122
	v_fmac_f32_e32 v106, v123, v123
	v_fmac_f32_e32 v106, v112, v112
	v_fmac_f32_e32 v106, v113, v113
	v_fmac_f32_e32 v106, v114, v114
	v_fmac_f32_e32 v106, v115, v115
	v_lshlrev_b32_e32 v120, 16, v76
	v_and_b32_e32 v121, 0xffff0000, v76
	v_lshlrev_b32_e32 v122, 16, v77
	v_and_b32_e32 v123, 0xffff0000, v77
	v_lshlrev_b32_e32 v112, 16, v78
	v_and_b32_e32 v113, 0xffff0000, v78
	v_lshlrev_b32_e32 v114, 16, v79
	v_and_b32_e32 v115, 0xffff0000, v79
	v_fmac_f32_e32 v106, v120, v120
	v_fmac_f32_e32 v106, v121, v121
	v_fmac_f32_e32 v106, v122, v122
	v_fmac_f32_e32 v106, v123, v123
	v_fmac_f32_e32 v106, v112, v112
	v_fmac_f32_e32 v106, v113, v113
	v_fmac_f32_e32 v106, v114, v114
	v_fmac_f32_e32 v106, v115, v115
	v_lshlrev_b32_e32 v120, 16, v100
	v_and_b32_e32 v121, 0xffff0000, v100
	v_lshlrev_b32_e32 v122, 16, v101
	v_and_b32_e32 v123, 0xffff0000, v101
	v_lshlrev_b32_e32 v112, 16, v102
	v_and_b32_e32 v113, 0xffff0000, v102
	v_lshlrev_b32_e32 v114, 16, v103
	v_and_b32_e32 v115, 0xffff0000, v103
	v_fmac_f32_e32 v107, v120, v120
; __device__ __forceinline__ float bflo(unsigned w) { return __uint_as_float(w << 16); }
; __device__ __forceinline__ float bfhi(unsigned w) { return __uint_as_float(w & 0xffff0000u); }
; template <bool OUT_F32, bool IN_BF16>
; __device__ __forceinline__ void phase_rmsnorm(const void* Xv, const float* gain, void* out) {
;     ...
;         float rs[RPT];
; #pragma unroll
;         for (int r = 0; r < RPT; ++r) { float sq = 0.f;
; #pragma unroll
;             for (int j = 0; j < 4; ++j) { if (IN_BF16) { const u32x4 q = t[r][j]; v[r][j][0] = (f32x4){bflo(q.x), bfhi(q.x), bflo(q.y), bfhi(q.y)}; v[r][j][1] = (f32x4){bflo(q.z), bfhi(q.z), bflo(q.w), bfhi(q.w)}; }
; #pragma unroll
;                 for (int h = 0; h < 2; ++h) { const f32x4 a = v[r][j][h]; sq += (a.x * a.x + a.y * a.y) + (a.z * a.z + a.w * a.w); } }
;             rs[r] = 1.0f / sqrtf(wave_sum(sq) * (1.0f / DM) + EPS); }
	v_fmac_f32_e32 v107, v121, v121
	v_fmac_f32_e32 v107, v122, v122
	v_fmac_f32_e32 v107, v123, v123
	v_fmac_f32_e32 v107, v112, v112
	v_fmac_f32_e32 v107, v113, v113
	v_fmac_f32_e32 v107, v114, v114
	v_fmac_f32_e32 v107, v115, v115
	v_lshlrev_b32_e32 v120, 16, v68
	v_and_b32_e32 v121, 0xffff0000, v68
	v_lshlrev_b32_e32 v122, 16, v69
	v_and_b32_e32 v123, 0xffff0000, v69
	v_lshlrev_b32_e32 v112, 16, v70
	v_and_b32_e32 v113, 0xffff0000, v70
	v_lshlrev_b32_e32 v114, 16, v71
	v_and_b32_e32 v115, 0xffff0000, v71
	v_fmac_f32_e32 v107, v120, v120
	v_fmac_f32_e32 v107, v121, v121
	v_fmac_f32_e32 v107, v122, v122
	v_fmac_f32_e32 v107, v123, v123
	v_fmac_f32_e32 v107, v112, v112
	v_fmac_f32_e32 v107, v113, v113
	v_fmac_f32_e32 v107, v114, v114
	v_fmac_f32_e32 v107, v115, v115
	v_lshlrev_b32_e32 v120, 16, v60
	v_and_b32_e32 v121, 0xffff0000, v60
	v_lshlrev_b32_e32 v122, 16, v61
	v_and_b32_e32 v123, 0xffff0000, v61
	v_lshlrev_b32_e32 v112, 16, v62
	v_and_b32_e32 v113, 0xffff0000, v62
	v_lshlrev_b32_e32 v114, 16, v63
	v_and_b32_e32 v115, 0xffff0000, v63
	v_fmac_f32_e32 v96, v120, v120
	v_fmac_f32_e32 v96, v121, v121
	v_fmac_f32_e32 v96, v122, v122
	v_fmac_f32_e32 v96, v123, v123
	v_fmac_f32_e32 v96, v112, v112
	v_fmac_f32_e32 v96, v113, v113
	v_fmac_f32_e32 v96, v114, v114
	v_fmac_f32_e32 v96, v115, v115
	v_lshlrev_b32_e32 v120, 16, v28
	v_and_b32_e32 v121, 0xffff0000, v28
	v_lshlrev_b32_e32 v122, 16, v29
	v_and_b32_e32 v123, 0xffff0000, v29
	v_lshlrev_b32_e32 v112, 16, v30
	v_and_b32_e32 v113, 0xffff0000, v30
	v_lshlrev_b32_e32 v114, 16, v31
	v_and_b32_e32 v115, 0xffff0000, v31
	v_fmac_f32_e32 v96, v120, v120
	v_fmac_f32_e32 v96, v121, v121
	v_fmac_f32_e32 v96, v122, v122
	v_fmac_f32_e32 v96, v123, v123
	v_fmac_f32_e32 v96, v112, v112
	v_fmac_f32_e32 v96, v113, v113
	v_fmac_f32_e32 v96, v114, v114
	v_fmac_f32_e32 v96, v115, v115
	v_lshlrev_b32_e32 v120, 16, v52
	v_and_b32_e32 v121, 0xffff0000, v52
	v_lshlrev_b32_e32 v122, 16, v53
	v_and_b32_e32 v123, 0xffff0000, v53
	v_lshlrev_b32_e32 v112, 16, v54
	v_and_b32_e32 v113, 0xffff0000, v54
	v_lshlrev_b32_e32 v114, 16, v55
	v_and_b32_e32 v115, 0xffff0000, v55
	v_fmac_f32_e32 v97, v120, v120
	v_fmac_f32_e32 v97, v121, v121
	v_fmac_f32_e32 v97, v122, v122
	v_fmac_f32_e32 v97, v123, v123
	v_fmac_f32_e32 v97, v112, v112
	v_fmac_f32_e32 v97, v113, v113
	v_fmac_f32_e32 v97, v114, v114
	v_fmac_f32_e32 v97, v115, v115
	v_lshlrev_b32_e32 v120, 16, v20
	v_and_b32_e32 v121, 0xffff0000, v20
	v_lshlrev_b32_e32 v122, 16, v21
	v_and_b32_e32 v123, 0xffff0000, v21
	v_lshlrev_b32_e32 v112, 16, v22
	v_and_b32_e32 v113, 0xffff0000, v22
	v_lshlrev_b32_e32 v114, 16, v23
	v_and_b32_e32 v115, 0xffff0000, v23
	v_fmac_f32_e32 v97, v120, v120
	v_fmac_f32_e32 v97, v121, v121
	v_fmac_f32_e32 v97, v122, v122
	v_fmac_f32_e32 v97, v123, v123
	v_fmac_f32_e32 v97, v112, v112
	v_fmac_f32_e32 v97, v113, v113
	v_fmac_f32_e32 v97, v114, v114
	v_fmac_f32_e32 v97, v115, v115
	v_lshlrev_b32_e32 v120, 16, v44
	v_and_b32_e32 v121, 0xffff0000, v44
	v_lshlrev_b32_e32 v122, 16, v45
	v_and_b32_e32 v123, 0xffff0000, v45
	v_lshlrev_b32_e32 v112, 16, v46
	v_and_b32_e32 v113, 0xffff0000, v46
	v_lshlrev_b32_e32 v114, 16, v47
	v_and_b32_e32 v115, 0xffff0000, v47
	v_fmac_f32_e32 v98, v120, v120
	v_fmac_f32_e32 v98, v121, v121
	v_fmac_f32_e32 v98, v122, v122
	v_fmac_f32_e32 v98, v123, v123
	v_fmac_f32_e32 v98, v112, v112
	v_fmac_f32_e32 v98, v113, v113
	v_fmac_f32_e32 v98, v114, v114
	v_fmac_f32_e32 v98, v115, v115
	v_lshlrev_b32_e32 v120, 16, v12
	v_and_b32_e32 v121, 0xffff0000, v12
	v_lshlrev_b32_e32 v122, 16, v13
	v_and_b32_e32 v123, 0xffff0000, v13
	v_lshlrev_b32_e32 v112, 16, v14
	v_and_b32_e32 v113, 0xffff0000, v14
	v_lshlrev_b32_e32 v114, 16, v15
	v_and_b32_e32 v115, 0xffff0000, v15
	v_fmac_f32_e32 v98, v120, v120
	v_fmac_f32_e32 v98, v121, v121
	v_fmac_f32_e32 v98, v122, v122
	v_fmac_f32_e32 v98, v123, v123
	v_fmac_f32_e32 v98, v112, v112
	v_fmac_f32_e32 v98, v113, v113
	v_fmac_f32_e32 v98, v114, v114
	v_fmac_f32_e32 v98, v115, v115
	v_lshlrev_b32_e32 v120, 16, v36
	v_and_b32_e32 v121, 0xffff0000, v36
	v_lshlrev_b32_e32 v122, 16, v37
	v_and_b32_e32 v123, 0xffff0000, v37
	v_lshlrev_b32_e32 v112, 16, v38
	v_and_b32_e32 v113, 0xffff0000, v38
	v_lshlrev_b32_e32 v114, 16, v39
	v_and_b32_e32 v115, 0xffff0000, v39
	v_fmac_f32_e32 v99, v120, v120
	v_fmac_f32_e32 v99, v121, v121
	v_fmac_f32_e32 v99, v122, v122
	v_fmac_f32_e32 v99, v123, v123
	v_fmac_f32_e32 v99, v112, v112
	v_fmac_f32_e32 v99, v113, v113
	v_fmac_f32_e32 v99, v114, v114
	v_fmac_f32_e32 v99, v115, v115
	v_lshlrev_b32_e32 v120, 16, v4
	v_and_b32_e32 v121, 0xffff0000, v4
	v_lshlrev_b32_e32 v122, 16, v5
	v_and_b32_e32 v123, 0xffff0000, v5
	v_lshlrev_b32_e32 v112, 16, v6
	v_and_b32_e32 v113, 0xffff0000, v6
	v_lshlrev_b32_e32 v114, 16, v7
	v_and_b32_e32 v115, 0xffff0000, v7
	v_fmac_f32_e32 v99, v120, v120
	v_fmac_f32_e32 v99, v121, v121
	v_fmac_f32_e32 v99, v122, v122
	v_fmac_f32_e32 v99, v123, v123
	v_fmac_f32_e32 v99, v112, v112
	v_fmac_f32_e32 v99, v113, v113
	v_fmac_f32_e32 v99, v114, v114
	v_fmac_f32_e32 v99, v115, v115
	ds_bpermute_b32 v120, v2, v104
	ds_bpermute_b32 v121, v2, v105
	ds_bpermute_b32 v122, v2, v106
	ds_bpermute_b32 v123, v2, v107
	ds_bpermute_b32 v112, v2, v96
	ds_bpermute_b32 v113, v2, v97
	ds_bpermute_b32 v114, v2, v98
	ds_bpermute_b32 v115, v2, v99
	s_waitcnt lgkmcnt(0)
	v_add_f32_e32 v104, v104, v120
	v_add_f32_e32 v105, v105, v121
	v_add_f32_e32 v106, v106, v122
	v_add_f32_e32 v107, v107, v123
	v_add_f32_e32 v96, v96, v112
	v_add_f32_e32 v97, v97, v113
	v_add_f32_e32 v98, v98, v114
	v_add_f32_e32 v99, v99, v115
	ds_bpermute_b32 v120, v3, v104
	ds_bpermute_b32 v121, v3, v105
	ds_bpermute_b32 v122, v3, v106
	ds_bpermute_b32 v123, v3, v107
	ds_bpermute_b32 v112, v3, v96
	ds_bpermute_b32 v113, v3, v97
	ds_bpermute_b32 v114, v3, v98
	ds_bpermute_b32 v115, v3, v99
	s_waitcnt lgkmcnt(0)
	v_add_f32_e32 v104, v104, v120
	v_add_f32_e32 v105, v105, v121
	v_add_f32_e32 v106, v106, v122
	v_add_f32_e32 v107, v107, v123
	v_add_f32_e32 v96, v96, v112
	v_add_f32_e32 v97, v97, v113
	v_add_f32_e32 v98, v98, v114
	v_add_f32_e32 v99, v99, v115
	v_and_b32_e32 v34, 48, v185
	v_cmp_eq_u32_e32 vcc, 0, v34
	s_and_saveexec_b64 s[64:65], vcc
	ds_write_b32 v35, v104 offset:0
	ds_write_b32 v35, v105 offset:256
	ds_write_b32 v35, v106 offset:512
	ds_write_b32 v35, v107 offset:768
	ds_write_b32 v35, v96 offset:2048
	ds_write_b32 v35, v97 offset:2304
	ds_write_b32 v35, v98 offset:2560
	ds_write_b32 v35, v99 offset:2816
	s_or_b64 exec, exec, s[64:65]
	s_waitcnt lgkmcnt(0)
	s_barrier
	v_cmp_gt_u32_e32 vcc, 0x100, v185
	s_and_saveexec_b64 s[64:65], vcc
	s_cbranch_execz .Lln_pub_done
	ds_read_b128 v[16:19], v42
	s_waitcnt lgkmcnt(0)
	v_add_f32_e32 v16, v16, v17
	v_add_f32_e32 v18, v18, v19
	v_add_f32_e32 v34, v16, v18
	global_store_dword v32, v34, s[38:39] sc0 sc1
	s_waitcnt vmcnt(0)
; __device__ __forceinline__ unsigned xb_ld(unsigned* p)              { return __hip_atomic_load(p, __ATOMIC_RELAXED, __HIP_MEMORY_SCOPE_AGENT); }
; __device__ __forceinline__ unsigned xb_add(unsigned* p, unsigned v) { return __hip_atomic_fetch_add(p, v, __ATOMIC_RELAXED, __HIP_MEMORY_SCOPE_AGENT); }
; __device__ __forceinline__ unsigned xb_xcc_id() { return (unsigned)__builtin_amdgcn_s_getreg((3 << 11) | 20) & 0xFu; }
.Lln_pub_done:
	s_or_b64 exec, exec, s[64:65]
	s_barrier
	v_cmp_eq_u32_e32 vcc, 0, v185
	s_and_saveexec_b64 s[64:65], vcc
	s_cbranch_execz .Lln_wait_done
	global_atomic_add v183, v33, s[58:59]
	s_mov_b32 s1, 0
.Lln_spin:
	global_load_dword v34, v183, s[58:59] sc1
	s_waitcnt vmcnt(0)
	v_cmp_gt_u32_e32 vcc, 8, v34
	s_cbranch_vccz .Lln_spin_done
	s_sleep 1
	s_add_i32 s1, s1, 1
	s_cmp_lt_u32 s1, 0x4000
	s_cbranch_scc1 .Lln_spin

; __device__ __forceinline__ unsigned pk2(float lo, float hi) { const f32x2 v = {lo, hi}; const hwbf16x2 b = __builtin_convertvector(v, hwbf16x2); return __builtin_bit_cast(unsigned, b); }
; template <bool OUT_F32, bool IN_BF16>
; __device__ __forceinline__ void phase_rmsnorm(const void* Xv, const float* gain, void* out) {
;     ...
;             rs[r] = 1.0f / sqrtf(wave_sum(sq) * (1.0f / DM) + EPS); }
; #pragma unroll
;         for (int r = 0; r < RPT; ++r) { const int m = m0 + r * NGW; if (m >= NTOK) continue;
; #pragma unroll
;             for (int j = 0; j < 4; ++j) { const f32x4 y0 = v[r][j][0] * rs[r] * g[j][0], y1 = v[r][j][1] * rs[r] * g[j][1];
;                 if (OUT_F32) { float* o = (float*)out + (size_t)m * DM + 8 * lane + 512 * j; *(f32x4*)o = y0; *(f32x4*)(o + 4) = y1; }
;                 else { u32x4 w; w.x = pk2(y0.x, y0.y); w.y = pk2(y0.z, y0.w); w.z = pk2(y1.x, y1.y); w.w = pk2(y1.z, y1.w); *(u32x4*)((bf16_t*)out + (size_t)m * DM + 8 * lane + 512 * j) = w; } } }
.Lln_wait_done:
	s_or_b64 exec, exec, s[64:65]
	s_barrier
	v_cmp_gt_u32_e32 vcc, 0x100, v185
	s_and_saveexec_b64 s[64:65], vcc
	s_cbranch_execz .Lln_rs_done
	global_load_dwordx4 v[16:19], v43, s[38:39] sc1
	global_load_dwordx4 v[24:27], v43, s[38:39] offset:16 sc1
	s_waitcnt vmcnt(0)
	v_add_f32_e32 v16, v16, v17
	v_add_f32_e32 v18, v18, v19
	v_add_f32_e32 v24, v24, v25
	v_add_f32_e32 v26, v26, v27
	v_add_f32_e32 v16, v16, v18
	v_add_f32_e32 v24, v24, v26
	v_add_f32_e32 v16, v16, v24
	v_mov_b32_e32 v17, 0x358637bd
	v_fmac_f32_e32 v17, 0x3a000000, v16
	v_rsq_f32_e32 v17, v17
	v_lshlrev_b32_e32 v18, 2, v185
	v_add_u32_e32 v18, 0x21000, v18
	s_nop 0
	ds_write_b32 v18, v17
.Lln_rs_done:
	s_or_b64 exec, exec, s[64:65]
	s_waitcnt lgkmcnt(0)
	s_barrier
	v_lshlrev_b32_e32 v2, 2, v40
	v_add_u32_e32 v2, 0x21000, v2
	ds_read_b32 v56, v2 offset:0
	ds_read_b32 v57, v2 offset:64
	ds_read_b32 v58, v2 offset:128
	ds_read_b32 v59, v2 offset:192
	ds_read_b32 v48, v2 offset:512
	ds_read_b32 v49, v2 offset:576
	ds_read_b32 v50, v2 offset:640
	ds_read_b32 v51, v2 offset:704
	s_mov_b32 s64, 0x4000000
	s_mov_b32 s65, 0
	v_lshl_add_u64 v[0:1], v[174:175], 0, s[64:65]
	s_mov_b32 s64, 0x10000
	s_waitcnt vmcnt(0) lgkmcnt(0)
	v_lshlrev_b32_e32 v120, 16, v124
	v_and_b32_e32 v121, 0xffff0000, v124
	v_lshlrev_b32_e32 v122, 16, v125
	v_and_b32_e32 v123, 0xffff0000, v125
	v_lshlrev_b32_e32 v112, 16, v126
	v_and_b32_e32 v113, 0xffff0000, v126
	v_lshlrev_b32_e32 v114, 16, v127
	v_and_b32_e32 v115, 0xffff0000, v127
	v_mul_f32_e32 v120, v120, v56
	v_mul_f32_e32 v121, v121, v56
	v_mul_f32_e32 v122, v122, v56
	v_mul_f32_e32 v123, v123, v56
	v_mul_f32_e32 v112, v112, v56
	v_mul_f32_e32 v113, v113, v56
	v_mul_f32_e32 v114, v114, v56
	v_mul_f32_e32 v115, v115, v56
	v_pk_mul_f32 v[120:121], v[120:121], v[88:89]
	v_pk_mul_f32 v[122:123], v[122:123], v[90:91]
	v_pk_mul_f32 v[112:113], v[112:113], v[80:81]
	v_pk_mul_f32 v[114:115], v[114:115], v[82:83]
	v_cvt_pk_bf16_f32 v8, v120, v121
	v_cvt_pk_bf16_f32 v9, v122, v123
	v_cvt_pk_bf16_f32 v10, v112, v113
	v_cvt_pk_bf16_f32 v11, v114, v115
	global_store_dwordx4 v[0:1], v[8:11], off
	v_lshlrev_b32_e32 v120, 16, v92
	v_and_b32_e32 v121, 0xffff0000, v92
	v_lshlrev_b32_e32 v122, 16, v93
	v_and_b32_e32 v123, 0xffff0000, v93
	v_lshlrev_b32_e32 v112, 16, v94
	v_and_b32_e32 v113, 0xffff0000, v94
	v_lshlrev_b32_e32 v114, 16, v95
	v_and_b32_e32 v115, 0xffff0000, v95
	v_mul_f32_e32 v120, v120, v56
	v_mul_f32_e32 v121, v121, v56
	v_mul_f32_e32 v122, v122, v56
	v_mul_f32_e32 v123, v123, v56
	v_mul_f32_e32 v112, v112, v56
	v_mul_f32_e32 v113, v113, v56
	v_mul_f32_e32 v114, v114, v56
	v_mul_f32_e32 v115, v115, v56
	v_pk_mul_f32 v[120:121], v[120:121], v[72:73]
	v_pk_mul_f32 v[122:123], v[122:123], v[74:75]
	v_pk_mul_f32 v[112:113], v[112:113], v[64:65]
	v_pk_mul_f32 v[114:115], v[114:115], v[66:67]
	v_cvt_pk_bf16_f32 v8, v120, v121
	v_cvt_pk_bf16_f32 v9, v122, v123
	v_cvt_pk_bf16_f32 v10, v112, v113
	v_cvt_pk_bf16_f32 v11, v114, v115
	global_store_dwordx4 v[0:1], v[8:11], off offset:256
	v_lshl_add_u64 v[0:1], v[0:1], 0, s[64:65]
	v_lshlrev_b32_e32 v120, 16, v116
	v_and_b32_e32 v121, 0xffff0000, v116
	v_lshlrev_b32_e32 v122, 16, v117
	v_and_b32_e32 v123, 0xffff0000, v117
	v_lshlrev_b32_e32 v112, 16, v118
	v_and_b32_e32 v113, 0xffff0000, v118
	v_lshlrev_b32_e32 v114, 16, v119
	v_and_b32_e32 v115, 0xffff0000, v119
	v_mul_f32_e32 v120, v120, v57
	v_mul_f32_e32 v121, v121, v57
	v_mul_f32_e32 v122, v122, v57
	v_mul_f32_e32 v123, v123, v57
	v_mul_f32_e32 v112, v112, v57
	v_mul_f32_e32 v113, v113, v57
	v_mul_f32_e32 v114, v114, v57
	v_mul_f32_e32 v115, v115, v57
	v_pk_mul_f32 v[120:121], v[120:121], v[88:89]
	v_pk_mul_f32 v[122:123], v[122:123], v[90:91]
	v_pk_mul_f32 v[112:113], v[112:113], v[80:81]
	v_pk_mul_f32 v[114:115], v[114:115], v[82:83]
	v_cvt_pk_bf16_f32 v8, v120, v121
	v_cvt_pk_bf16_f32 v9, v122, v123
	v_cvt_pk_bf16_f32 v10, v112, v113
	v_cvt_pk_bf16_f32 v11, v114, v115
	global_store_dwordx4 v[0:1], v[8:11], off
	v_lshlrev_b32_e32 v120, 16, v84
	v_and_b32_e32 v121, 0xffff0000, v84
	v_lshlrev_b32_e32 v122, 16, v85
	v_and_b32_e32 v123, 0xffff0000, v85
	v_lshlrev_b32_e32 v112, 16, v86
	v_and_b32_e32 v113, 0xffff0000, v86
	v_lshlrev_b32_e32 v114, 16, v87
	v_and_b32_e32 v115, 0xffff0000, v87
	v_mul_f32_e32 v120, v120, v57
	v_mul_f32_e32 v121, v121, v57
	v_mul_f32_e32 v122, v122, v57
	v_mul_f32_e32 v123, v123, v57
	v_mul_f32_e32 v112, v112, v57
	v_mul_f32_e32 v113, v113, v57
	v_mul_f32_e32 v114, v114, v57
	v_mul_f32_e32 v115, v115, v57
	v_pk_mul_f32 v[120:121], v[120:121], v[72:73]
	v_pk_mul_f32 v[122:123], v[122:123], v[74:75]
	v_pk_mul_f32 v[112:113], v[112:113], v[64:65]
	v_pk_mul_f32 v[114:115], v[114:115], v[66:67]
	v_cvt_pk_bf16_f32 v8, v120, v121
	v_cvt_pk_bf16_f32 v9, v122, v123
	v_cvt_pk_bf16_f32 v10, v112, v113
	v_cvt_pk_bf16_f32 v11, v114, v115
	global_store_dwordx4 v[0:1], v[8:11], off offset:256
	v_lshl_add_u64 v[0:1], v[0:1], 0, s[64:65]
	v_lshlrev_b32_e32 v120, 16, v108
	v_and_b32_e32 v121, 0xffff0000, v108
	v_lshlrev_b32_e32 v122, 16, v109
	v_and_b32_e32 v123, 0xffff0000, v109
	v_lshlrev_b32_e32 v112, 16, v110
	v_and_b32_e32 v113, 0xffff0000, v110
	v_lshlrev_b32_e32 v114, 16, v111
	v_and_b32_e32 v115, 0xffff0000, v111
	v_mul_f32_e32 v120, v120, v58
	v_mul_f32_e32 v121, v121, v58
	v_mul_f32_e32 v122, v122, v58
	v_mul_f32_e32 v123, v123, v58
	v_mul_f32_e32 v112, v112, v58
	v_mul_f32_e32 v113, v113, v58
	v_mul_f32_e32 v114, v114, v58
	v_mul_f32_e32 v115, v115, v58
	v_pk_mul_f32 v[120:121], v[120:121], v[88:89]
	v_pk_mul_f32 v[122:123], v[122:123], v[90:91]
	v_pk_mul_f32 v[112:113], v[112:113], v[80:81]
	v_pk_mul_f32 v[114:115], v[114:115], v[82:83]
; __device__ __forceinline__ unsigned pk2(float lo, float hi) { const f32x2 v = {lo, hi}; const hwbf16x2 b = __builtin_convertvector(v, hwbf16x2); return __builtin_bit_cast(unsigned, b); }
; template <bool OUT_F32, bool IN_BF16>
; __device__ __forceinline__ void phase_rmsnorm(const void* Xv, const float* gain, void* out) {
;     ...
; #pragma unroll
;         for (int r = 0; r < RPT; ++r) { const int m = m0 + r * NGW; if (m >= NTOK) continue;
; #pragma unroll
;             for (int j = 0; j < 4; ++j) { const f32x4 y0 = v[r][j][0] * rs[r] * g[j][0], y1 = v[r][j][1] * rs[r] * g[j][1];
;                 if (OUT_F32) { float* o = (float*)out + (size_t)m * DM + 8 * lane + 512 * j; *(f32x4*)o = y0; *(f32x4*)(o + 4) = y1; }
;                 else { u32x4 w; w.x = pk2(y0.x, y0.y); w.y = pk2(y0.z, y0.w); w.z = pk2(y1.x, y1.y); w.w = pk2(y1.z, y1.w); *(u32x4*)((bf16_t*)out + (size_t)m * DM + 8 * lane + 512 * j) = w; } } }
	v_cvt_pk_bf16_f32 v8, v120, v121
	v_cvt_pk_bf16_f32 v9, v122, v123
	v_cvt_pk_bf16_f32 v10, v112, v113
	v_cvt_pk_bf16_f32 v11, v114, v115
	global_store_dwordx4 v[0:1], v[8:11], off
	v_lshlrev_b32_e32 v120, 16, v76
	v_and_b32_e32 v121, 0xffff0000, v76
	v_lshlrev_b32_e32 v122, 16, v77
	v_and_b32_e32 v123, 0xffff0000, v77
	v_lshlrev_b32_e32 v112, 16, v78
	v_and_b32_e32 v113, 0xffff0000, v78
	v_lshlrev_b32_e32 v114, 16, v79
	v_and_b32_e32 v115, 0xffff0000, v79
	v_mul_f32_e32 v120, v120, v58
	v_mul_f32_e32 v121, v121, v58
	v_mul_f32_e32 v122, v122, v58
	v_mul_f32_e32 v123, v123, v58
	v_mul_f32_e32 v112, v112, v58
	v_mul_f32_e32 v113, v113, v58
	v_mul_f32_e32 v114, v114, v58
	v_mul_f32_e32 v115, v115, v58
	v_pk_mul_f32 v[120:121], v[120:121], v[72:73]
	v_pk_mul_f32 v[122:123], v[122:123], v[74:75]
	v_pk_mul_f32 v[112:113], v[112:113], v[64:65]
	v_pk_mul_f32 v[114:115], v[114:115], v[66:67]
	v_cvt_pk_bf16_f32 v8, v120, v121
	v_cvt_pk_bf16_f32 v9, v122, v123
	v_cvt_pk_bf16_f32 v10, v112, v113
	v_cvt_pk_bf16_f32 v11, v114, v115
	global_store_dwordx4 v[0:1], v[8:11], off offset:256
	v_lshl_add_u64 v[0:1], v[0:1], 0, s[64:65]
	v_lshlrev_b32_e32 v120, 16, v100
	v_and_b32_e32 v121, 0xffff0000, v100
	v_lshlrev_b32_e32 v122, 16, v101
	v_and_b32_e32 v123, 0xffff0000, v101
	v_lshlrev_b32_e32 v112, 16, v102
	v_and_b32_e32 v113, 0xffff0000, v102
	v_lshlrev_b32_e32 v114, 16, v103
	v_and_b32_e32 v115, 0xffff0000, v103
	v_mul_f32_e32 v120, v120, v59
	v_mul_f32_e32 v121, v121, v59
	v_mul_f32_e32 v122, v122, v59
	v_mul_f32_e32 v123, v123, v59
	v_mul_f32_e32 v112, v112, v59
	v_mul_f32_e32 v113, v113, v59
	v_mul_f32_e32 v114, v114, v59
	v_mul_f32_e32 v115, v115, v59
	v_pk_mul_f32 v[120:121], v[120:121], v[88:89]
	v_pk_mul_f32 v[122:123], v[122:123], v[90:91]
	v_pk_mul_f32 v[112:113], v[112:113], v[80:81]
	v_pk_mul_f32 v[114:115], v[114:115], v[82:83]
	v_cvt_pk_bf16_f32 v8, v120, v121
	v_cvt_pk_bf16_f32 v9, v122, v123
	v_cvt_pk_bf16_f32 v10, v112, v113
	v_cvt_pk_bf16_f32 v11, v114, v115
	global_store_dwordx4 v[0:1], v[8:11], off
	v_lshlrev_b32_e32 v120, 16, v68
	v_and_b32_e32 v121, 0xffff0000, v68
	v_lshlrev_b32_e32 v122, 16, v69
	v_and_b32_e32 v123, 0xffff0000, v69
	v_lshlrev_b32_e32 v112, 16, v70
	v_and_b32_e32 v113, 0xffff0000, v70
	v_lshlrev_b32_e32 v114, 16, v71
	v_and_b32_e32 v115, 0xffff0000, v71
	v_mul_f32_e32 v120, v120, v59
	v_mul_f32_e32 v121, v121, v59
	v_mul_f32_e32 v122, v122, v59
	v_mul_f32_e32 v123, v123, v59
	v_mul_f32_e32 v112, v112, v59
	v_mul_f32_e32 v113, v113, v59
	v_mul_f32_e32 v114, v114, v59
	v_mul_f32_e32 v115, v115, v59
	v_pk_mul_f32 v[120:121], v[120:121], v[72:73]
	v_pk_mul_f32 v[122:123], v[122:123], v[74:75]
	v_pk_mul_f32 v[112:113], v[112:113], v[64:65]
	v_pk_mul_f32 v[114:115], v[114:115], v[66:67]
	v_cvt_pk_bf16_f32 v8, v120, v121
	v_cvt_pk_bf16_f32 v9, v122, v123
	v_cvt_pk_bf16_f32 v10, v112, v113
	v_cvt_pk_bf16_f32 v11, v114, v115
	global_store_dwordx4 v[0:1], v[8:11], off offset:256
	s_mov_b32 s64, 0x50000
	v_lshl_add_u64 v[0:1], v[0:1], 0, s[64:65]
	s_mov_b32 s64, 0x10000
	v_lshlrev_b32_e32 v120, 16, v60
	v_and_b32_e32 v121, 0xffff0000, v60
	v_lshlrev_b32_e32 v122, 16, v61
	v_and_b32_e32 v123, 0xffff0000, v61
	v_lshlrev_b32_e32 v112, 16, v62
	v_and_b32_e32 v113, 0xffff0000, v62
	v_lshlrev_b32_e32 v114, 16, v63
	v_and_b32_e32 v115, 0xffff0000, v63
	v_mul_f32_e32 v120, v120, v48
	v_mul_f32_e32 v121, v121, v48
	v_mul_f32_e32 v122, v122, v48
	v_mul_f32_e32 v123, v123, v48
	v_mul_f32_e32 v112, v112, v48
	v_mul_f32_e32 v113, v113, v48
	v_mul_f32_e32 v114, v114, v48
	v_mul_f32_e32 v115, v115, v48
	v_pk_mul_f32 v[120:121], v[120:121], v[88:89]
	v_pk_mul_f32 v[122:123], v[122:123], v[90:91]
	v_pk_mul_f32 v[112:113], v[112:113], v[80:81]
	v_pk_mul_f32 v[114:115], v[114:115], v[82:83]
	v_cvt_pk_bf16_f32 v8, v120, v121
	v_cvt_pk_bf16_f32 v9, v122, v123
	v_cvt_pk_bf16_f32 v10, v112, v113
	v_cvt_pk_bf16_f32 v11, v114, v115
	global_store_dwordx4 v[0:1], v[8:11], off
	v_lshlrev_b32_e32 v120, 16, v28
	v_and_b32_e32 v121, 0xffff0000, v28
	v_lshlrev_b32_e32 v122, 16, v29
	v_and_b32_e32 v123, 0xffff0000, v29
	v_lshlrev_b32_e32 v112, 16, v30
	v_and_b32_e32 v113, 0xffff0000, v30
	v_lshlrev_b32_e32 v114, 16, v31
	v_and_b32_e32 v115, 0xffff0000, v31
	v_mul_f32_e32 v120, v120, v48
	v_mul_f32_e32 v121, v121, v48
	v_mul_f32_e32 v122, v122, v48
	v_mul_f32_e32 v123, v123, v48
	v_mul_f32_e32 v112, v112, v48
	v_mul_f32_e32 v113, v113, v48
	v_mul_f32_e32 v114, v114, v48
	v_mul_f32_e32 v115, v115, v48
	v_pk_mul_f32 v[120:121], v[120:121], v[72:73]
	v_pk_mul_f32 v[122:123], v[122:123], v[74:75]
	v_pk_mul_f32 v[112:113], v[112:113], v[64:65]
	v_pk_mul_f32 v[114:115], v[114:115], v[66:67]
	v_cvt_pk_bf16_f32 v8, v120, v121
	v_cvt_pk_bf16_f32 v9, v122, v123
	v_cvt_pk_bf16_f32 v10, v112, v113
	v_cvt_pk_bf16_f32 v11, v114, v115
	global_store_dwordx4 v[0:1], v[8:11], off offset:256
	v_lshl_add_u64 v[0:1], v[0:1], 0, s[64:65]
	v_lshlrev_b32_e32 v120, 16, v52
	v_and_b32_e32 v121, 0xffff0000, v52
	v_lshlrev_b32_e32 v122, 16, v53
	v_and_b32_e32 v123, 0xffff0000, v53
	v_lshlrev_b32_e32 v112, 16, v54
	v_and_b32_e32 v113, 0xffff0000, v54
	v_lshlrev_b32_e32 v114, 16, v55
	v_and_b32_e32 v115, 0xffff0000, v55
	v_mul_f32_e32 v120, v120, v49
; __device__ __forceinline__ unsigned pk2(float lo, float hi) { const f32x2 v = {lo, hi}; const hwbf16x2 b = __builtin_convertvector(v, hwbf16x2); return __builtin_bit_cast(unsigned, b); }
; template <bool OUT_F32, bool IN_BF16>
; __device__ __forceinline__ void phase_rmsnorm(const void* Xv, const float* gain, void* out) {
;     ...
; #pragma unroll
;         for (int r = 0; r < RPT; ++r) { const int m = m0 + r * NGW; if (m >= NTOK) continue;
; #pragma unroll
;             for (int j = 0; j < 4; ++j) { const f32x4 y0 = v[r][j][0] * rs[r] * g[j][0], y1 = v[r][j][1] * rs[r] * g[j][1];
;                 if (OUT_F32) { float* o = (float*)out + (size_t)m * DM + 8 * lane + 512 * j; *(f32x4*)o = y0; *(f32x4*)(o + 4) = y1; }
;                 else { u32x4 w; w.x = pk2(y0.x, y0.y); w.y = pk2(y0.z, y0.w); w.z = pk2(y1.x, y1.y); w.w = pk2(y1.z, y1.w); *(u32x4*)((bf16_t*)out + (size_t)m * DM + 8 * lane + 512 * j) = w; } } }
	v_mul_f32_e32 v121, v121, v49
	v_mul_f32_e32 v122, v122, v49
	v_mul_f32_e32 v123, v123, v49
	v_mul_f32_e32 v112, v112, v49
	v_mul_f32_e32 v113, v113, v49
	v_mul_f32_e32 v114, v114, v49
	v_mul_f32_e32 v115, v115, v49
	v_pk_mul_f32 v[120:121], v[120:121], v[88:89]
	v_pk_mul_f32 v[122:123], v[122:123], v[90:91]
	v_pk_mul_f32 v[112:113], v[112:113], v[80:81]
	v_pk_mul_f32 v[114:115], v[114:115], v[82:83]
	v_cvt_pk_bf16_f32 v8, v120, v121
	v_cvt_pk_bf16_f32 v9, v122, v123
	v_cvt_pk_bf16_f32 v10, v112, v113
	v_cvt_pk_bf16_f32 v11, v114, v115
	global_store_dwordx4 v[0:1], v[8:11], off
	v_lshlrev_b32_e32 v120, 16, v20
	v_and_b32_e32 v121, 0xffff0000, v20
	v_lshlrev_b32_e32 v122, 16, v21
	v_and_b32_e32 v123, 0xffff0000, v21
	v_lshlrev_b32_e32 v112, 16, v22
	v_and_b32_e32 v113, 0xffff0000, v22
	v_lshlrev_b32_e32 v114, 16, v23
	v_and_b32_e32 v115, 0xffff0000, v23
	v_mul_f32_e32 v120, v120, v49
	v_mul_f32_e32 v121, v121, v49
	v_mul_f32_e32 v122, v122, v49
	v_mul_f32_e32 v123, v123, v49
	v_mul_f32_e32 v112, v112, v49
	v_mul_f32_e32 v113, v113, v49
	v_mul_f32_e32 v114, v114, v49
	v_mul_f32_e32 v115, v115, v49
	v_pk_mul_f32 v[120:121], v[120:121], v[72:73]
	v_pk_mul_f32 v[122:123], v[122:123], v[74:75]
	v_pk_mul_f32 v[112:113], v[112:113], v[64:65]
	v_pk_mul_f32 v[114:115], v[114:115], v[66:67]
	v_cvt_pk_bf16_f32 v8, v120, v121
	v_cvt_pk_bf16_f32 v9, v122, v123
	v_cvt_pk_bf16_f32 v10, v112, v113
	v_cvt_pk_bf16_f32 v11, v114, v115
	global_store_dwordx4 v[0:1], v[8:11], off offset:256
	v_lshl_add_u64 v[0:1], v[0:1], 0, s[64:65]
	v_lshlrev_b32_e32 v120, 16, v44
	v_and_b32_e32 v121, 0xffff0000, v44
	v_lshlrev_b32_e32 v122, 16, v45
	v_and_b32_e32 v123, 0xffff0000, v45
	v_lshlrev_b32_e32 v112, 16, v46
	v_and_b32_e32 v113, 0xffff0000, v46
	v_lshlrev_b32_e32 v114, 16, v47
	v_and_b32_e32 v115, 0xffff0000, v47
	v_mul_f32_e32 v120, v120, v50
	v_mul_f32_e32 v121, v121, v50
	v_mul_f32_e32 v122, v122, v50
	v_mul_f32_e32 v123, v123, v50
	v_mul_f32_e32 v112, v112, v50
	v_mul_f32_e32 v113, v113, v50
	v_mul_f32_e32 v114, v114, v50
	v_mul_f32_e32 v115, v115, v50
	v_pk_mul_f32 v[120:121], v[120:121], v[88:89]
	v_pk_mul_f32 v[122:123], v[122:123], v[90:91]
	v_pk_mul_f32 v[112:113], v[112:113], v[80:81]
	v_pk_mul_f32 v[114:115], v[114:115], v[82:83]
	v_cvt_pk_bf16_f32 v8, v120, v121
	v_cvt_pk_bf16_f32 v9, v122, v123
	v_cvt_pk_bf16_f32 v10, v112, v113
	v_cvt_pk_bf16_f32 v11, v114, v115
	global_store_dwordx4 v[0:1], v[8:11], off
	v_lshlrev_b32_e32 v120, 16, v12
	v_and_b32_e32 v121, 0xffff0000, v12
	v_lshlrev_b32_e32 v122, 16, v13
	v_and_b32_e32 v123, 0xffff0000, v13
	v_lshlrev_b32_e32 v112, 16, v14
	v_and_b32_e32 v113, 0xffff0000, v14
	v_lshlrev_b32_e32 v114, 16, v15
	v_and_b32_e32 v115, 0xffff0000, v15
	v_mul_f32_e32 v120, v120, v50
	v_mul_f32_e32 v121, v121, v50
	v_mul_f32_e32 v122, v122, v50
	v_mul_f32_e32 v123, v123, v50
	v_mul_f32_e32 v112, v112, v50
	v_mul_f32_e32 v113, v113, v50
	v_mul_f32_e32 v114, v114, v50
	v_mul_f32_e32 v115, v115, v50
	v_pk_mul_f32 v[120:121], v[120:121], v[72:73]
	v_pk_mul_f32 v[122:123], v[122:123], v[74:75]
	v_pk_mul_f32 v[112:113], v[112:113], v[64:65]
	v_pk_mul_f32 v[114:115], v[114:115], v[66:67]
	v_cvt_pk_bf16_f32 v8, v120, v121
	v_cvt_pk_bf16_f32 v9, v122, v123
	v_cvt_pk_bf16_f32 v10, v112, v113
	v_cvt_pk_bf16_f32 v11, v114, v115
	global_store_dwordx4 v[0:1], v[8:11], off offset:256
	v_lshl_add_u64 v[0:1], v[0:1], 0, s[64:65]
	v_lshlrev_b32_e32 v120, 16, v36
	v_and_b32_e32 v121, 0xffff0000, v36
	v_lshlrev_b32_e32 v122, 16, v37
	v_and_b32_e32 v123, 0xffff0000, v37
	v_lshlrev_b32_e32 v112, 16, v38
	v_and_b32_e32 v113, 0xffff0000, v38
	v_lshlrev_b32_e32 v114, 16, v39
	v_and_b32_e32 v115, 0xffff0000, v39
	v_mul_f32_e32 v120, v120, v51
	v_mul_f32_e32 v121, v121, v51
	v_mul_f32_e32 v122, v122, v51
	v_mul_f32_e32 v123, v123, v51
	v_mul_f32_e32 v112, v112, v51
	v_mul_f32_e32 v113, v113, v51
	v_mul_f32_e32 v114, v114, v51
	v_mul_f32_e32 v115, v115, v51
	v_pk_mul_f32 v[120:121], v[120:121], v[88:89]
	v_pk_mul_f32 v[122:123], v[122:123], v[90:91]
	v_pk_mul_f32 v[112:113], v[112:113], v[80:81]
	v_pk_mul_f32 v[114:115], v[114:115], v[82:83]
	v_cvt_pk_bf16_f32 v8, v120, v121
	v_cvt_pk_bf16_f32 v9, v122, v123
	v_cvt_pk_bf16_f32 v10, v112, v113
	v_cvt_pk_bf16_f32 v11, v114, v115
	global_store_dwordx4 v[0:1], v[8:11], off
	v_lshlrev_b32_e32 v120, 16, v4
	v_and_b32_e32 v121, 0xffff0000, v4
	v_lshlrev_b32_e32 v122, 16, v5
	v_and_b32_e32 v123, 0xffff0000, v5
	v_lshlrev_b32_e32 v112, 16, v6
	v_and_b32_e32 v113, 0xffff0000, v6
	v_lshlrev_b32_e32 v114, 16, v7
	v_and_b32_e32 v115, 0xffff0000, v7
	v_mul_f32_e32 v120, v120, v51
	v_mul_f32_e32 v121, v121, v51
	v_mul_f32_e32 v122, v122, v51
	v_mul_f32_e32 v123, v123, v51
	v_mul_f32_e32 v112, v112, v51
	v_mul_f32_e32 v113, v113, v51
	v_mul_f32_e32 v114, v114, v51
	v_mul_f32_e32 v115, v115, v51
	v_pk_mul_f32 v[120:121], v[120:121], v[72:73]
	v_pk_mul_f32 v[122:123], v[122:123], v[74:75]
	v_pk_mul_f32 v[112:113], v[112:113], v[64:65]
	v_pk_mul_f32 v[114:115], v[114:115], v[66:67]
	v_cvt_pk_bf16_f32 v8, v120, v121
	v_cvt_pk_bf16_f32 v9, v122, v123
	v_cvt_pk_bf16_f32 v10, v112, v113
	v_cvt_pk_bf16_f32 v11, v114, v115
	global_store_dwordx4 v[0:1], v[8:11], off offset:256
